# v-side residual-row loads hoisted from the token epilogue to the mid-body drain point (6 of 8 loads, renamed into free VGPRs)
# baseline (speedup 1.0000x reference)
; __device__ void phase_gather(const Params& p) {
;     ...
;       const int idv = half ? id1 : id0;
;       const int pkv = half ? pk1 : pk0;
;       u32x4 rr[3][GROWS];
; #pragma unroll
;       for (int k = 0; k < GROWS; ++k) {
;         const int e = __builtin_amdgcn_readlane(idv, k);
;         rr[0][k] = *(const u32x4*)(vb + (size_t)e * 1024 + lane * 16);
;         const int e2 = __builtin_amdgcn_readlane(idv, GROWS + k);
;         rr[1][k] = *(const u32x4*)(vb + (size_t)e2 * 1024 + lane * 16);
;       }
; #pragma unroll
;       for (int gi = 0; gi < 64 / GROWS; ++gi) {
;         const int j0 = gi * GROWS;
;         if (gi + 2 < 64 / GROWS) {
; #pragma unroll
;           for (int k = 0; k < GROWS; ++k) {
;             const int e = __builtin_amdgcn_readlane(idv, j0 + 2 * GROWS + k);
;             rr[(gi + 2) % 3][k] = *(const u32x4*)(vb + (size_t)e * 1024 + lane * 16);
.LBB0_1321:
	v_cndmask_b32_e64 v1, v124, v122, s[0:1]
	v_cndmask_b32_e64 v0, 0, 1, s[0:1]
	v_readlane_b32 s56, v1, 24
	s_ashr_i32 s57, s56, 31
	s_lshl_b64 s[84:85], s[56:57], 10
	v_readlane_b32 s56, v1, 25
	s_ashr_i32 s57, s56, 31
	s_lshl_b64 s[82:83], s[56:57], 10
	v_readlane_b32 s56, v1, 26
	s_ashr_i32 s57, s56, 31
	s_lshl_b64 s[86:87], s[56:57], 10
	v_readlane_b32 s56, v1, 27
	s_ashr_i32 s57, s56, 31
	s_lshl_b64 s[88:89], s[56:57], 10
	v_readlane_b32 s56, v1, 28
	s_ashr_i32 s57, s56, 31
	s_lshl_b64 s[90:91], s[56:57], 10
	v_readlane_b32 s56, v1, 29
	s_ashr_i32 s57, s56, 31
	s_lshl_b64 s[92:93], s[56:57], 10
	v_readlane_b32 s56, v1, 30
	s_ashr_i32 s57, s56, 31
	s_lshl_b64 s[94:95], s[56:57], 10
	v_readlane_b32 s56, v1, 31
	s_ashr_i32 s57, s56, 31
	s_lshl_b64 s[96:97], s[56:57], 10
	v_readlane_b32 s56, v1, 32
	s_ashr_i32 s57, s56, 31
	s_lshl_b64 s[66:67], s[56:57], 10
	v_readlane_b32 s56, v1, 33
	s_ashr_i32 s57, s56, 31
	s_lshl_b64 s[68:69], s[56:57], 10
	v_readlane_b32 s56, v1, 34
	s_ashr_i32 s57, s56, 31
	s_lshl_b64 s[70:71], s[56:57], 10
	v_readlane_b32 s56, v1, 35
	s_ashr_i32 s57, s56, 31
	s_lshl_b64 s[72:73], s[56:57], 10
	v_readlane_b32 s56, v1, 36
	s_ashr_i32 s57, s56, 31
	s_lshl_b64 s[74:75], s[56:57], 10
	v_readlane_b32 s56, v1, 37
	s_ashr_i32 s57, s56, 31
	s_lshl_b64 s[76:77], s[56:57], 10
	v_readlane_b32 s56, v1, 38
	s_ashr_i32 s57, s56, 31
	s_lshl_b64 s[78:79], s[56:57], 10
	v_readlane_b32 s56, v1, 39
	s_ashr_i32 s57, s56, 31
	s_lshl_b64 s[80:81], s[56:57], 10
	v_readlane_b32 s56, v1, 40
	s_ashr_i32 s57, s56, 31
	s_lshl_b64 s[56:57], s[56:57], 10
	v_writelane_b32 v250, s56, 34
	v_readlane_b32 vcc_lo, v1, 48
	s_ashr_i32 vcc_hi, vcc_lo, 31
	v_writelane_b32 v250, s57, 35
	v_readlane_b32 s56, v1, 41
	s_ashr_i32 s57, s56, 31
	s_lshl_b64 s[56:57], s[56:57], 10
	v_writelane_b32 v250, s56, 36
	s_lshl_b64 vcc, vcc, 10
	v_readlane_b32 s2, v1, 0
	v_writelane_b32 v250, s57, 37
	v_readlane_b32 s56, v1, 42
	s_ashr_i32 s57, s56, 31
	s_lshl_b64 s[56:57], s[56:57], 10
	v_writelane_b32 v250, s56, 38
	s_ashr_i32 s3, s2, 31
	s_lshl_b64 s[50:51], s[2:3], 10
	v_writelane_b32 v250, s57, 39
	v_writelane_b32 v250, vcc_lo, 40
	v_readlane_b32 s2, v1, 8
	s_ashr_i32 s3, s2, 31
	v_writelane_b32 v250, vcc_hi, 41
	v_readlane_b32 vcc_lo, v1, 49
	s_ashr_i32 vcc_hi, vcc_lo, 31
	s_lshl_b64 vcc, vcc, 10
	v_writelane_b32 v250, vcc_lo, 42
	s_lshl_b64 s[48:49], s[2:3], 10
	v_readlane_b32 s2, v1, 1
	v_writelane_b32 v250, vcc_hi, 43
	v_readlane_b32 vcc_lo, v1, 50
	s_ashr_i32 vcc_hi, vcc_lo, 31
	s_lshl_b64 vcc, vcc, 10
	v_writelane_b32 v250, vcc_lo, 44
	s_ashr_i32 s3, s2, 31
	s_lshl_b64 s[46:47], s[2:3], 10
	v_writelane_b32 v250, vcc_hi, 45
	v_readlane_b32 vcc_lo, v1, 51
	s_ashr_i32 vcc_hi, vcc_lo, 31
	s_lshl_b64 vcc, vcc, 10
	v_writelane_b32 v250, vcc_lo, 46
	v_readlane_b32 s2, v1, 9
	s_ashr_i32 s3, s2, 31
	v_writelane_b32 v250, vcc_hi, 47
	v_readlane_b32 vcc_lo, v1, 52
	s_ashr_i32 vcc_hi, vcc_lo, 31
	s_lshl_b64 vcc, vcc, 10
	v_writelane_b32 v250, vcc_lo, 48
	s_lshl_b64 s[44:45], s[2:3], 10
	v_readlane_b32 s2, v1, 2
	v_writelane_b32 v250, vcc_hi, 49
	v_readlane_b32 vcc_lo, v1, 53
	s_ashr_i32 vcc_hi, vcc_lo, 31
	s_lshl_b64 vcc, vcc, 10
	v_writelane_b32 v250, vcc_lo, 50
	s_ashr_i32 s3, s2, 31
	s_lshl_b64 s[42:43], s[2:3], 10
	v_writelane_b32 v250, vcc_hi, 51
	v_readlane_b32 vcc_lo, v1, 54
	s_ashr_i32 vcc_hi, vcc_lo, 31
	s_lshl_b64 vcc, vcc, 10
	v_writelane_b32 v250, vcc_lo, 52
	v_readlane_b32 s2, v1, 10
	s_ashr_i32 s3, s2, 31
	v_writelane_b32 v250, vcc_hi, 53
	v_readlane_b32 vcc_lo, v1, 55
	s_ashr_i32 vcc_hi, vcc_lo, 31
	s_lshl_b64 s[40:41], s[2:3], 10
	v_readlane_b32 s2, v1, 3
	s_lshl_b64 vcc, vcc, 10
	s_ashr_i32 s3, s2, 31
	v_writelane_b32 v250, vcc_lo, 54
	s_lshl_b64 s[38:39], s[2:3], 10
	v_readlane_b32 s2, v1, 11
	v_writelane_b32 v250, vcc_hi, 55
	v_readlane_b32 vcc_lo, v1, 56
	s_ashr_i32 s3, s2, 31
	s_ashr_i32 vcc_hi, vcc_lo, 31
	s_lshl_b64 s[36:37], s[2:3], 10
	v_readlane_b32 s2, v1, 4
	s_lshl_b64 vcc, vcc, 10
	s_ashr_i32 s3, s2, 31
	v_writelane_b32 v250, vcc_lo, 6
	s_lshl_b64 s[34:35], s[2:3], 10
	v_readlane_b32 s2, v1, 12
	v_writelane_b32 v250, vcc_hi, 7
	v_readlane_b32 vcc_lo, v1, 57
	s_ashr_i32 s3, s2, 31
	s_ashr_i32 vcc_hi, vcc_lo, 31
	s_lshl_b64 s[30:31], s[2:3], 10
	v_readlane_b32 s2, v1, 5
	s_lshl_b64 vcc, vcc, 10
	s_ashr_i32 s3, s2, 31
	v_writelane_b32 v250, vcc_lo, 4
	s_lshl_b64 s[28:29], s[2:3], 10
	v_readlane_b32 s2, v1, 13
	v_writelane_b32 v250, vcc_hi, 5
	v_readlane_b32 vcc_lo, v1, 58
	s_ashr_i32 s3, s2, 31
	s_ashr_i32 vcc_hi, vcc_lo, 31
	s_lshl_b64 s[26:27], s[2:3], 10
	v_readlane_b32 s2, v1, 6
	s_lshl_b64 vcc, vcc, 10
	s_ashr_i32 s3, s2, 31
	v_writelane_b32 v250, vcc_lo, 14
	s_lshl_b64 s[24:25], s[2:3], 10
	v_readlane_b32 s2, v1, 14
	v_writelane_b32 v250, vcc_hi, 15
	v_readlane_b32 vcc_lo, v1, 59
	s_ashr_i32 s3, s2, 31
	s_ashr_i32 vcc_hi, vcc_lo, 31
	s_lshl_b64 s[22:23], s[2:3], 10
	v_readlane_b32 s2, v1, 7
	s_lshl_b64 vcc, vcc, 10
	s_ashr_i32 s3, s2, 31
	v_writelane_b32 v250, vcc_lo, 10
	s_lshl_b64 s[20:21], s[2:3], 10
	v_readlane_b32 s2, v1, 15
	v_writelane_b32 v250, vcc_hi, 11
	v_readlane_b32 vcc_lo, v1, 60
	s_ashr_i32 s3, s2, 31
	s_ashr_i32 vcc_hi, vcc_lo, 31
	s_lshl_b64 s[18:19], s[2:3], 10
	v_readlane_b32 s2, v1, 16
	s_lshl_b64 vcc, vcc, 10
	s_ashr_i32 s3, s2, 31
	v_writelane_b32 v250, vcc_lo, 12
	s_lshl_b64 s[16:17], s[2:3], 10
	v_readlane_b32 s2, v1, 17
	v_writelane_b32 v250, vcc_hi, 13
	v_readlane_b32 vcc_lo, v1, 61
	s_ashr_i32 s3, s2, 31
	s_ashr_i32 vcc_hi, vcc_lo, 31
	s_lshl_b64 s[14:15], s[2:3], 10
	v_readlane_b32 s2, v1, 18
	s_lshl_b64 vcc, vcc, 10
	s_ashr_i32 s3, s2, 31
	v_writelane_b32 v250, vcc_lo, 2
	s_lshl_b64 s[12:13], s[2:3], 10
; __device__ void phase_gather(const Params& p) {
;     ...
; #pragma unroll
;       for (int k = 0; k < GROWS; ++k) {
;         const int e = __builtin_amdgcn_readlane(idv, k);
;         rr[0][k] = *(const u32x4*)(vb + (size_t)e * 1024 + lane * 16);
;         const int e2 = __builtin_amdgcn_readlane(idv, GROWS + k);
;         rr[1][k] = *(const u32x4*)(vb + (size_t)e2 * 1024 + lane * 16);
;       }
; #pragma unroll
;       for (int gi = 0; gi < 64 / GROWS; ++gi) {
;         const int j0 = gi * GROWS;
;         if (gi + 2 < 64 / GROWS) {
; #pragma unroll
;           for (int k = 0; k < GROWS; ++k) {
;             const int e = __builtin_amdgcn_readlane(idv, j0 + 2 * GROWS + k);
;             rr[(gi + 2) % 3][k] = *(const u32x4*)(vb + (size_t)e * 1024 + lane * 16);
;           }
;         }
; #pragma unroll
;         for (int sub = 0; sub < GROWS / 4; ++sub) {
;           const int W4 = __builtin_amdgcn_readlane(pkv, j0 + 4 * sub);
; #pragma unroll
;           for (int m = 0; m < 4; ++m) {
;             unsigned lo[4], hi[4];
; #pragma unroll
;             for (int k = 0; k < 4; ++k) {
;               const unsigned w = rr[gi % 3][sub * 4 + k][m];
;               lo[k] = w & 0x0f0f0f0fu;
;               hi[k] = (w >> 4) & 0x0f0f0f0fu;
;             }
;             {
;               const unsigned p01l = __builtin_amdgcn_perm(lo[1], lo[0], 0x05010400u), p01h = __builtin_amdgcn_perm(lo[1], lo[0], 0x07030602u);
;               const unsigned p23l = __builtin_amdgcn_perm(lo[3], lo[2], 0x05010400u), p23h = __builtin_amdgcn_perm(lo[3], lo[2], 0x07030602u);
;               acc[m * 8 + 0] = __builtin_amdgcn_sdot4((int)__builtin_amdgcn_perm(p23l, p01l, 0x05040100u), W4, acc[m * 8 + 0], false);
;               acc[m * 8 + 1] = __builtin_amdgcn_sdot4((int)__builtin_amdgcn_perm(p23l, p01l, 0x07060302u), W4, acc[m * 8 + 1], false);
;               acc[m * 8 + 2] = __builtin_amdgcn_sdot4((int)__builtin_amdgcn_perm(p23h, p01h, 0x05040100u), W4, acc[m * 8 + 2], false);
;               acc[m * 8 + 3] = __builtin_amdgcn_sdot4((int)__builtin_amdgcn_perm(p23h, p01h, 0x07060302u), W4, acc[m * 8 + 3], false);
;             }
;             {
;               const unsigned p01l = __builtin_amdgcn_perm(hi[1], hi[0], 0x05010400u), p01h = __builtin_amdgcn_perm(hi[1], hi[0], 0x07030602u);
	v_readlane_b32 s2, v1, 19
	v_writelane_b32 v250, vcc_hi, 3
	v_readlane_b32 vcc_lo, v1, 62
	s_ashr_i32 s3, s2, 31
	s_ashr_i32 vcc_hi, vcc_lo, 31
	s_lshl_b64 s[10:11], s[2:3], 10
	v_readlane_b32 s2, v1, 20
	s_lshl_b64 vcc, vcc, 10
	s_ashr_i32 s3, s2, 31
	v_writelane_b32 v250, vcc_lo, 0
	s_lshl_b64 s[8:9], s[2:3], 10
	v_readlane_b32 s2, v1, 21
	v_writelane_b32 v250, vcc_hi, 1
	v_readlane_b32 vcc_lo, v1, 63
	s_ashr_i32 s3, s2, 31
	s_ashr_i32 vcc_hi, vcc_lo, 31
	s_lshl_b64 s[6:7], s[2:3], 10
	v_readlane_b32 s2, v1, 22
	s_lshl_b64 vcc, vcc, 10
	s_ashr_i32 s3, s2, 31
	v_writelane_b32 v250, vcc_lo, 16
	s_lshl_b64 s[4:5], s[2:3], 10
	v_readlane_b32 s2, v1, 23
	v_readlane_b32 s56, v1, 43
	v_readlane_b32 s58, v1, 44
	v_readlane_b32 s60, v1, 45
	v_readlane_b32 s62, v1, 46
	v_readlane_b32 s64, v1, 47
	v_writelane_b32 v250, vcc_hi, 17
	v_cmp_ne_u32_e32 vcc, 1, v0
	v_lshl_add_u64 v[0:1], v[116:117], 0, s[50:51]
	global_load_dwordx4 v[64:67], v[0:1], off
	v_lshl_add_u64 v[0:1], v[116:117], 0, s[48:49]
	global_load_dwordx4 v[80:83], v[0:1], off
	v_lshl_add_u64 v[0:1], v[116:117], 0, s[46:47]
	global_load_dwordx4 v[68:71], v[0:1], off
	v_lshl_add_u64 v[0:1], v[116:117], 0, s[44:45]
	global_load_dwordx4 v[84:87], v[0:1], off
	v_lshl_add_u64 v[0:1], v[116:117], 0, s[42:43]
	global_load_dwordx4 v[72:75], v[0:1], off
	v_lshl_add_u64 v[0:1], v[116:117], 0, s[40:41]
	global_load_dwordx4 v[88:91], v[0:1], off
	v_lshl_add_u64 v[0:1], v[116:117], 0, s[38:39]
	global_load_dwordx4 v[76:79], v[0:1], off
	v_lshl_add_u64 v[0:1], v[116:117], 0, s[36:37]
	global_load_dwordx4 v[92:95], v[0:1], off
	v_lshl_add_u64 v[0:1], v[116:117], 0, s[34:35]
	global_load_dwordx4 v[48:51], v[0:1], off
	v_lshl_add_u64 v[0:1], v[116:117], 0, s[30:31]
	global_load_dwordx4 v[32:35], v[0:1], off
	v_lshl_add_u64 v[0:1], v[116:117], 0, s[28:29]
	global_load_dwordx4 v[52:55], v[0:1], off
	v_lshl_add_u64 v[0:1], v[116:117], 0, s[26:27]
	global_load_dwordx4 v[36:39], v[0:1], off
	v_lshl_add_u64 v[0:1], v[116:117], 0, s[24:25]
	global_load_dwordx4 v[56:59], v[0:1], off
	v_lshl_add_u64 v[0:1], v[116:117], 0, s[22:23]
	global_load_dwordx4 v[40:43], v[0:1], off
	v_lshl_add_u64 v[0:1], v[116:117], 0, s[20:21]
	global_load_dwordx4 v[60:63], v[0:1], off
	v_cndmask_b32_e64 v170, v169, v168, s[0:1]
	v_lshl_add_u64 v[0:1], v[116:117], 0, s[18:19]
	v_readlane_b32 s0, v170, 0
	global_load_dwordx4 v[44:47], v[0:1], off
	s_ashr_i32 s63, s62, 31
	s_lshl_b64 s[62:63], s[62:63], 10
	s_ashr_i32 s65, s64, 31
	s_lshl_b64 s[64:65], s[64:65], 10
	s_ashr_i32 s3, s2, 31
	s_lshl_b64 s[2:3], s[2:3], 10
	s_ashr_i32 s57, s56, 31
	s_lshl_b64 s[56:57], s[56:57], 10
	s_ashr_i32 s59, s58, 31
	s_ashr_i32 s61, s60, 31
	s_lshl_b64 s[58:59], s[58:59], 10
	s_lshl_b64 s[60:61], s[60:61], 10
	s_and_b64 vcc, exec, vcc
	s_waitcnt vmcnt(15)
	v_and_b32_e32 v96, 0xf0f0f0f, v64
	v_lshrrev_b32_e32 v64, 4, v64
	v_and_b32_e32 v64, 0xf0f0f0f, v64
	s_waitcnt vmcnt(13)
	v_and_b32_e32 v97, 0xf0f0f0f, v68
	v_perm_b32 v100, v97, v96, s33
	v_perm_b32 v96, v97, v96, s52
	v_lshrrev_b32_e32 v68, 4, v68
	s_waitcnt vmcnt(11)
	v_and_b32_e32 v98, 0xf0f0f0f, v72
	v_lshrrev_b32_e32 v72, 4, v72
	v_and_b32_e32 v68, 0xf0f0f0f, v68
	v_and_b32_e32 v72, 0xf0f0f0f, v72
	s_waitcnt vmcnt(9)
	v_and_b32_e32 v99, 0xf0f0f0f, v76
	v_perm_b32 v97, v99, v98, s33
	v_lshrrev_b32_e32 v76, 4, v76
	v_perm_b32 v98, v99, v98, s52
	v_perm_b32 v99, v97, v100, s53
	v_perm_b32 v97, v97, v100, s54
	v_and_b32_e32 v76, 0xf0f0f0f, v76
	v_dot4c_i32_i8_e32 v164, s0, v97
	v_perm_b32 v97, v98, v96, s53
	v_perm_b32 v96, v98, v96, s54
	v_dot4c_i32_i8_e32 v162, s0, v96
	v_perm_b32 v96, v68, v64, s33
	v_perm_b32 v64, v68, v64, s52
	v_perm_b32 v68, v76, v72, s33
	v_perm_b32 v72, v76, v72, s52
	v_perm_b32 v76, v68, v96, s53
	v_perm_b32 v68, v68, v96, s54
	v_dot4c_i32_i8_e32 v160, s0, v68
	v_perm_b32 v68, v72, v64, s53
	v_perm_b32 v64, v72, v64, s54
	v_dot4c_i32_i8_e32 v159, s0, v76
	v_dot4c_i32_i8_e32 v157, s0, v68
	v_dot4c_i32_i8_e32 v158, s0, v64
	v_and_b32_e32 v64, 0xf0f0f0f, v65
	v_and_b32_e32 v68, 0xf0f0f0f, v69
	v_and_b32_e32 v72, 0xf0f0f0f, v73
	v_and_b32_e32 v76, 0xf0f0f0f, v77
	v_perm_b32 v96, v68, v64, s33
	v_perm_b32 v64, v68, v64, s52
	v_perm_b32 v68, v76, v72, s33
	v_lshrrev_b32_e32 v65, 4, v65
	v_lshrrev_b32_e32 v69, 4, v69
	v_lshrrev_b32_e32 v73, 4, v73
	v_lshrrev_b32_e32 v77, 4, v77
	v_perm_b32 v72, v76, v72, s52
	v_perm_b32 v76, v68, v96, s53
	v_perm_b32 v68, v68, v96, s54
	v_and_b32_e32 v65, 0xf0f0f0f, v65
	v_and_b32_e32 v69, 0xf0f0f0f, v69
	v_and_b32_e32 v73, 0xf0f0f0f, v73
	v_and_b32_e32 v77, 0xf0f0f0f, v77
	v_dot4c_i32_i8_e32 v154, s0, v68
	v_perm_b32 v68, v72, v64, s53
	v_perm_b32 v64, v72, v64, s54
	v_dot4c_i32_i8_e32 v149, s0, v68
	v_dot4c_i32_i8_e32 v150, s0, v64
	v_perm_b32 v64, v69, v65, s33
	v_perm_b32 v68, v77, v73, s33
	v_perm_b32 v65, v69, v65, s52
	v_perm_b32 v69, v77, v73, s52
	v_perm_b32 v72, v68, v64, s53
	v_perm_b32 v64, v68, v64, s54
	v_dot4c_i32_i8_e32 v146, s0, v64
	v_perm_b32 v64, v69, v65, s53
	v_dot4c_i32_i8_e32 v155, s0, v64
	v_perm_b32 v64, v69, v65, s54
	v_dot4c_i32_i8_e32 v144, s0, v72
	v_dot4c_i32_i8_e32 v156, s0, v64
	v_and_b32_e32 v64, 0xf0f0f0f, v66
	v_lshrrev_b32_e32 v65, 4, v66
	v_and_b32_e32 v66, 0xf0f0f0f, v70
	v_and_b32_e32 v69, 0xf0f0f0f, v74
	v_and_b32_e32 v72, 0xf0f0f0f, v78
	v_lshrrev_b32_e32 v68, 4, v70
	v_lshrrev_b32_e32 v70, 4, v74
	v_perm_b32 v74, v66, v64, s33
	v_perm_b32 v64, v66, v64, s52
	v_perm_b32 v66, v72, v69, s33
	v_lshrrev_b32_e32 v73, 4, v78
	v_perm_b32 v69, v72, v69, s52
	v_perm_b32 v72, v66, v74, s53
	v_perm_b32 v66, v66, v74, s54
	v_and_b32_e32 v65, 0xf0f0f0f, v65
	v_and_b32_e32 v68, 0xf0f0f0f, v68
	v_and_b32_e32 v70, 0xf0f0f0f, v70
; __device__ void phase_gather(const Params& p) {
;     ...
;         for (int sub = 0; sub < GROWS / 4; ++sub) {
;           const int W4 = __builtin_amdgcn_readlane(pkv, j0 + 4 * sub);
; #pragma unroll
;           for (int m = 0; m < 4; ++m) {
;             unsigned lo[4], hi[4];
; #pragma unroll
;             for (int k = 0; k < 4; ++k) {
;               const unsigned w = rr[gi % 3][sub * 4 + k][m];
;               lo[k] = w & 0x0f0f0f0fu;
;               hi[k] = (w >> 4) & 0x0f0f0f0fu;
;             }
;             {
;               const unsigned p01l = __builtin_amdgcn_perm(lo[1], lo[0], 0x05010400u), p01h = __builtin_amdgcn_perm(lo[1], lo[0], 0x07030602u);
;               const unsigned p23l = __builtin_amdgcn_perm(lo[3], lo[2], 0x05010400u), p23h = __builtin_amdgcn_perm(lo[3], lo[2], 0x07030602u);
;               acc[m * 8 + 0] = __builtin_amdgcn_sdot4((int)__builtin_amdgcn_perm(p23l, p01l, 0x05040100u), W4, acc[m * 8 + 0], false);
;               acc[m * 8 + 1] = __builtin_amdgcn_sdot4((int)__builtin_amdgcn_perm(p23l, p01l, 0x07060302u), W4, acc[m * 8 + 1], false);
;               acc[m * 8 + 2] = __builtin_amdgcn_sdot4((int)__builtin_amdgcn_perm(p23h, p01h, 0x05040100u), W4, acc[m * 8 + 2], false);
;               acc[m * 8 + 3] = __builtin_amdgcn_sdot4((int)__builtin_amdgcn_perm(p23h, p01h, 0x07060302u), W4, acc[m * 8 + 3], false);
;             }
;             {
;               const unsigned p01l = __builtin_amdgcn_perm(hi[1], hi[0], 0x05010400u), p01h = __builtin_amdgcn_perm(hi[1], hi[0], 0x07030602u);
;               const unsigned p23l = __builtin_amdgcn_perm(hi[3], hi[2], 0x05010400u), p23h = __builtin_amdgcn_perm(hi[3], hi[2], 0x07030602u);
;               acc[m * 8 + 4] = __builtin_amdgcn_sdot4((int)__builtin_amdgcn_perm(p23l, p01l, 0x05040100u), W4, acc[m * 8 + 4], false);
;               acc[m * 8 + 5] = __builtin_amdgcn_sdot4((int)__builtin_amdgcn_perm(p23l, p01l, 0x07060302u), W4, acc[m * 8 + 5], false);
;               acc[m * 8 + 6] = __builtin_amdgcn_sdot4((int)__builtin_amdgcn_perm(p23h, p01h, 0x05040100u), W4, acc[m * 8 + 6], false);
;               acc[m * 8 + 7] = __builtin_amdgcn_sdot4((int)__builtin_amdgcn_perm(p23h, p01h, 0x07060302u), W4, acc[m * 8 + 7], false);
;             }
;           }
	v_and_b32_e32 v73, 0xf0f0f0f, v73
	v_dot4c_i32_i8_e32 v153, s0, v66
	v_perm_b32 v66, v69, v64, s53
	v_perm_b32 v64, v69, v64, s54
	v_dot4c_i32_i8_e32 v147, s0, v66
	v_dot4c_i32_i8_e32 v148, s0, v64
	v_perm_b32 v64, v68, v65, s33
	v_perm_b32 v66, v73, v70, s33
	v_perm_b32 v65, v68, v65, s52
	v_perm_b32 v68, v73, v70, s52
	v_perm_b32 v69, v66, v64, s53
	v_perm_b32 v64, v66, v64, s54
	v_dot4c_i32_i8_e32 v145, s0, v64
	v_perm_b32 v64, v68, v65, s53
	v_dot4c_i32_i8_e32 v141, s0, v64
	v_perm_b32 v64, v68, v65, s54
	v_dot4c_i32_i8_e32 v142, s0, v64
	v_and_b32_e32 v64, 0xf0f0f0f, v67
	v_and_b32_e32 v66, 0xf0f0f0f, v71
	v_and_b32_e32 v68, 0xf0f0f0f, v75
	v_and_b32_e32 v70, 0xf0f0f0f, v79
	v_dot4c_i32_i8_e32 v151, s0, v72
	v_perm_b32 v72, v66, v64, s33
	v_perm_b32 v64, v66, v64, s52
	v_perm_b32 v66, v70, v68, s33
	v_dot4c_i32_i8_e32 v143, s0, v69
	v_lshrrev_b32_e32 v65, 4, v67
	v_lshrrev_b32_e32 v67, 4, v71
	v_lshrrev_b32_e32 v69, 4, v75
	v_lshrrev_b32_e32 v71, 4, v79
	v_perm_b32 v68, v70, v68, s52
	v_perm_b32 v70, v66, v72, s53
	v_perm_b32 v66, v66, v72, s54
	v_and_b32_e32 v65, 0xf0f0f0f, v65
	v_and_b32_e32 v67, 0xf0f0f0f, v67
	v_and_b32_e32 v69, 0xf0f0f0f, v69
	v_and_b32_e32 v71, 0xf0f0f0f, v71
	v_dot4c_i32_i8_e32 v140, s0, v66
	v_perm_b32 v66, v68, v64, s53
	v_perm_b32 v64, v68, v64, s54
	v_dot4c_i32_i8_e32 v137, s0, v66
	v_dot4c_i32_i8_e32 v139, s0, v64
	v_perm_b32 v64, v67, v65, s33
	v_perm_b32 v66, v71, v69, s33
	v_perm_b32 v65, v67, v65, s52
	v_perm_b32 v67, v71, v69, s52
	v_perm_b32 v68, v66, v64, s53
	v_perm_b32 v64, v66, v64, s54
	v_dot4c_i32_i8_e32 v135, s0, v64
	v_perm_b32 v64, v67, v65, s53
	v_dot4c_i32_i8_e32 v123, s0, v64
	v_perm_b32 v64, v67, v65, s54
	v_dot4c_i32_i8_e32 v125, s0, v64
	s_waitcnt vmcnt(7)
	v_and_b32_e32 v64, 0xf0f0f0f, v48
	s_waitcnt vmcnt(5)
	v_and_b32_e32 v65, 0xf0f0f0f, v52
	s_waitcnt vmcnt(3)
	v_and_b32_e32 v66, 0xf0f0f0f, v56
	s_waitcnt vmcnt(1)
	v_and_b32_e32 v67, 0xf0f0f0f, v60
	v_dot4c_i32_i8_e32 v134, s0, v68
	v_perm_b32 v68, v65, v64, s33
	v_perm_b32 v64, v65, v64, s52
	v_perm_b32 v65, v67, v66, s33
	v_dot4c_i32_i8_e32 v163, s0, v99
	v_dot4c_i32_i8_e32 v161, s0, v97
	v_dot4c_i32_i8_e32 v152, s0, v76
	v_dot4c_i32_i8_e32 v136, s0, v70
	v_readlane_b32 s0, v170, 4
	v_lshrrev_b32_e32 v48, 4, v48
	v_lshrrev_b32_e32 v52, 4, v52
	v_lshrrev_b32_e32 v56, 4, v56
	v_lshrrev_b32_e32 v60, 4, v60
	v_perm_b32 v66, v67, v66, s52
	v_perm_b32 v67, v65, v68, s53
	v_perm_b32 v65, v65, v68, s54
	v_and_b32_e32 v48, 0xf0f0f0f, v48
	v_and_b32_e32 v52, 0xf0f0f0f, v52
	v_and_b32_e32 v56, 0xf0f0f0f, v56
	v_and_b32_e32 v60, 0xf0f0f0f, v60
	v_dot4c_i32_i8_e32 v164, s0, v65
	v_perm_b32 v65, v66, v64, s53
	v_perm_b32 v64, v66, v64, s54
	v_dot4c_i32_i8_e32 v162, s0, v64
	v_perm_b32 v64, v52, v48, s33
	v_perm_b32 v48, v52, v48, s52
	v_perm_b32 v52, v60, v56, s33
	v_perm_b32 v56, v60, v56, s52
	v_perm_b32 v60, v52, v64, s53
	v_perm_b32 v52, v52, v64, s54
	v_dot4c_i32_i8_e32 v160, s0, v52
	v_perm_b32 v52, v56, v48, s53
	v_perm_b32 v48, v56, v48, s54
	v_dot4c_i32_i8_e32 v159, s0, v60
	v_dot4c_i32_i8_e32 v157, s0, v52
	v_dot4c_i32_i8_e32 v158, s0, v48
	v_and_b32_e32 v48, 0xf0f0f0f, v49
	v_and_b32_e32 v52, 0xf0f0f0f, v53
	v_and_b32_e32 v56, 0xf0f0f0f, v57
	v_and_b32_e32 v60, 0xf0f0f0f, v61
	v_perm_b32 v64, v52, v48, s33
	v_perm_b32 v48, v52, v48, s52
	v_perm_b32 v52, v60, v56, s33
	v_lshrrev_b32_e32 v49, 4, v49
	v_lshrrev_b32_e32 v53, 4, v53
	v_lshrrev_b32_e32 v57, 4, v57
	v_lshrrev_b32_e32 v61, 4, v61
	v_perm_b32 v56, v60, v56, s52
	v_perm_b32 v60, v52, v64, s53
	v_perm_b32 v52, v52, v64, s54
	v_and_b32_e32 v49, 0xf0f0f0f, v49
	v_and_b32_e32 v53, 0xf0f0f0f, v53
	v_and_b32_e32 v57, 0xf0f0f0f, v57
	v_and_b32_e32 v61, 0xf0f0f0f, v61
	v_dot4c_i32_i8_e32 v154, s0, v52
	v_perm_b32 v52, v56, v48, s53
	v_perm_b32 v48, v56, v48, s54
	v_dot4c_i32_i8_e32 v149, s0, v52
	v_dot4c_i32_i8_e32 v150, s0, v48
	v_perm_b32 v48, v53, v49, s33
	v_perm_b32 v52, v61, v57, s33
	v_perm_b32 v49, v53, v49, s52
	v_perm_b32 v53, v61, v57, s52
	v_perm_b32 v56, v52, v48, s53
	v_perm_b32 v48, v52, v48, s54
	v_dot4c_i32_i8_e32 v146, s0, v48
	v_perm_b32 v48, v53, v49, s53
	v_dot4c_i32_i8_e32 v155, s0, v48
	v_perm_b32 v48, v53, v49, s54
	v_dot4c_i32_i8_e32 v144, s0, v56
	v_dot4c_i32_i8_e32 v156, s0, v48
	v_and_b32_e32 v48, 0xf0f0f0f, v50
	v_lshrrev_b32_e32 v49, 4, v50
	v_and_b32_e32 v50, 0xf0f0f0f, v54
	v_and_b32_e32 v53, 0xf0f0f0f, v58
	v_and_b32_e32 v56, 0xf0f0f0f, v62
	v_lshrrev_b32_e32 v52, 4, v54
	v_lshrrev_b32_e32 v54, 4, v58
	v_perm_b32 v58, v50, v48, s33
	v_perm_b32 v48, v50, v48, s52
	v_perm_b32 v50, v56, v53, s33
	v_lshrrev_b32_e32 v57, 4, v62
	v_perm_b32 v53, v56, v53, s52
	v_perm_b32 v56, v50, v58, s53
	v_perm_b32 v50, v50, v58, s54
	v_and_b32_e32 v49, 0xf0f0f0f, v49
	v_and_b32_e32 v52, 0xf0f0f0f, v52
	v_and_b32_e32 v54, 0xf0f0f0f, v54
	v_and_b32_e32 v57, 0xf0f0f0f, v57
	v_dot4c_i32_i8_e32 v153, s0, v50
	v_perm_b32 v50, v53, v48, s53
	v_perm_b32 v48, v53, v48, s54
	v_dot4c_i32_i8_e32 v147, s0, v50
	v_dot4c_i32_i8_e32 v148, s0, v48
	v_perm_b32 v48, v52, v49, s33
	v_perm_b32 v50, v57, v54, s33
	v_perm_b32 v49, v52, v49, s52
	v_perm_b32 v52, v57, v54, s52
	v_perm_b32 v53, v50, v48, s53
	v_perm_b32 v48, v50, v48, s54
	v_dot4c_i32_i8_e32 v145, s0, v48
	v_perm_b32 v48, v52, v49, s53
	v_dot4c_i32_i8_e32 v141, s0, v48
	v_perm_b32 v48, v52, v49, s54
	v_dot4c_i32_i8_e32 v142, s0, v48
	v_and_b32_e32 v48, 0xf0f0f0f, v51
	v_and_b32_e32 v50, 0xf0f0f0f, v55
	v_and_b32_e32 v52, 0xf0f0f0f, v59
	v_and_b32_e32 v54, 0xf0f0f0f, v63
	v_dot4c_i32_i8_e32 v151, s0, v56
	v_perm_b32 v56, v50, v48, s33
	v_perm_b32 v48, v50, v48, s52
	v_perm_b32 v50, v54, v52, s33
	v_dot4c_i32_i8_e32 v143, s0, v53
; __device__ void phase_gather(const Params& p) {
;     ...
;         for (int sub = 0; sub < GROWS / 4; ++sub) {
;           const int W4 = __builtin_amdgcn_readlane(pkv, j0 + 4 * sub);
; #pragma unroll
;           for (int m = 0; m < 4; ++m) {
;             unsigned lo[4], hi[4];
; #pragma unroll
;             for (int k = 0; k < 4; ++k) {
;               const unsigned w = rr[gi % 3][sub * 4 + k][m];
;               lo[k] = w & 0x0f0f0f0fu;
;               hi[k] = (w >> 4) & 0x0f0f0f0fu;
;             }
;             {
;               const unsigned p01l = __builtin_amdgcn_perm(lo[1], lo[0], 0x05010400u), p01h = __builtin_amdgcn_perm(lo[1], lo[0], 0x07030602u);
;               const unsigned p23l = __builtin_amdgcn_perm(lo[3], lo[2], 0x05010400u), p23h = __builtin_amdgcn_perm(lo[3], lo[2], 0x07030602u);
;               acc[m * 8 + 0] = __builtin_amdgcn_sdot4((int)__builtin_amdgcn_perm(p23l, p01l, 0x05040100u), W4, acc[m * 8 + 0], false);
;               acc[m * 8 + 1] = __builtin_amdgcn_sdot4((int)__builtin_amdgcn_perm(p23l, p01l, 0x07060302u), W4, acc[m * 8 + 1], false);
;               acc[m * 8 + 2] = __builtin_amdgcn_sdot4((int)__builtin_amdgcn_perm(p23h, p01h, 0x05040100u), W4, acc[m * 8 + 2], false);
;               acc[m * 8 + 3] = __builtin_amdgcn_sdot4((int)__builtin_amdgcn_perm(p23h, p01h, 0x07060302u), W4, acc[m * 8 + 3], false);
;             }
;             {
;               const unsigned p01l = __builtin_amdgcn_perm(hi[1], hi[0], 0x05010400u), p01h = __builtin_amdgcn_perm(hi[1], hi[0], 0x07030602u);
;               const unsigned p23l = __builtin_amdgcn_perm(hi[3], hi[2], 0x05010400u), p23h = __builtin_amdgcn_perm(hi[3], hi[2], 0x07030602u);
;               acc[m * 8 + 4] = __builtin_amdgcn_sdot4((int)__builtin_amdgcn_perm(p23l, p01l, 0x05040100u), W4, acc[m * 8 + 4], false);
;               acc[m * 8 + 5] = __builtin_amdgcn_sdot4((int)__builtin_amdgcn_perm(p23l, p01l, 0x07060302u), W4, acc[m * 8 + 5], false);
;               acc[m * 8 + 6] = __builtin_amdgcn_sdot4((int)__builtin_amdgcn_perm(p23h, p01h, 0x05040100u), W4, acc[m * 8 + 6], false);
;               acc[m * 8 + 7] = __builtin_amdgcn_sdot4((int)__builtin_amdgcn_perm(p23h, p01h, 0x07060302u), W4, acc[m * 8 + 7], false);
;             }
;           }
	v_lshrrev_b32_e32 v49, 4, v51
	v_lshrrev_b32_e32 v51, 4, v55
	v_lshrrev_b32_e32 v53, 4, v59
	v_lshrrev_b32_e32 v55, 4, v63
	v_perm_b32 v52, v54, v52, s52
	v_perm_b32 v54, v50, v56, s53
	v_perm_b32 v50, v50, v56, s54
	v_and_b32_e32 v49, 0xf0f0f0f, v49
	v_and_b32_e32 v51, 0xf0f0f0f, v51
	v_and_b32_e32 v53, 0xf0f0f0f, v53
	v_and_b32_e32 v55, 0xf0f0f0f, v55
	v_dot4c_i32_i8_e32 v140, s0, v50
	v_perm_b32 v50, v52, v48, s53
	v_perm_b32 v48, v52, v48, s54
	v_dot4c_i32_i8_e32 v137, s0, v50
	v_dot4c_i32_i8_e32 v139, s0, v48
	v_perm_b32 v48, v51, v49, s33
	v_perm_b32 v50, v55, v53, s33
	v_perm_b32 v49, v51, v49, s52
	v_perm_b32 v51, v55, v53, s52
	v_perm_b32 v52, v50, v48, s53
	v_perm_b32 v48, v50, v48, s54
	v_dot4c_i32_i8_e32 v135, s0, v48
	v_perm_b32 v48, v51, v49, s53
	v_and_b32_e32 v96, 0xf0f0f0f, v80
	v_and_b32_e32 v97, 0xf0f0f0f, v84
	v_and_b32_e32 v98, 0xf0f0f0f, v88
	v_and_b32_e32 v99, 0xf0f0f0f, v92
	v_dot4c_i32_i8_e32 v123, s0, v48
	v_perm_b32 v48, v51, v49, s54
	v_perm_b32 v100, v97, v96, s33
	v_perm_b32 v96, v97, v96, s52
	v_perm_b32 v97, v99, v98, s33
	v_dot4c_i32_i8_e32 v163, s0, v67
	v_dot4c_i32_i8_e32 v161, s0, v65
	v_dot4c_i32_i8_e32 v152, s0, v60
	v_dot4c_i32_i8_e32 v136, s0, v54
	v_dot4c_i32_i8_e32 v134, s0, v52
	v_dot4c_i32_i8_e32 v125, s0, v48
	v_readlane_b32 s0, v170, 8
	v_lshrrev_b32_e32 v80, 4, v80
	v_lshrrev_b32_e32 v84, 4, v84
	v_lshrrev_b32_e32 v88, 4, v88
	v_lshrrev_b32_e32 v92, 4, v92
	v_perm_b32 v98, v99, v98, s52
	v_perm_b32 v99, v97, v100, s53
	v_perm_b32 v97, v97, v100, s54
	v_and_b32_e32 v80, 0xf0f0f0f, v80
	v_and_b32_e32 v84, 0xf0f0f0f, v84
	v_and_b32_e32 v88, 0xf0f0f0f, v88
	v_and_b32_e32 v92, 0xf0f0f0f, v92
	v_dot4c_i32_i8_e32 v164, s0, v97
	v_perm_b32 v97, v98, v96, s53
	v_perm_b32 v96, v98, v96, s54
	v_dot4c_i32_i8_e32 v162, s0, v96
	v_perm_b32 v96, v84, v80, s33
	v_perm_b32 v80, v84, v80, s52
	v_perm_b32 v84, v92, v88, s33
	v_perm_b32 v88, v92, v88, s52
	v_perm_b32 v92, v84, v96, s53
	v_perm_b32 v84, v84, v96, s54
	v_dot4c_i32_i8_e32 v160, s0, v84
	v_perm_b32 v84, v88, v80, s53
	v_perm_b32 v80, v88, v80, s54
	v_dot4c_i32_i8_e32 v159, s0, v92
	v_dot4c_i32_i8_e32 v157, s0, v84
	v_dot4c_i32_i8_e32 v158, s0, v80
	v_and_b32_e32 v80, 0xf0f0f0f, v81
	v_and_b32_e32 v84, 0xf0f0f0f, v85
	v_and_b32_e32 v88, 0xf0f0f0f, v89
	v_and_b32_e32 v92, 0xf0f0f0f, v93
	v_perm_b32 v96, v84, v80, s33
	v_perm_b32 v80, v84, v80, s52
	v_perm_b32 v84, v92, v88, s33
	v_lshrrev_b32_e32 v81, 4, v81
	v_lshrrev_b32_e32 v85, 4, v85
	v_lshrrev_b32_e32 v89, 4, v89
	v_lshrrev_b32_e32 v93, 4, v93
	v_perm_b32 v88, v92, v88, s52
	v_perm_b32 v92, v84, v96, s53
	v_perm_b32 v84, v84, v96, s54
	v_and_b32_e32 v81, 0xf0f0f0f, v81
	v_and_b32_e32 v85, 0xf0f0f0f, v85
	v_and_b32_e32 v89, 0xf0f0f0f, v89
	v_and_b32_e32 v93, 0xf0f0f0f, v93
	v_dot4c_i32_i8_e32 v154, s0, v84
	v_perm_b32 v84, v88, v80, s53
	v_perm_b32 v80, v88, v80, s54
	v_dot4c_i32_i8_e32 v149, s0, v84
	v_dot4c_i32_i8_e32 v150, s0, v80
	v_perm_b32 v80, v85, v81, s33
	v_perm_b32 v84, v93, v89, s33
	v_perm_b32 v81, v85, v81, s52
	v_perm_b32 v85, v93, v89, s52
	v_perm_b32 v88, v84, v80, s53
	v_perm_b32 v80, v84, v80, s54
	v_dot4c_i32_i8_e32 v146, s0, v80
	v_perm_b32 v80, v85, v81, s53
	v_dot4c_i32_i8_e32 v155, s0, v80
	v_perm_b32 v80, v85, v81, s54
	v_dot4c_i32_i8_e32 v144, s0, v88
	v_dot4c_i32_i8_e32 v156, s0, v80
	v_and_b32_e32 v80, 0xf0f0f0f, v82
	v_lshrrev_b32_e32 v81, 4, v82
	v_and_b32_e32 v82, 0xf0f0f0f, v86
	v_and_b32_e32 v85, 0xf0f0f0f, v90
	v_and_b32_e32 v88, 0xf0f0f0f, v94
	v_lshrrev_b32_e32 v84, 4, v86
	v_lshrrev_b32_e32 v86, 4, v90
	v_perm_b32 v90, v82, v80, s33
	v_perm_b32 v80, v82, v80, s52
	v_perm_b32 v82, v88, v85, s33
	v_lshrrev_b32_e32 v89, 4, v94
	v_perm_b32 v85, v88, v85, s52
	v_perm_b32 v88, v82, v90, s53
	v_perm_b32 v82, v82, v90, s54
	v_and_b32_e32 v81, 0xf0f0f0f, v81
	v_and_b32_e32 v84, 0xf0f0f0f, v84
	v_and_b32_e32 v86, 0xf0f0f0f, v86
	v_and_b32_e32 v89, 0xf0f0f0f, v89
	v_dot4c_i32_i8_e32 v153, s0, v82
	v_perm_b32 v82, v85, v80, s53
	v_perm_b32 v80, v85, v80, s54
	v_dot4c_i32_i8_e32 v147, s0, v82
	v_dot4c_i32_i8_e32 v148, s0, v80
	v_perm_b32 v80, v84, v81, s33
	v_perm_b32 v82, v89, v86, s33
	v_perm_b32 v81, v84, v81, s52
	v_perm_b32 v84, v89, v86, s52
	v_perm_b32 v85, v82, v80, s53
	v_perm_b32 v80, v82, v80, s54
	v_dot4c_i32_i8_e32 v145, s0, v80
	v_perm_b32 v80, v84, v81, s53
	v_dot4c_i32_i8_e32 v141, s0, v80
	v_perm_b32 v80, v84, v81, s54
	v_dot4c_i32_i8_e32 v142, s0, v80
	v_and_b32_e32 v80, 0xf0f0f0f, v83
	v_and_b32_e32 v82, 0xf0f0f0f, v87
	v_and_b32_e32 v84, 0xf0f0f0f, v91
	v_and_b32_e32 v86, 0xf0f0f0f, v95
	v_dot4c_i32_i8_e32 v151, s0, v88
	v_perm_b32 v88, v82, v80, s33
	v_perm_b32 v80, v82, v80, s52
	v_perm_b32 v82, v86, v84, s33
	v_dot4c_i32_i8_e32 v143, s0, v85
	v_lshrrev_b32_e32 v81, 4, v83
	v_lshrrev_b32_e32 v83, 4, v87
	v_lshrrev_b32_e32 v85, 4, v91
	v_lshrrev_b32_e32 v87, 4, v95
	v_perm_b32 v84, v86, v84, s52
	v_perm_b32 v86, v82, v88, s53
	v_perm_b32 v82, v82, v88, s54
	v_and_b32_e32 v81, 0xf0f0f0f, v81
	v_and_b32_e32 v83, 0xf0f0f0f, v83
	v_and_b32_e32 v85, 0xf0f0f0f, v85
	v_and_b32_e32 v87, 0xf0f0f0f, v87
	v_dot4c_i32_i8_e32 v140, s0, v82
	v_perm_b32 v82, v84, v80, s53
	v_perm_b32 v80, v84, v80, s54
	v_dot4c_i32_i8_e32 v137, s0, v82
	v_dot4c_i32_i8_e32 v139, s0, v80
	v_perm_b32 v80, v83, v81, s33
	v_perm_b32 v82, v87, v85, s33
	v_perm_b32 v81, v83, v81, s52
	v_perm_b32 v83, v87, v85, s52
	v_perm_b32 v84, v82, v80, s53
	v_perm_b32 v80, v82, v80, s54
	v_dot4c_i32_i8_e32 v135, s0, v80
	v_perm_b32 v80, v83, v81, s53
	v_lshl_add_u64 v[48:49], v[116:117], 0, s[84:85]
	v_dot4c_i32_i8_e32 v123, s0, v80
	v_perm_b32 v80, v83, v81, s54
	global_load_dwordx4 v[72:75], v[48:49], off
	v_dot4c_i32_i8_e32 v125, s0, v80
	v_and_b32_e32 v80, 0xf0f0f0f, v32
	v_and_b32_e32 v81, 0xf0f0f0f, v36
	v_and_b32_e32 v82, 0xf0f0f0f, v40
	s_waitcnt vmcnt(1)
; __device__ void phase_gather(const Params& p) {
;     ...
;         for (int sub = 0; sub < GROWS / 4; ++sub) {
;           const int W4 = __builtin_amdgcn_readlane(pkv, j0 + 4 * sub);
; #pragma unroll
;           for (int m = 0; m < 4; ++m) {
;             unsigned lo[4], hi[4];
; #pragma unroll
;             for (int k = 0; k < 4; ++k) {
;               const unsigned w = rr[gi % 3][sub * 4 + k][m];
;               lo[k] = w & 0x0f0f0f0fu;
;               hi[k] = (w >> 4) & 0x0f0f0f0fu;
;             }
;             {
;               const unsigned p01l = __builtin_amdgcn_perm(lo[1], lo[0], 0x05010400u), p01h = __builtin_amdgcn_perm(lo[1], lo[0], 0x07030602u);
;               const unsigned p23l = __builtin_amdgcn_perm(lo[3], lo[2], 0x05010400u), p23h = __builtin_amdgcn_perm(lo[3], lo[2], 0x07030602u);
;               acc[m * 8 + 0] = __builtin_amdgcn_sdot4((int)__builtin_amdgcn_perm(p23l, p01l, 0x05040100u), W4, acc[m * 8 + 0], false);
;               acc[m * 8 + 1] = __builtin_amdgcn_sdot4((int)__builtin_amdgcn_perm(p23l, p01l, 0x07060302u), W4, acc[m * 8 + 1], false);
;               acc[m * 8 + 2] = __builtin_amdgcn_sdot4((int)__builtin_amdgcn_perm(p23h, p01h, 0x05040100u), W4, acc[m * 8 + 2], false);
;               acc[m * 8 + 3] = __builtin_amdgcn_sdot4((int)__builtin_amdgcn_perm(p23h, p01h, 0x07060302u), W4, acc[m * 8 + 3], false);
;             }
;             {
;               const unsigned p01l = __builtin_amdgcn_perm(hi[1], hi[0], 0x05010400u), p01h = __builtin_amdgcn_perm(hi[1], hi[0], 0x07030602u);
;               const unsigned p23l = __builtin_amdgcn_perm(hi[3], hi[2], 0x05010400u), p23h = __builtin_amdgcn_perm(hi[3], hi[2], 0x07030602u);
;               acc[m * 8 + 4] = __builtin_amdgcn_sdot4((int)__builtin_amdgcn_perm(p23l, p01l, 0x05040100u), W4, acc[m * 8 + 4], false);
;               acc[m * 8 + 5] = __builtin_amdgcn_sdot4((int)__builtin_amdgcn_perm(p23l, p01l, 0x07060302u), W4, acc[m * 8 + 5], false);
;               acc[m * 8 + 6] = __builtin_amdgcn_sdot4((int)__builtin_amdgcn_perm(p23h, p01h, 0x05040100u), W4, acc[m * 8 + 6], false);
;               acc[m * 8 + 7] = __builtin_amdgcn_sdot4((int)__builtin_amdgcn_perm(p23h, p01h, 0x07060302u), W4, acc[m * 8 + 7], false);
;             }
;           }
	v_and_b32_e32 v83, 0xf0f0f0f, v44
	v_dot4c_i32_i8_e32 v134, s0, v84
	v_perm_b32 v84, v81, v80, s33
	v_perm_b32 v80, v81, v80, s52
	v_perm_b32 v81, v83, v82, s33
	v_dot4c_i32_i8_e32 v163, s0, v99
	v_dot4c_i32_i8_e32 v161, s0, v97
	v_dot4c_i32_i8_e32 v152, s0, v92
	v_dot4c_i32_i8_e32 v136, s0, v86
	v_readlane_b32 s0, v170, 12
	v_lshrrev_b32_e32 v32, 4, v32
	v_lshrrev_b32_e32 v36, 4, v36
	v_lshrrev_b32_e32 v40, 4, v40
	v_lshrrev_b32_e32 v44, 4, v44
	v_perm_b32 v82, v83, v82, s52
	v_perm_b32 v83, v81, v84, s53
	v_perm_b32 v81, v81, v84, s54
	v_and_b32_e32 v32, 0xf0f0f0f, v32
	v_and_b32_e32 v36, 0xf0f0f0f, v36
	v_and_b32_e32 v40, 0xf0f0f0f, v40
	v_and_b32_e32 v44, 0xf0f0f0f, v44
	v_dot4c_i32_i8_e32 v164, s0, v81
	v_perm_b32 v81, v82, v80, s53
	v_perm_b32 v80, v82, v80, s54
	v_dot4c_i32_i8_e32 v162, s0, v80
	v_perm_b32 v80, v36, v32, s33
	v_perm_b32 v32, v36, v32, s52
	v_perm_b32 v36, v44, v40, s33
	v_perm_b32 v40, v44, v40, s52
	v_perm_b32 v44, v36, v80, s53
	v_perm_b32 v36, v36, v80, s54
	v_dot4c_i32_i8_e32 v160, s0, v36
	v_perm_b32 v36, v40, v32, s53
	v_perm_b32 v32, v40, v32, s54
	v_dot4c_i32_i8_e32 v159, s0, v44
	v_dot4c_i32_i8_e32 v157, s0, v36
	v_dot4c_i32_i8_e32 v158, s0, v32
	v_and_b32_e32 v32, 0xf0f0f0f, v33
	v_and_b32_e32 v36, 0xf0f0f0f, v37
	v_and_b32_e32 v40, 0xf0f0f0f, v41
	v_and_b32_e32 v44, 0xf0f0f0f, v45
	v_perm_b32 v80, v36, v32, s33
	v_perm_b32 v32, v36, v32, s52
	v_perm_b32 v36, v44, v40, s33
	v_lshrrev_b32_e32 v33, 4, v33
	v_lshrrev_b32_e32 v37, 4, v37
	v_lshrrev_b32_e32 v41, 4, v41
	v_lshrrev_b32_e32 v45, 4, v45
	v_perm_b32 v40, v44, v40, s52
	v_perm_b32 v44, v36, v80, s53
	v_perm_b32 v36, v36, v80, s54
	v_and_b32_e32 v33, 0xf0f0f0f, v33
	v_and_b32_e32 v37, 0xf0f0f0f, v37
	v_and_b32_e32 v41, 0xf0f0f0f, v41
	v_and_b32_e32 v45, 0xf0f0f0f, v45
	v_dot4c_i32_i8_e32 v154, s0, v36
	v_perm_b32 v36, v40, v32, s53
	v_perm_b32 v32, v40, v32, s54
	v_dot4c_i32_i8_e32 v149, s0, v36
	v_dot4c_i32_i8_e32 v150, s0, v32
	v_perm_b32 v32, v37, v33, s33
	v_perm_b32 v36, v45, v41, s33
	v_perm_b32 v33, v37, v33, s52
	v_perm_b32 v37, v45, v41, s52
	v_perm_b32 v40, v36, v32, s53
	v_perm_b32 v32, v36, v32, s54
	v_dot4c_i32_i8_e32 v146, s0, v32
	v_perm_b32 v32, v37, v33, s53
	v_dot4c_i32_i8_e32 v155, s0, v32
	v_perm_b32 v32, v37, v33, s54
	v_dot4c_i32_i8_e32 v144, s0, v40
	v_dot4c_i32_i8_e32 v156, s0, v32
	v_and_b32_e32 v32, 0xf0f0f0f, v34
	v_lshrrev_b32_e32 v33, 4, v34
	v_and_b32_e32 v34, 0xf0f0f0f, v38
	v_and_b32_e32 v37, 0xf0f0f0f, v42
	v_and_b32_e32 v40, 0xf0f0f0f, v46
	v_lshrrev_b32_e32 v36, 4, v38
	v_lshrrev_b32_e32 v38, 4, v42
	v_perm_b32 v42, v34, v32, s33
	v_perm_b32 v32, v34, v32, s52
	v_perm_b32 v34, v40, v37, s33
	v_lshrrev_b32_e32 v41, 4, v46
	v_perm_b32 v37, v40, v37, s52
	v_perm_b32 v40, v34, v42, s53
	v_perm_b32 v34, v34, v42, s54
	v_and_b32_e32 v33, 0xf0f0f0f, v33
	v_and_b32_e32 v36, 0xf0f0f0f, v36
	v_and_b32_e32 v38, 0xf0f0f0f, v38
	v_and_b32_e32 v41, 0xf0f0f0f, v41
	v_dot4c_i32_i8_e32 v153, s0, v34
	v_perm_b32 v34, v37, v32, s53
	v_perm_b32 v32, v37, v32, s54
	v_dot4c_i32_i8_e32 v147, s0, v34
	v_dot4c_i32_i8_e32 v148, s0, v32
	v_perm_b32 v32, v36, v33, s33
	v_perm_b32 v34, v41, v38, s33
	v_perm_b32 v33, v36, v33, s52
	v_perm_b32 v36, v41, v38, s52
	v_perm_b32 v37, v34, v32, s53
	v_perm_b32 v32, v34, v32, s54
	v_dot4c_i32_i8_e32 v145, s0, v32
	v_perm_b32 v32, v36, v33, s53
	v_dot4c_i32_i8_e32 v141, s0, v32
	v_perm_b32 v32, v36, v33, s54
	v_dot4c_i32_i8_e32 v142, s0, v32
	v_and_b32_e32 v32, 0xf0f0f0f, v35
	v_and_b32_e32 v34, 0xf0f0f0f, v39
	v_and_b32_e32 v36, 0xf0f0f0f, v43
	v_and_b32_e32 v38, 0xf0f0f0f, v47
	v_dot4c_i32_i8_e32 v151, s0, v40
	v_perm_b32 v40, v34, v32, s33
	v_perm_b32 v32, v34, v32, s52
	v_perm_b32 v34, v38, v36, s33
	v_dot4c_i32_i8_e32 v143, s0, v37
	v_lshrrev_b32_e32 v33, 4, v35
	v_lshrrev_b32_e32 v35, 4, v39
	v_lshrrev_b32_e32 v37, 4, v43
	v_lshrrev_b32_e32 v39, 4, v47
	v_perm_b32 v36, v38, v36, s52
	v_perm_b32 v38, v34, v40, s53
	v_perm_b32 v34, v34, v40, s54
	v_and_b32_e32 v33, 0xf0f0f0f, v33
	v_and_b32_e32 v35, 0xf0f0f0f, v35
	v_and_b32_e32 v37, 0xf0f0f0f, v37
	v_and_b32_e32 v39, 0xf0f0f0f, v39
	v_dot4c_i32_i8_e32 v140, s0, v34
	v_perm_b32 v34, v36, v32, s53
	v_perm_b32 v32, v36, v32, s54
	v_dot4c_i32_i8_e32 v137, s0, v34
	v_dot4c_i32_i8_e32 v139, s0, v32
	v_perm_b32 v32, v35, v33, s33
	v_perm_b32 v34, v39, v37, s33
	v_perm_b32 v33, v35, v33, s52
	v_perm_b32 v35, v39, v37, s52
	v_perm_b32 v36, v34, v32, s53
	v_perm_b32 v32, v34, v32, s54
	v_dot4c_i32_i8_e32 v135, s0, v32
	v_perm_b32 v32, v35, v33, s53
	v_dot4c_i32_i8_e32 v123, s0, v32
	v_perm_b32 v32, v35, v33, s54
	v_lshl_add_u64 v[0:1], v[116:117], 0, s[16:17]
	v_dot4c_i32_i8_e32 v125, s0, v32
	v_lshl_add_u64 v[32:33], v[116:117], 0, s[66:67]
	global_load_dwordx4 v[28:31], v[0:1], off
	global_load_dwordx4 v[108:111], v[32:33], off
	v_lshl_add_u64 v[0:1], v[116:117], 0, s[14:15]
	v_lshl_add_u64 v[32:33], v[116:117], 0, s[68:69]
	global_load_dwordx4 v[24:27], v[0:1], off
	global_load_dwordx4 v[104:107], v[32:33], off
	v_lshl_add_u64 v[0:1], v[116:117], 0, s[12:13]
	v_lshl_add_u64 v[32:33], v[116:117], 0, s[70:71]
	global_load_dwordx4 v[20:23], v[0:1], off
	global_load_dwordx4 v[100:103], v[32:33], off
	v_lshl_add_u64 v[0:1], v[116:117], 0, s[10:11]
	global_load_dwordx4 v[16:19], v[0:1], off
	v_lshl_add_u64 v[32:33], v[116:117], 0, s[72:73]
	v_dot4c_i32_i8_e32 v163, s0, v83
	v_dot4c_i32_i8_e32 v161, s0, v81
	global_load_dwordx4 v[96:99], v[32:33], off
	v_dot4c_i32_i8_e32 v152, s0, v44
	v_dot4c_i32_i8_e32 v136, s0, v38
	v_dot4c_i32_i8_e32 v134, s0, v36
	v_readlane_b32 s0, v170, 16
	v_lshl_add_u64 v[0:1], v[116:117], 0, s[8:9]
	global_load_dwordx4 v[12:15], v[0:1], off
	v_lshl_add_u64 v[32:33], v[116:117], 0, s[74:75]
	global_load_dwordx4 v[44:47], v[32:33], off
	v_lshl_add_u64 v[32:33], v[116:117], 0, s[76:77]
	v_lshl_add_u64 v[48:49], v[116:117], 0, s[82:83]
	global_load_dwordx4 v[40:43], v[32:33], off
	v_lshl_add_u64 v[32:33], v[116:117], 0, s[78:79]
	global_load_dwordx4 v[76:79], v[48:49], off
	global_load_dwordx4 v[36:39], v[32:33], off
	v_lshl_add_u64 v[48:49], v[116:117], 0, s[86:87]
	v_lshl_add_u64 v[32:33], v[116:117], 0, s[80:81]
	global_load_dwordx4 v[68:71], v[48:49], off
	s_waitcnt vmcnt(13)
; __device__ void phase_gather(const Params& p) {
;     ...
;         for (int sub = 0; sub < GROWS / 4; ++sub) {
;           const int W4 = __builtin_amdgcn_readlane(pkv, j0 + 4 * sub);
; #pragma unroll
;           for (int m = 0; m < 4; ++m) {
;             unsigned lo[4], hi[4];
; #pragma unroll
;             for (int k = 0; k < 4; ++k) {
;               const unsigned w = rr[gi % 3][sub * 4 + k][m];
;               lo[k] = w & 0x0f0f0f0fu;
;               hi[k] = (w >> 4) & 0x0f0f0f0fu;
;             }
;             {
;               const unsigned p01l = __builtin_amdgcn_perm(lo[1], lo[0], 0x05010400u), p01h = __builtin_amdgcn_perm(lo[1], lo[0], 0x07030602u);
;               const unsigned p23l = __builtin_amdgcn_perm(lo[3], lo[2], 0x05010400u), p23h = __builtin_amdgcn_perm(lo[3], lo[2], 0x07030602u);
;               acc[m * 8 + 0] = __builtin_amdgcn_sdot4((int)__builtin_amdgcn_perm(p23l, p01l, 0x05040100u), W4, acc[m * 8 + 0], false);
;               acc[m * 8 + 1] = __builtin_amdgcn_sdot4((int)__builtin_amdgcn_perm(p23l, p01l, 0x07060302u), W4, acc[m * 8 + 1], false);
;               acc[m * 8 + 2] = __builtin_amdgcn_sdot4((int)__builtin_amdgcn_perm(p23h, p01h, 0x05040100u), W4, acc[m * 8 + 2], false);
;               acc[m * 8 + 3] = __builtin_amdgcn_sdot4((int)__builtin_amdgcn_perm(p23h, p01h, 0x07060302u), W4, acc[m * 8 + 3], false);
;             }
;             {
;               const unsigned p01l = __builtin_amdgcn_perm(hi[1], hi[0], 0x05010400u), p01h = __builtin_amdgcn_perm(hi[1], hi[0], 0x07030602u);
;               const unsigned p23l = __builtin_amdgcn_perm(hi[3], hi[2], 0x05010400u), p23h = __builtin_amdgcn_perm(hi[3], hi[2], 0x07030602u);
;               acc[m * 8 + 4] = __builtin_amdgcn_sdot4((int)__builtin_amdgcn_perm(p23l, p01l, 0x05040100u), W4, acc[m * 8 + 4], false);
;               acc[m * 8 + 5] = __builtin_amdgcn_sdot4((int)__builtin_amdgcn_perm(p23l, p01l, 0x07060302u), W4, acc[m * 8 + 5], false);
;               acc[m * 8 + 6] = __builtin_amdgcn_sdot4((int)__builtin_amdgcn_perm(p23h, p01h, 0x05040100u), W4, acc[m * 8 + 6], false);
;               acc[m * 8 + 7] = __builtin_amdgcn_sdot4((int)__builtin_amdgcn_perm(p23h, p01h, 0x07060302u), W4, acc[m * 8 + 7], false);
;             }
;           }
	v_and_b32_e32 v80, 0xf0f0f0f, v28
	v_lshrrev_b32_e32 v28, 4, v28
	v_and_b32_e32 v28, 0xf0f0f0f, v28
	global_load_dwordx4 v[32:35], v[32:33], off
	s_waitcnt vmcnt(12)
	v_and_b32_e32 v81, 0xf0f0f0f, v24
	v_perm_b32 v84, v81, v80, s33
	v_perm_b32 v80, v81, v80, s52
	v_lshrrev_b32_e32 v24, 4, v24
	s_waitcnt vmcnt(10)
	v_and_b32_e32 v82, 0xf0f0f0f, v20
	v_lshrrev_b32_e32 v20, 4, v20
	v_and_b32_e32 v24, 0xf0f0f0f, v24
	s_waitcnt vmcnt(8)
	v_and_b32_e32 v83, 0xf0f0f0f, v16
	v_perm_b32 v81, v83, v82, s33
	v_lshrrev_b32_e32 v16, 4, v16
	v_perm_b32 v82, v83, v82, s52
	v_perm_b32 v83, v81, v84, s53
	v_perm_b32 v81, v81, v84, s54
	v_and_b32_e32 v20, 0xf0f0f0f, v20
	v_and_b32_e32 v16, 0xf0f0f0f, v16
	v_dot4c_i32_i8_e32 v164, s0, v81
	v_perm_b32 v81, v82, v80, s53
	v_perm_b32 v80, v82, v80, s54
	v_dot4c_i32_i8_e32 v162, s0, v80
	v_perm_b32 v80, v24, v28, s33
	v_perm_b32 v24, v24, v28, s52
	v_perm_b32 v28, v16, v20, s33
	v_perm_b32 v16, v16, v20, s52
	v_perm_b32 v20, v28, v80, s53
	v_dot4c_i32_i8_e32 v159, s0, v20
	v_perm_b32 v20, v28, v80, s54
	v_dot4c_i32_i8_e32 v160, s0, v20
	v_perm_b32 v20, v16, v24, s53
	v_perm_b32 v16, v16, v24, s54
	v_dot4c_i32_i8_e32 v157, s0, v20
	v_dot4c_i32_i8_e32 v158, s0, v16
	v_and_b32_e32 v16, 0xf0f0f0f, v29
	v_lshrrev_b32_e32 v20, 4, v29
	v_and_b32_e32 v24, 0xf0f0f0f, v25
	v_and_b32_e32 v28, 0xf0f0f0f, v21
	v_and_b32_e32 v29, 0xf0f0f0f, v17
	v_perm_b32 v80, v24, v16, s33
	v_perm_b32 v16, v24, v16, s52
	v_perm_b32 v24, v29, v28, s33
	v_lshrrev_b32_e32 v25, 4, v25
	v_lshrrev_b32_e32 v21, 4, v21
	v_lshrrev_b32_e32 v17, 4, v17
	v_perm_b32 v28, v29, v28, s52
	v_perm_b32 v29, v24, v80, s53
	v_perm_b32 v24, v24, v80, s54
	v_and_b32_e32 v20, 0xf0f0f0f, v20
	v_and_b32_e32 v25, 0xf0f0f0f, v25
	v_and_b32_e32 v21, 0xf0f0f0f, v21
	v_and_b32_e32 v17, 0xf0f0f0f, v17
	v_dot4c_i32_i8_e32 v154, s0, v24
	v_perm_b32 v24, v28, v16, s53
	v_perm_b32 v16, v28, v16, s54
	v_dot4c_i32_i8_e32 v149, s0, v24
	v_dot4c_i32_i8_e32 v150, s0, v16
	v_perm_b32 v16, v25, v20, s33
	v_perm_b32 v24, v17, v21, s33
	v_perm_b32 v20, v25, v20, s52
	v_perm_b32 v17, v17, v21, s52
	v_perm_b32 v21, v24, v16, s53
	v_perm_b32 v16, v24, v16, s54
	v_dot4c_i32_i8_e32 v146, s0, v16
	v_perm_b32 v16, v17, v20, s53
	v_dot4c_i32_i8_e32 v155, s0, v16
	v_perm_b32 v16, v17, v20, s54
	v_dot4c_i32_i8_e32 v156, s0, v16
	v_and_b32_e32 v16, 0xf0f0f0f, v30
	v_and_b32_e32 v20, 0xf0f0f0f, v26
	v_and_b32_e32 v24, 0xf0f0f0f, v22
	v_and_b32_e32 v25, 0xf0f0f0f, v18
	v_dot4c_i32_i8_e32 v144, s0, v21
	v_lshrrev_b32_e32 v21, 4, v26
	v_perm_b32 v26, v20, v16, s33
	v_perm_b32 v16, v20, v16, s52
	v_perm_b32 v20, v25, v24, s33
	v_lshrrev_b32_e32 v17, 4, v30
	v_lshrrev_b32_e32 v22, 4, v22
	v_lshrrev_b32_e32 v18, 4, v18
	v_perm_b32 v24, v25, v24, s52
	v_perm_b32 v25, v20, v26, s53
	v_perm_b32 v20, v20, v26, s54
	v_and_b32_e32 v17, 0xf0f0f0f, v17
	v_and_b32_e32 v21, 0xf0f0f0f, v21
	v_and_b32_e32 v22, 0xf0f0f0f, v22
	v_and_b32_e32 v18, 0xf0f0f0f, v18
	v_dot4c_i32_i8_e32 v153, s0, v20
	v_perm_b32 v20, v24, v16, s53
	v_perm_b32 v16, v24, v16, s54
	v_dot4c_i32_i8_e32 v147, s0, v20
	v_dot4c_i32_i8_e32 v148, s0, v16
	v_perm_b32 v16, v21, v17, s33
	v_perm_b32 v20, v18, v22, s33
	v_perm_b32 v17, v21, v17, s52
	v_perm_b32 v18, v18, v22, s52
	v_perm_b32 v21, v20, v16, s53
	v_perm_b32 v16, v20, v16, s54
	v_dot4c_i32_i8_e32 v145, s0, v16
	v_perm_b32 v16, v18, v17, s53
	v_dot4c_i32_i8_e32 v141, s0, v16
	v_perm_b32 v16, v18, v17, s54
	v_dot4c_i32_i8_e32 v143, s0, v21
	v_dot4c_i32_i8_e32 v142, s0, v16
	v_and_b32_e32 v16, 0xf0f0f0f, v31
	v_and_b32_e32 v18, 0xf0f0f0f, v27
	v_and_b32_e32 v21, 0xf0f0f0f, v23
	v_lshrrev_b32_e32 v22, 4, v23
	v_and_b32_e32 v23, 0xf0f0f0f, v19
	v_perm_b32 v24, v18, v16, s33
	v_perm_b32 v16, v18, v16, s52
	v_perm_b32 v18, v23, v21, s33
	v_dot4c_i32_i8_e32 v151, s0, v25
	v_perm_b32 v21, v23, v21, s52
	v_perm_b32 v23, v18, v24, s53
	v_perm_b32 v18, v18, v24, s54
	v_lshl_add_u64 v[24:25], v[116:117], 0, s[62:63]
	v_dot4c_i32_i8_e32 v152, s0, v29
	v_lshrrev_b32_e32 v20, 4, v27
	global_load_dwordx4 v[24:27], v[24:25], off
	v_lshl_add_u64 v[0:1], v[116:117], 0, s[6:7]
	v_lshl_add_u64 v[28:29], v[116:117], 0, s[64:65]
	global_load_dwordx4 v[8:11], v[0:1], off
	v_lshrrev_b32_e32 v17, 4, v31
	global_load_dwordx4 v[28:31], v[28:29], off
	v_lshl_add_u64 v[0:1], v[116:117], 0, s[4:5]
	global_load_dwordx4 v[4:7], v[0:1], off
	v_lshl_add_u64 v[0:1], v[116:117], 0, s[2:3]
	global_load_dwordx4 v[0:3], v[0:1], off
	v_lshl_add_u64 v[48:49], v[116:117], 0, s[88:89]
	global_load_dwordx4 v[64:67], v[48:49], off
	v_lshl_add_u64 v[48:49], v[116:117], 0, s[90:91]
	global_load_dwordx4 v[60:63], v[48:49], off
	v_lshl_add_u64 v[48:49], v[116:117], 0, s[92:93]
	global_load_dwordx4 v[56:59], v[48:49], off
	v_lshl_add_u64 v[48:49], v[116:117], 0, s[94:95]
	global_load_dwordx4 v[52:55], v[48:49], off
	v_lshl_add_u64 v[48:49], v[116:117], 0, s[96:97]
	global_load_dwordx4 v[48:51], v[48:49], off
	v_lshrrev_b32_e32 v19, 4, v19
	v_and_b32_e32 v17, 0xf0f0f0f, v17
	v_and_b32_e32 v20, 0xf0f0f0f, v20
	v_and_b32_e32 v22, 0xf0f0f0f, v22
	v_and_b32_e32 v19, 0xf0f0f0f, v19
	v_dot4c_i32_i8_e32 v140, s0, v18
	v_perm_b32 v18, v21, v16, s53
	v_perm_b32 v16, v21, v16, s54
	v_dot4c_i32_i8_e32 v137, s0, v18
	v_dot4c_i32_i8_e32 v139, s0, v16
	v_perm_b32 v16, v20, v17, s33
	v_perm_b32 v18, v19, v22, s33
	v_perm_b32 v17, v20, v17, s52
	v_perm_b32 v19, v19, v22, s52
	v_perm_b32 v20, v18, v16, s53
	v_perm_b32 v16, v18, v16, s54
	v_dot4c_i32_i8_e32 v135, s0, v16
	v_perm_b32 v16, v19, v17, s53
	v_dot4c_i32_i8_e32 v123, s0, v16
	v_perm_b32 v16, v19, v17, s54
	v_dot4c_i32_i8_e32 v125, s0, v16
	s_waitcnt vmcnt(16)
; __device__ void phase_gather(const Params& p) {
;     ...
;         for (int sub = 0; sub < GROWS / 4; ++sub) {
;           const int W4 = __builtin_amdgcn_readlane(pkv, j0 + 4 * sub);
; #pragma unroll
;           for (int m = 0; m < 4; ++m) {
;             unsigned lo[4], hi[4];
; #pragma unroll
;             for (int k = 0; k < 4; ++k) {
;               const unsigned w = rr[gi % 3][sub * 4 + k][m];
;               lo[k] = w & 0x0f0f0f0fu;
;               hi[k] = (w >> 4) & 0x0f0f0f0fu;
;             }
;             {
;               const unsigned p01l = __builtin_amdgcn_perm(lo[1], lo[0], 0x05010400u), p01h = __builtin_amdgcn_perm(lo[1], lo[0], 0x07030602u);
;               const unsigned p23l = __builtin_amdgcn_perm(lo[3], lo[2], 0x05010400u), p23h = __builtin_amdgcn_perm(lo[3], lo[2], 0x07030602u);
;               acc[m * 8 + 0] = __builtin_amdgcn_sdot4((int)__builtin_amdgcn_perm(p23l, p01l, 0x05040100u), W4, acc[m * 8 + 0], false);
;               acc[m * 8 + 1] = __builtin_amdgcn_sdot4((int)__builtin_amdgcn_perm(p23l, p01l, 0x07060302u), W4, acc[m * 8 + 1], false);
;               acc[m * 8 + 2] = __builtin_amdgcn_sdot4((int)__builtin_amdgcn_perm(p23h, p01h, 0x05040100u), W4, acc[m * 8 + 2], false);
;               acc[m * 8 + 3] = __builtin_amdgcn_sdot4((int)__builtin_amdgcn_perm(p23h, p01h, 0x07060302u), W4, acc[m * 8 + 3], false);
;             }
;             {
;               const unsigned p01l = __builtin_amdgcn_perm(hi[1], hi[0], 0x05010400u), p01h = __builtin_amdgcn_perm(hi[1], hi[0], 0x07030602u);
;               const unsigned p23l = __builtin_amdgcn_perm(hi[3], hi[2], 0x05010400u), p23h = __builtin_amdgcn_perm(hi[3], hi[2], 0x07030602u);
;               acc[m * 8 + 4] = __builtin_amdgcn_sdot4((int)__builtin_amdgcn_perm(p23l, p01l, 0x05040100u), W4, acc[m * 8 + 4], false);
;               acc[m * 8 + 5] = __builtin_amdgcn_sdot4((int)__builtin_amdgcn_perm(p23l, p01l, 0x07060302u), W4, acc[m * 8 + 5], false);
;               acc[m * 8 + 6] = __builtin_amdgcn_sdot4((int)__builtin_amdgcn_perm(p23h, p01h, 0x05040100u), W4, acc[m * 8 + 6], false);
;               acc[m * 8 + 7] = __builtin_amdgcn_sdot4((int)__builtin_amdgcn_perm(p23h, p01h, 0x07060302u), W4, acc[m * 8 + 7], false);
;             }
;           }
	v_and_b32_e32 v16, 0xf0f0f0f, v12
	v_dot4c_i32_i8_e32 v134, s0, v20
	v_dot4c_i32_i8_e32 v163, s0, v83
	v_dot4c_i32_i8_e32 v161, s0, v81
	v_dot4c_i32_i8_e32 v136, s0, v23
	v_readlane_b32 s0, v170, 20
	v_lshrrev_b32_e32 v12, 4, v12
	v_and_b32_e32 v12, 0xf0f0f0f, v12
	v_and_b32_e32 v80, 0xf0f0f0f, v72
	s_waitcnt vmcnt(13)
	v_and_b32_e32 v81, 0xf0f0f0f, v76
	s_waitcnt vmcnt(11)
	v_and_b32_e32 v82, 0xf0f0f0f, v68
	v_perm_b32 v84, v81, v80, s33
	v_perm_b32 v80, v81, v80, s52
	v_lshrrev_b32_e32 v72, 4, v72
	v_lshrrev_b32_e32 v76, 4, v76
	v_lshrrev_b32_e32 v68, 4, v68
	v_and_b32_e32 v72, 0xf0f0f0f, v72
	v_and_b32_e32 v76, 0xf0f0f0f, v76
	v_and_b32_e32 v68, 0xf0f0f0f, v68
	v_readlane_b32 s2, v170, 48
	v_readlane_b32 s3, v170, 52
	s_waitcnt vmcnt(8)
	v_and_b32_e32 v17, 0xf0f0f0f, v8
	v_perm_b32 v20, v17, v16, s33
	v_perm_b32 v16, v17, v16, s52
	v_lshrrev_b32_e32 v8, 4, v8
	s_waitcnt vmcnt(6)
	v_and_b32_e32 v18, 0xf0f0f0f, v4
	v_lshrrev_b32_e32 v4, 4, v4
	s_waitcnt vmcnt(5)
	v_and_b32_e32 v19, 0xf0f0f0f, v0
	v_perm_b32 v17, v19, v18, s33
	v_lshrrev_b32_e32 v0, 4, v0
	v_perm_b32 v18, v19, v18, s52
	v_perm_b32 v19, v17, v20, s53
	v_perm_b32 v17, v17, v20, s54
	v_and_b32_e32 v8, 0xf0f0f0f, v8
	v_and_b32_e32 v4, 0xf0f0f0f, v4
	v_and_b32_e32 v0, 0xf0f0f0f, v0
	v_dot4c_i32_i8_e32 v164, s0, v17
	v_perm_b32 v17, v18, v16, s53
	v_perm_b32 v16, v18, v16, s54
	v_dot4c_i32_i8_e32 v162, s0, v16
	v_perm_b32 v16, v8, v12, s33
	v_perm_b32 v8, v8, v12, s52
	v_perm_b32 v12, v0, v4, s33
	v_perm_b32 v0, v0, v4, s52
	v_perm_b32 v4, v12, v16, s53
	v_dot4c_i32_i8_e32 v159, s0, v4
	v_perm_b32 v4, v12, v16, s54
	v_dot4c_i32_i8_e32 v160, s0, v4
	v_perm_b32 v4, v0, v8, s53
	v_perm_b32 v0, v0, v8, s54
	v_dot4c_i32_i8_e32 v157, s0, v4
	v_dot4c_i32_i8_e32 v158, s0, v0
	v_and_b32_e32 v0, 0xf0f0f0f, v13
	v_lshrrev_b32_e32 v4, 4, v13
	v_and_b32_e32 v8, 0xf0f0f0f, v9
	v_and_b32_e32 v12, 0xf0f0f0f, v5
	v_and_b32_e32 v13, 0xf0f0f0f, v1
	v_perm_b32 v16, v8, v0, s33
	v_perm_b32 v0, v8, v0, s52
	v_perm_b32 v8, v13, v12, s33
	v_lshrrev_b32_e32 v9, 4, v9
	v_lshrrev_b32_e32 v5, 4, v5
	v_lshrrev_b32_e32 v1, 4, v1
	v_perm_b32 v12, v13, v12, s52
	v_perm_b32 v13, v8, v16, s53
	v_perm_b32 v8, v8, v16, s54
	v_and_b32_e32 v4, 0xf0f0f0f, v4
	v_and_b32_e32 v9, 0xf0f0f0f, v9
	v_and_b32_e32 v5, 0xf0f0f0f, v5
	v_and_b32_e32 v1, 0xf0f0f0f, v1
	v_dot4c_i32_i8_e32 v154, s0, v8
	v_perm_b32 v8, v12, v0, s53
	v_perm_b32 v0, v12, v0, s54
	v_dot4c_i32_i8_e32 v149, s0, v8
	v_dot4c_i32_i8_e32 v150, s0, v0
	v_perm_b32 v0, v9, v4, s33
	v_perm_b32 v8, v1, v5, s33
	v_perm_b32 v4, v9, v4, s52
	v_perm_b32 v1, v1, v5, s52
	v_perm_b32 v5, v8, v0, s53
	v_perm_b32 v0, v8, v0, s54
	v_dot4c_i32_i8_e32 v146, s0, v0
	v_perm_b32 v0, v1, v4, s53
	v_dot4c_i32_i8_e32 v155, s0, v0
	v_perm_b32 v0, v1, v4, s54
	v_dot4c_i32_i8_e32 v156, s0, v0
	v_and_b32_e32 v0, 0xf0f0f0f, v14
	v_and_b32_e32 v4, 0xf0f0f0f, v10
	v_and_b32_e32 v8, 0xf0f0f0f, v6
	v_and_b32_e32 v9, 0xf0f0f0f, v2
	v_dot4c_i32_i8_e32 v144, s0, v5
	v_lshrrev_b32_e32 v5, 4, v10
	v_perm_b32 v10, v4, v0, s33
	v_perm_b32 v0, v4, v0, s52
	v_perm_b32 v4, v9, v8, s33
	v_lshrrev_b32_e32 v1, 4, v14
	v_lshrrev_b32_e32 v6, 4, v6
	v_lshrrev_b32_e32 v2, 4, v2
	v_perm_b32 v8, v9, v8, s52
	v_perm_b32 v9, v4, v10, s53
	v_perm_b32 v4, v4, v10, s54
	v_and_b32_e32 v1, 0xf0f0f0f, v1
	v_and_b32_e32 v5, 0xf0f0f0f, v5
	v_and_b32_e32 v6, 0xf0f0f0f, v6
	v_and_b32_e32 v2, 0xf0f0f0f, v2
	v_dot4c_i32_i8_e32 v153, s0, v4
	v_perm_b32 v4, v8, v0, s53
	v_perm_b32 v0, v8, v0, s54
	v_dot4c_i32_i8_e32 v147, s0, v4
	v_dot4c_i32_i8_e32 v148, s0, v0
	v_perm_b32 v0, v5, v1, s33
	v_perm_b32 v4, v2, v6, s33
	v_perm_b32 v1, v5, v1, s52
	v_perm_b32 v2, v2, v6, s52
	v_perm_b32 v5, v4, v0, s53
	v_perm_b32 v0, v4, v0, s54
	v_dot4c_i32_i8_e32 v145, s0, v0
	v_perm_b32 v0, v2, v1, s53
	v_dot4c_i32_i8_e32 v141, s0, v0
	v_perm_b32 v0, v2, v1, s54
	v_dot4c_i32_i8_e32 v143, s0, v5
	v_dot4c_i32_i8_e32 v142, s0, v0
	v_and_b32_e32 v0, 0xf0f0f0f, v15
	v_and_b32_e32 v2, 0xf0f0f0f, v11
	v_and_b32_e32 v5, 0xf0f0f0f, v7
	v_lshrrev_b32_e32 v6, 4, v7
	v_and_b32_e32 v7, 0xf0f0f0f, v3
	v_perm_b32 v8, v2, v0, s33
	v_perm_b32 v0, v2, v0, s52
	v_perm_b32 v2, v7, v5, s33
	v_lshrrev_b32_e32 v1, 4, v15
	v_lshrrev_b32_e32 v4, 4, v11
	v_lshrrev_b32_e32 v3, 4, v3
	v_perm_b32 v5, v7, v5, s52
	v_perm_b32 v7, v2, v8, s53
	v_perm_b32 v2, v2, v8, s54
	v_and_b32_e32 v1, 0xf0f0f0f, v1
	v_and_b32_e32 v4, 0xf0f0f0f, v4
	v_and_b32_e32 v6, 0xf0f0f0f, v6
	v_and_b32_e32 v3, 0xf0f0f0f, v3
	v_dot4c_i32_i8_e32 v140, s0, v2
	v_perm_b32 v2, v5, v0, s53
	v_perm_b32 v0, v5, v0, s54
	v_dot4c_i32_i8_e32 v137, s0, v2
	v_dot4c_i32_i8_e32 v139, s0, v0
	v_perm_b32 v0, v4, v1, s33
	v_perm_b32 v2, v3, v6, s33
	v_perm_b32 v1, v4, v1, s52
	v_perm_b32 v3, v3, v6, s52
	v_perm_b32 v4, v2, v0, s53
	v_perm_b32 v0, v2, v0, s54
	v_dot4c_i32_i8_e32 v135, s0, v0
	v_perm_b32 v0, v3, v1, s53
	v_dot4c_i32_i8_e32 v123, s0, v0
	v_perm_b32 v0, v3, v1, s54
	v_dot4c_i32_i8_e32 v163, s0, v19
	v_dot4c_i32_i8_e32 v161, s0, v17
	v_dot4c_i32_i8_e32 v152, s0, v13
	v_dot4c_i32_i8_e32 v151, s0, v9
	v_dot4c_i32_i8_e32 v136, s0, v7
	v_dot4c_i32_i8_e32 v134, s0, v4
	v_dot4c_i32_i8_e32 v125, s0, v0
	v_readlane_b32 s0, v250, 34
	v_readlane_b32 s1, v250, 35
	s_waitcnt vmcnt(4)
; __device__ void phase_gather(const Params& p) {
;     ...
;         for (int sub = 0; sub < GROWS / 4; ++sub) {
;           const int W4 = __builtin_amdgcn_readlane(pkv, j0 + 4 * sub);
; #pragma unroll
;           for (int m = 0; m < 4; ++m) {
;             unsigned lo[4], hi[4];
; #pragma unroll
;             for (int k = 0; k < 4; ++k) {
;               const unsigned w = rr[gi % 3][sub * 4 + k][m];
;               lo[k] = w & 0x0f0f0f0fu;
;               hi[k] = (w >> 4) & 0x0f0f0f0fu;
;             }
;             {
;               const unsigned p01l = __builtin_amdgcn_perm(lo[1], lo[0], 0x05010400u), p01h = __builtin_amdgcn_perm(lo[1], lo[0], 0x07030602u);
;               const unsigned p23l = __builtin_amdgcn_perm(lo[3], lo[2], 0x05010400u), p23h = __builtin_amdgcn_perm(lo[3], lo[2], 0x07030602u);
;               acc[m * 8 + 0] = __builtin_amdgcn_sdot4((int)__builtin_amdgcn_perm(p23l, p01l, 0x05040100u), W4, acc[m * 8 + 0], false);
;               acc[m * 8 + 1] = __builtin_amdgcn_sdot4((int)__builtin_amdgcn_perm(p23l, p01l, 0x07060302u), W4, acc[m * 8 + 1], false);
;               acc[m * 8 + 2] = __builtin_amdgcn_sdot4((int)__builtin_amdgcn_perm(p23h, p01h, 0x05040100u), W4, acc[m * 8 + 2], false);
;               acc[m * 8 + 3] = __builtin_amdgcn_sdot4((int)__builtin_amdgcn_perm(p23h, p01h, 0x07060302u), W4, acc[m * 8 + 3], false);
;             }
;             {
;               const unsigned p01l = __builtin_amdgcn_perm(hi[1], hi[0], 0x05010400u), p01h = __builtin_amdgcn_perm(hi[1], hi[0], 0x07030602u);
;               const unsigned p23l = __builtin_amdgcn_perm(hi[3], hi[2], 0x05010400u), p23h = __builtin_amdgcn_perm(hi[3], hi[2], 0x07030602u);
;               acc[m * 8 + 4] = __builtin_amdgcn_sdot4((int)__builtin_amdgcn_perm(p23l, p01l, 0x05040100u), W4, acc[m * 8 + 4], false);
;               acc[m * 8 + 5] = __builtin_amdgcn_sdot4((int)__builtin_amdgcn_perm(p23l, p01l, 0x07060302u), W4, acc[m * 8 + 5], false);
;               acc[m * 8 + 6] = __builtin_amdgcn_sdot4((int)__builtin_amdgcn_perm(p23h, p01h, 0x05040100u), W4, acc[m * 8 + 6], false);
;               acc[m * 8 + 7] = __builtin_amdgcn_sdot4((int)__builtin_amdgcn_perm(p23h, p01h, 0x07060302u), W4, acc[m * 8 + 7], false);
;             }
;           }
	v_and_b32_e32 v83, 0xf0f0f0f, v64
	v_perm_b32 v81, v83, v82, s33
	v_lshl_add_u64 v[0:1], v[116:117], 0, s[0:1]
	v_readlane_b32 s0, v250, 36
	v_readlane_b32 s1, v250, 37
	v_lshrrev_b32_e32 v64, 4, v64
	v_perm_b32 v82, v83, v82, s52
	v_lshl_add_u64 v[4:5], v[116:117], 0, s[0:1]
	v_readlane_b32 s0, v250, 38
	v_readlane_b32 s1, v250, 39
	v_perm_b32 v83, v81, v84, s53
	v_perm_b32 v81, v81, v84, s54
	v_lshl_add_u64 v[8:9], v[116:117], 0, s[0:1]
	v_readlane_b32 s0, v170, 24
	v_and_b32_e32 v64, 0xf0f0f0f, v64
	v_lshl_add_u64 v[12:13], v[116:117], 0, s[56:57]
	v_dot4c_i32_i8_e32 v164, s0, v81
	v_perm_b32 v81, v82, v80, s53
	v_perm_b32 v80, v82, v80, s54
	v_dot4c_i32_i8_e32 v162, s0, v80
	v_perm_b32 v80, v76, v72, s33
	v_perm_b32 v72, v76, v72, s52
	v_perm_b32 v76, v64, v68, s33
	v_perm_b32 v64, v64, v68, s52
	v_perm_b32 v68, v76, v80, s53
	v_dot4c_i32_i8_e32 v159, s0, v68
	v_perm_b32 v68, v76, v80, s54
	v_dot4c_i32_i8_e32 v160, s0, v68
	v_perm_b32 v68, v64, v72, s53
	v_perm_b32 v64, v64, v72, s54
	v_dot4c_i32_i8_e32 v157, s0, v68
	v_dot4c_i32_i8_e32 v158, s0, v64
	v_and_b32_e32 v64, 0xf0f0f0f, v73
	v_lshrrev_b32_e32 v68, 4, v73
	v_and_b32_e32 v72, 0xf0f0f0f, v77
	v_lshrrev_b32_e32 v73, 4, v77
	v_and_b32_e32 v76, 0xf0f0f0f, v69
	v_and_b32_e32 v77, 0xf0f0f0f, v65
	v_perm_b32 v80, v72, v64, s33
	v_perm_b32 v64, v72, v64, s52
	v_perm_b32 v72, v77, v76, s33
	v_lshrrev_b32_e32 v69, 4, v69
	v_lshrrev_b32_e32 v65, 4, v65
	v_perm_b32 v76, v77, v76, s52
	v_perm_b32 v77, v72, v80, s53
	v_perm_b32 v72, v72, v80, s54
	v_and_b32_e32 v68, 0xf0f0f0f, v68
	v_and_b32_e32 v73, 0xf0f0f0f, v73
	v_and_b32_e32 v69, 0xf0f0f0f, v69
	v_and_b32_e32 v65, 0xf0f0f0f, v65
	v_dot4c_i32_i8_e32 v154, s0, v72
	v_perm_b32 v72, v76, v64, s53
	v_perm_b32 v64, v76, v64, s54
	v_dot4c_i32_i8_e32 v149, s0, v72
	v_dot4c_i32_i8_e32 v150, s0, v64
	v_perm_b32 v64, v73, v68, s33
	v_perm_b32 v72, v65, v69, s33
	v_perm_b32 v68, v73, v68, s52
	v_perm_b32 v65, v65, v69, s52
	v_perm_b32 v69, v72, v64, s53
	v_perm_b32 v64, v72, v64, s54
	v_dot4c_i32_i8_e32 v146, s0, v64
	v_perm_b32 v64, v65, v68, s53
	v_dot4c_i32_i8_e32 v155, s0, v64
	v_perm_b32 v64, v65, v68, s54
	v_dot4c_i32_i8_e32 v156, s0, v64
	v_and_b32_e32 v64, 0xf0f0f0f, v74
	v_and_b32_e32 v68, 0xf0f0f0f, v78
	v_and_b32_e32 v72, 0xf0f0f0f, v70
	v_and_b32_e32 v73, 0xf0f0f0f, v66
	v_lshrrev_b32_e32 v65, 4, v74
	v_perm_b32 v74, v68, v64, s33
	v_perm_b32 v64, v68, v64, s52
	v_perm_b32 v68, v73, v72, s33
	v_dot4c_i32_i8_e32 v144, s0, v69
	v_lshrrev_b32_e32 v69, 4, v78
	v_lshrrev_b32_e32 v70, 4, v70
	v_lshrrev_b32_e32 v66, 4, v66
	v_perm_b32 v72, v73, v72, s52
	v_perm_b32 v73, v68, v74, s53
	v_perm_b32 v68, v68, v74, s54
	v_and_b32_e32 v65, 0xf0f0f0f, v65
	v_and_b32_e32 v69, 0xf0f0f0f, v69
	v_and_b32_e32 v70, 0xf0f0f0f, v70
	v_and_b32_e32 v66, 0xf0f0f0f, v66
	v_dot4c_i32_i8_e32 v153, s0, v68
	v_perm_b32 v68, v72, v64, s53
	v_perm_b32 v64, v72, v64, s54
	v_dot4c_i32_i8_e32 v147, s0, v68
	v_dot4c_i32_i8_e32 v148, s0, v64
	v_perm_b32 v64, v69, v65, s33
	v_perm_b32 v68, v66, v70, s33
	v_perm_b32 v65, v69, v65, s52
	v_perm_b32 v66, v66, v70, s52
	v_perm_b32 v69, v68, v64, s53
	v_perm_b32 v64, v68, v64, s54
	v_dot4c_i32_i8_e32 v145, s0, v64
	v_perm_b32 v64, v66, v65, s53
	v_dot4c_i32_i8_e32 v141, s0, v64
	v_perm_b32 v64, v66, v65, s54
	v_dot4c_i32_i8_e32 v143, s0, v69
	v_dot4c_i32_i8_e32 v142, s0, v64
	v_and_b32_e32 v64, 0xf0f0f0f, v75
	v_and_b32_e32 v66, 0xf0f0f0f, v79
	v_and_b32_e32 v69, 0xf0f0f0f, v71
	v_lshrrev_b32_e32 v70, 4, v71
	v_and_b32_e32 v71, 0xf0f0f0f, v67
	v_perm_b32 v72, v66, v64, s33
	v_perm_b32 v64, v66, v64, s52
	v_perm_b32 v66, v71, v69, s33
	v_lshrrev_b32_e32 v65, 4, v75
	v_lshrrev_b32_e32 v68, 4, v79
	v_lshrrev_b32_e32 v67, 4, v67
	v_perm_b32 v69, v71, v69, s52
	v_perm_b32 v71, v66, v72, s53
	v_perm_b32 v66, v66, v72, s54
	v_and_b32_e32 v65, 0xf0f0f0f, v65
	v_and_b32_e32 v68, 0xf0f0f0f, v68
	v_and_b32_e32 v70, 0xf0f0f0f, v70
	v_and_b32_e32 v67, 0xf0f0f0f, v67
	v_dot4c_i32_i8_e32 v140, s0, v66
	v_perm_b32 v66, v69, v64, s53
	v_perm_b32 v64, v69, v64, s54
	v_dot4c_i32_i8_e32 v137, s0, v66
	v_dot4c_i32_i8_e32 v139, s0, v64
	v_perm_b32 v64, v68, v65, s33
	v_perm_b32 v66, v67, v70, s33
	v_perm_b32 v65, v68, v65, s52
	v_perm_b32 v67, v67, v70, s52
	v_perm_b32 v68, v66, v64, s53
	v_perm_b32 v64, v66, v64, s54
	v_dot4c_i32_i8_e32 v135, s0, v64
	v_perm_b32 v64, v67, v65, s53
	v_dot4c_i32_i8_e32 v123, s0, v64
	v_perm_b32 v64, v67, v65, s54
	v_dot4c_i32_i8_e32 v125, s0, v64
	s_waitcnt vmcnt(3)
	v_and_b32_e32 v64, 0xf0f0f0f, v60
	s_waitcnt vmcnt(2)
	v_and_b32_e32 v65, 0xf0f0f0f, v56
	s_waitcnt vmcnt(1)
	v_and_b32_e32 v66, 0xf0f0f0f, v52
	s_waitcnt vmcnt(0)
; __device__ void phase_gather(const Params& p) {
;     ...
;         for (int sub = 0; sub < GROWS / 4; ++sub) {
;           const int W4 = __builtin_amdgcn_readlane(pkv, j0 + 4 * sub);
; #pragma unroll
;           for (int m = 0; m < 4; ++m) {
;             unsigned lo[4], hi[4];
; #pragma unroll
;             for (int k = 0; k < 4; ++k) {
;               const unsigned w = rr[gi % 3][sub * 4 + k][m];
;               lo[k] = w & 0x0f0f0f0fu;
;               hi[k] = (w >> 4) & 0x0f0f0f0fu;
;             }
;             {
;               const unsigned p01l = __builtin_amdgcn_perm(lo[1], lo[0], 0x05010400u), p01h = __builtin_amdgcn_perm(lo[1], lo[0], 0x07030602u);
;               const unsigned p23l = __builtin_amdgcn_perm(lo[3], lo[2], 0x05010400u), p23h = __builtin_amdgcn_perm(lo[3], lo[2], 0x07030602u);
;               acc[m * 8 + 0] = __builtin_amdgcn_sdot4((int)__builtin_amdgcn_perm(p23l, p01l, 0x05040100u), W4, acc[m * 8 + 0], false);
;               acc[m * 8 + 1] = __builtin_amdgcn_sdot4((int)__builtin_amdgcn_perm(p23l, p01l, 0x07060302u), W4, acc[m * 8 + 1], false);
;               acc[m * 8 + 2] = __builtin_amdgcn_sdot4((int)__builtin_amdgcn_perm(p23h, p01h, 0x05040100u), W4, acc[m * 8 + 2], false);
;               acc[m * 8 + 3] = __builtin_amdgcn_sdot4((int)__builtin_amdgcn_perm(p23h, p01h, 0x07060302u), W4, acc[m * 8 + 3], false);
;             }
;             {
;               const unsigned p01l = __builtin_amdgcn_perm(hi[1], hi[0], 0x05010400u), p01h = __builtin_amdgcn_perm(hi[1], hi[0], 0x07030602u);
;               const unsigned p23l = __builtin_amdgcn_perm(hi[3], hi[2], 0x05010400u), p23h = __builtin_amdgcn_perm(hi[3], hi[2], 0x07030602u);
;               acc[m * 8 + 4] = __builtin_amdgcn_sdot4((int)__builtin_amdgcn_perm(p23l, p01l, 0x05040100u), W4, acc[m * 8 + 4], false);
;               acc[m * 8 + 5] = __builtin_amdgcn_sdot4((int)__builtin_amdgcn_perm(p23l, p01l, 0x07060302u), W4, acc[m * 8 + 5], false);
;               acc[m * 8 + 6] = __builtin_amdgcn_sdot4((int)__builtin_amdgcn_perm(p23h, p01h, 0x05040100u), W4, acc[m * 8 + 6], false);
;               acc[m * 8 + 7] = __builtin_amdgcn_sdot4((int)__builtin_amdgcn_perm(p23h, p01h, 0x07060302u), W4, acc[m * 8 + 7], false);
;             }
;           }
;     ...
;     for (int q = 0; q < 8; ++q) {
;       f32x4 v = *(const f32x4*)(orow + q * 4);
	v_lshlrev_b64 v[246:247], 13, v[112:113]
	v_lshl_add_u64 v[246:247], v[118:119], 0, v[246:247]
	global_load_dwordx4 v[228:231], v[246:247], off
	global_load_dwordx4 v[232:235], v[246:247], off offset:16
	global_load_dwordx4 v[236:239], v[246:247], off offset:32
	global_load_dwordx4 v[240:243], v[246:247], off offset:48
	global_load_dwordx4 v[184:187], v[246:247], off offset:80
	global_load_dwordx4 v[244:247], v[246:247], off offset:64
	v_and_b32_e32 v67, 0xf0f0f0f, v48
	v_dot4c_i32_i8_e32 v134, s0, v68
	v_perm_b32 v68, v65, v64, s33
	v_perm_b32 v64, v65, v64, s52
	v_perm_b32 v65, v67, v66, s33
	v_dot4c_i32_i8_e32 v163, s0, v83
	v_dot4c_i32_i8_e32 v161, s0, v81
	v_dot4c_i32_i8_e32 v152, s0, v77
	v_dot4c_i32_i8_e32 v151, s0, v73
	v_dot4c_i32_i8_e32 v136, s0, v71
	v_readlane_b32 s0, v170, 28
	v_lshrrev_b32_e32 v60, 4, v60
	v_lshrrev_b32_e32 v56, 4, v56
	v_lshrrev_b32_e32 v52, 4, v52
	v_lshrrev_b32_e32 v48, 4, v48
	v_perm_b32 v66, v67, v66, s52
	v_perm_b32 v67, v65, v68, s53
	v_perm_b32 v65, v65, v68, s54
	v_and_b32_e32 v60, 0xf0f0f0f, v60
	v_and_b32_e32 v56, 0xf0f0f0f, v56
	v_and_b32_e32 v52, 0xf0f0f0f, v52
	v_and_b32_e32 v48, 0xf0f0f0f, v48
	v_dot4c_i32_i8_e32 v164, s0, v65
	v_perm_b32 v65, v66, v64, s53
	v_perm_b32 v64, v66, v64, s54
	v_dot4c_i32_i8_e32 v162, s0, v64
	v_perm_b32 v64, v56, v60, s33
	v_perm_b32 v56, v56, v60, s52
	v_perm_b32 v60, v48, v52, s33
	v_perm_b32 v48, v48, v52, s52
	v_perm_b32 v52, v60, v64, s53
	v_dot4c_i32_i8_e32 v159, s0, v52
	v_perm_b32 v52, v60, v64, s54
	v_dot4c_i32_i8_e32 v160, s0, v52
	v_perm_b32 v52, v48, v56, s53
	v_perm_b32 v48, v48, v56, s54
	v_dot4c_i32_i8_e32 v157, s0, v52
	v_dot4c_i32_i8_e32 v158, s0, v48
	v_and_b32_e32 v48, 0xf0f0f0f, v61
	v_lshrrev_b32_e32 v52, 4, v61
	v_and_b32_e32 v56, 0xf0f0f0f, v57
	v_and_b32_e32 v60, 0xf0f0f0f, v53
	v_and_b32_e32 v61, 0xf0f0f0f, v49
	v_perm_b32 v64, v56, v48, s33
	v_perm_b32 v48, v56, v48, s52
	v_perm_b32 v56, v61, v60, s33
	v_lshrrev_b32_e32 v57, 4, v57
	v_lshrrev_b32_e32 v53, 4, v53
	v_lshrrev_b32_e32 v49, 4, v49
	v_perm_b32 v60, v61, v60, s52
	v_perm_b32 v61, v56, v64, s53
	v_perm_b32 v56, v56, v64, s54
	v_and_b32_e32 v52, 0xf0f0f0f, v52
	v_and_b32_e32 v57, 0xf0f0f0f, v57
	v_and_b32_e32 v53, 0xf0f0f0f, v53
	v_and_b32_e32 v49, 0xf0f0f0f, v49
	v_dot4c_i32_i8_e32 v154, s0, v56
	v_perm_b32 v56, v60, v48, s53
	v_perm_b32 v48, v60, v48, s54
	v_dot4c_i32_i8_e32 v149, s0, v56
	v_dot4c_i32_i8_e32 v150, s0, v48
	v_perm_b32 v48, v57, v52, s33
	v_perm_b32 v56, v49, v53, s33
	v_perm_b32 v52, v57, v52, s52
	v_perm_b32 v49, v49, v53, s52
	v_perm_b32 v53, v56, v48, s53
	v_perm_b32 v48, v56, v48, s54
	v_dot4c_i32_i8_e32 v146, s0, v48
	v_perm_b32 v48, v49, v52, s53
	v_dot4c_i32_i8_e32 v155, s0, v48
	v_perm_b32 v48, v49, v52, s54
	v_dot4c_i32_i8_e32 v156, s0, v48
	v_and_b32_e32 v48, 0xf0f0f0f, v62
	v_and_b32_e32 v52, 0xf0f0f0f, v58
	v_and_b32_e32 v56, 0xf0f0f0f, v54
	v_and_b32_e32 v57, 0xf0f0f0f, v50
	v_dot4c_i32_i8_e32 v144, s0, v53
	v_lshrrev_b32_e32 v53, 4, v58
	v_perm_b32 v58, v52, v48, s33
	v_perm_b32 v48, v52, v48, s52
	v_perm_b32 v52, v57, v56, s33
	v_lshrrev_b32_e32 v49, 4, v62
	v_lshrrev_b32_e32 v54, 4, v54
	v_lshrrev_b32_e32 v50, 4, v50
	v_perm_b32 v56, v57, v56, s52
	v_perm_b32 v57, v52, v58, s53
	v_perm_b32 v52, v52, v58, s54
	v_and_b32_e32 v49, 0xf0f0f0f, v49
	v_and_b32_e32 v53, 0xf0f0f0f, v53
	v_and_b32_e32 v54, 0xf0f0f0f, v54
	v_and_b32_e32 v50, 0xf0f0f0f, v50
	v_dot4c_i32_i8_e32 v153, s0, v52
	v_perm_b32 v52, v56, v48, s53
	v_perm_b32 v48, v56, v48, s54
	v_dot4c_i32_i8_e32 v147, s0, v52
	v_dot4c_i32_i8_e32 v148, s0, v48
	v_perm_b32 v48, v53, v49, s33
	v_perm_b32 v52, v50, v54, s33
	v_perm_b32 v49, v53, v49, s52
	v_perm_b32 v50, v50, v54, s52
	v_perm_b32 v53, v52, v48, s53
	v_perm_b32 v48, v52, v48, s54
	v_dot4c_i32_i8_e32 v145, s0, v48
	v_perm_b32 v48, v50, v49, s53
	v_dot4c_i32_i8_e32 v141, s0, v48
	v_perm_b32 v48, v50, v49, s54
	v_dot4c_i32_i8_e32 v143, s0, v53
	v_dot4c_i32_i8_e32 v142, s0, v48
	v_and_b32_e32 v48, 0xf0f0f0f, v63
	v_and_b32_e32 v50, 0xf0f0f0f, v59
	v_and_b32_e32 v53, 0xf0f0f0f, v55
	v_lshrrev_b32_e32 v54, 4, v55
	v_and_b32_e32 v55, 0xf0f0f0f, v51
	v_perm_b32 v56, v50, v48, s33
	v_perm_b32 v48, v50, v48, s52
	v_perm_b32 v50, v55, v53, s33
	v_lshrrev_b32_e32 v49, 4, v63
	v_lshrrev_b32_e32 v52, 4, v59
	v_lshrrev_b32_e32 v51, 4, v51
	v_perm_b32 v53, v55, v53, s52
	v_perm_b32 v55, v50, v56, s53
	v_perm_b32 v50, v50, v56, s54
	v_and_b32_e32 v49, 0xf0f0f0f, v49
	v_and_b32_e32 v52, 0xf0f0f0f, v52
	v_and_b32_e32 v54, 0xf0f0f0f, v54
	v_and_b32_e32 v51, 0xf0f0f0f, v51
	v_dot4c_i32_i8_e32 v140, s0, v50
	v_perm_b32 v50, v53, v48, s53
	v_perm_b32 v48, v53, v48, s54
	v_dot4c_i32_i8_e32 v137, s0, v50
	v_dot4c_i32_i8_e32 v139, s0, v48
	v_perm_b32 v48, v52, v49, s33
	v_perm_b32 v50, v51, v54, s33
	v_perm_b32 v49, v52, v49, s52
	v_perm_b32 v51, v51, v54, s52
	v_perm_b32 v52, v50, v48, s53
	v_perm_b32 v48, v50, v48, s54
	v_dot4c_i32_i8_e32 v135, s0, v48
	v_perm_b32 v48, v51, v49, s53
	v_dot4c_i32_i8_e32 v123, s0, v48
	v_perm_b32 v48, v51, v49, s54
	v_dot4c_i32_i8_e32 v163, s0, v67
	v_dot4c_i32_i8_e32 v161, s0, v65
	v_dot4c_i32_i8_e32 v152, s0, v61
	v_dot4c_i32_i8_e32 v151, s0, v57
	v_dot4c_i32_i8_e32 v136, s0, v55
	v_dot4c_i32_i8_e32 v134, s0, v52
	v_dot4c_i32_i8_e32 v125, s0, v48
	v_readlane_b32 s0, v250, 40
	v_readlane_b32 s1, v250, 41
	global_load_dwordx4 v[0:3], v[0:1], off
	v_lshl_add_u64 v[16:17], v[116:117], 0, s[58:59]
	v_lshl_add_u64 v[48:49], v[116:117], 0, s[0:1]
	v_readlane_b32 s0, v250, 42
	v_readlane_b32 s1, v250, 43
	global_load_dwordx4 v[64:67], v[48:49], off
	v_lshl_add_u64 v[20:21], v[116:117], 0, s[60:61]
	v_lshl_add_u64 v[48:49], v[116:117], 0, s[0:1]
; __device__ void phase_gather(const Params& p) {
;     ...
; #pragma unroll
;           for (int k = 0; k < GROWS; ++k) {
;             const int e = __builtin_amdgcn_readlane(idv, j0 + 2 * GROWS + k);
;             rr[(gi + 2) % 3][k] = *(const u32x4*)(vb + (size_t)e * 1024 + lane * 16);
;           }
;         }
; #pragma unroll
;         for (int sub = 0; sub < GROWS / 4; ++sub) {
;           const int W4 = __builtin_amdgcn_readlane(pkv, j0 + 4 * sub);
; #pragma unroll
;           for (int m = 0; m < 4; ++m) {
;             unsigned lo[4], hi[4];
; #pragma unroll
;             for (int k = 0; k < 4; ++k) {
;               const unsigned w = rr[gi % 3][sub * 4 + k][m];
;               lo[k] = w & 0x0f0f0f0fu;
;               hi[k] = (w >> 4) & 0x0f0f0f0fu;
;             }
;             {
;               const unsigned p01l = __builtin_amdgcn_perm(lo[1], lo[0], 0x05010400u), p01h = __builtin_amdgcn_perm(lo[1], lo[0], 0x07030602u);
;               const unsigned p23l = __builtin_amdgcn_perm(lo[3], lo[2], 0x05010400u), p23h = __builtin_amdgcn_perm(lo[3], lo[2], 0x07030602u);
;               acc[m * 8 + 0] = __builtin_amdgcn_sdot4((int)__builtin_amdgcn_perm(p23l, p01l, 0x05040100u), W4, acc[m * 8 + 0], false);
;               acc[m * 8 + 1] = __builtin_amdgcn_sdot4((int)__builtin_amdgcn_perm(p23l, p01l, 0x07060302u), W4, acc[m * 8 + 1], false);
;               acc[m * 8 + 2] = __builtin_amdgcn_sdot4((int)__builtin_amdgcn_perm(p23h, p01h, 0x05040100u), W4, acc[m * 8 + 2], false);
;               acc[m * 8 + 3] = __builtin_amdgcn_sdot4((int)__builtin_amdgcn_perm(p23h, p01h, 0x07060302u), W4, acc[m * 8 + 3], false);
;             }
;             {
;               const unsigned p01l = __builtin_amdgcn_perm(hi[1], hi[0], 0x05010400u), p01h = __builtin_amdgcn_perm(hi[1], hi[0], 0x07030602u);
;               const unsigned p23l = __builtin_amdgcn_perm(hi[3], hi[2], 0x05010400u), p23h = __builtin_amdgcn_perm(hi[3], hi[2], 0x07030602u);
;               acc[m * 8 + 4] = __builtin_amdgcn_sdot4((int)__builtin_amdgcn_perm(p23l, p01l, 0x05040100u), W4, acc[m * 8 + 4], false);
;               acc[m * 8 + 5] = __builtin_amdgcn_sdot4((int)__builtin_amdgcn_perm(p23l, p01l, 0x07060302u), W4, acc[m * 8 + 5], false);
;               acc[m * 8 + 6] = __builtin_amdgcn_sdot4((int)__builtin_amdgcn_perm(p23h, p01h, 0x05040100u), W4, acc[m * 8 + 6], false);
	v_readlane_b32 s0, v250, 44
	v_readlane_b32 s1, v250, 45
	global_load_dwordx4 v[68:71], v[48:49], off
	v_and_b32_e32 v50, 0xf0f0f0f, v104
	v_lshl_add_u64 v[48:49], v[116:117], 0, s[0:1]
	v_readlane_b32 s0, v250, 46
	v_readlane_b32 s1, v250, 47
	global_load_dwordx4 v[72:75], v[48:49], off
	v_and_b32_e32 v52, 0xf0f0f0f, v100
	v_lshl_add_u64 v[48:49], v[116:117], 0, s[0:1]
	v_readlane_b32 s0, v250, 48
	v_readlane_b32 s1, v250, 49
	global_load_dwordx4 v[76:79], v[48:49], off
	v_and_b32_e32 v54, 0xf0f0f0f, v96
	v_lshl_add_u64 v[48:49], v[116:117], 0, s[0:1]
	v_readlane_b32 s0, v250, 50
	v_readlane_b32 s1, v250, 51
	global_load_dwordx4 v[80:83], v[48:49], off
	v_lshrrev_b32_e32 v51, 4, v104
	v_lshl_add_u64 v[48:49], v[116:117], 0, s[0:1]
	v_readlane_b32 s0, v250, 52
	v_readlane_b32 s1, v250, 53
	global_load_dwordx4 v[4:7], v[4:5], off
	v_lshrrev_b32_e32 v53, 4, v100
	global_load_dwordx4 v[8:11], v[8:9], off
	v_lshrrev_b32_e32 v55, 4, v96
	global_load_dwordx4 v[12:15], v[12:13], off
	v_and_b32_e32 v51, 0xf0f0f0f, v51
	global_load_dwordx4 v[84:87], v[48:49], off
	v_lshl_add_u64 v[48:49], v[116:117], 0, s[0:1]
	v_readlane_b32 s0, v250, 54
	global_load_dwordx4 v[16:19], v[16:17], off
	v_readlane_b32 s1, v250, 55
	global_load_dwordx4 v[20:23], v[20:21], off
	v_and_b32_e32 v53, 0xf0f0f0f, v53
	global_load_dwordx4 v[88:91], v[48:49], off
	v_lshl_add_u64 v[48:49], v[116:117], 0, s[0:1]
	global_load_dwordx4 v[92:95], v[48:49], off
	v_and_b32_e32 v48, 0xf0f0f0f, v108
	v_perm_b32 v56, v50, v48, s33
	v_perm_b32 v48, v50, v48, s52
	v_perm_b32 v50, v54, v52, s33
	v_readlane_b32 s0, v170, 32
	v_lshrrev_b32_e32 v49, 4, v108
	v_perm_b32 v52, v54, v52, s52
	v_perm_b32 v54, v50, v56, s53
	v_perm_b32 v50, v50, v56, s54
	v_and_b32_e32 v49, 0xf0f0f0f, v49
	v_and_b32_e32 v55, 0xf0f0f0f, v55
	v_dot4c_i32_i8_e32 v164, s0, v50
	v_perm_b32 v50, v52, v48, s53
	v_perm_b32 v48, v52, v48, s54
	v_dot4c_i32_i8_e32 v161, s0, v50
	v_dot4c_i32_i8_e32 v162, s0, v48
	v_perm_b32 v48, v51, v49, s33
	v_perm_b32 v50, v55, v53, s33
	v_perm_b32 v49, v51, v49, s52
	v_perm_b32 v51, v55, v53, s52
	v_perm_b32 v52, v50, v48, s53
	v_perm_b32 v48, v50, v48, s54
	v_dot4c_i32_i8_e32 v160, s0, v48
	v_perm_b32 v48, v51, v49, s53
	v_dot4c_i32_i8_e32 v157, s0, v48
	v_perm_b32 v48, v51, v49, s54
	v_dot4c_i32_i8_e32 v163, s0, v54
	v_dot4c_i32_i8_e32 v159, s0, v52
	v_dot4c_i32_i8_e32 v158, s0, v48
	v_and_b32_e32 v48, 0xf0f0f0f, v109
	v_and_b32_e32 v50, 0xf0f0f0f, v105
	v_and_b32_e32 v52, 0xf0f0f0f, v101
	v_and_b32_e32 v54, 0xf0f0f0f, v97
	v_perm_b32 v56, v50, v48, s33
	v_perm_b32 v48, v50, v48, s52
	v_perm_b32 v50, v54, v52, s33
	v_lshrrev_b32_e32 v49, 4, v109
	v_lshrrev_b32_e32 v51, 4, v105
	v_lshrrev_b32_e32 v53, 4, v101
	v_lshrrev_b32_e32 v55, 4, v97
	v_perm_b32 v52, v54, v52, s52
	v_perm_b32 v54, v50, v56, s53
	v_perm_b32 v50, v50, v56, s54
	v_and_b32_e32 v49, 0xf0f0f0f, v49
	v_and_b32_e32 v51, 0xf0f0f0f, v51
	v_and_b32_e32 v53, 0xf0f0f0f, v53
	v_and_b32_e32 v55, 0xf0f0f0f, v55
	v_dot4c_i32_i8_e32 v154, s0, v50
	v_perm_b32 v50, v52, v48, s53
	v_perm_b32 v48, v52, v48, s54
	v_dot4c_i32_i8_e32 v149, s0, v50
	v_dot4c_i32_i8_e32 v150, s0, v48
	v_perm_b32 v48, v51, v49, s33
	v_perm_b32 v50, v55, v53, s33
	v_perm_b32 v49, v51, v49, s52
	v_perm_b32 v51, v55, v53, s52
	v_perm_b32 v52, v50, v48, s53
	v_perm_b32 v48, v50, v48, s54
	v_dot4c_i32_i8_e32 v146, s0, v48
	v_perm_b32 v48, v51, v49, s53
	v_dot4c_i32_i8_e32 v155, s0, v48
	v_perm_b32 v48, v51, v49, s54
	v_dot4c_i32_i8_e32 v152, s0, v54
	v_dot4c_i32_i8_e32 v144, s0, v52
	v_dot4c_i32_i8_e32 v156, s0, v48
	v_and_b32_e32 v48, 0xf0f0f0f, v110
	v_and_b32_e32 v50, 0xf0f0f0f, v106
	v_and_b32_e32 v52, 0xf0f0f0f, v102
	v_and_b32_e32 v54, 0xf0f0f0f, v98
	v_perm_b32 v56, v50, v48, s33
	v_perm_b32 v48, v50, v48, s52
	v_perm_b32 v50, v54, v52, s33
	v_lshrrev_b32_e32 v49, 4, v110
	v_lshrrev_b32_e32 v51, 4, v106
	v_lshrrev_b32_e32 v53, 4, v102
	v_lshrrev_b32_e32 v55, 4, v98
	v_perm_b32 v52, v54, v52, s52
	v_perm_b32 v54, v50, v56, s53
	v_perm_b32 v50, v50, v56, s54
	v_and_b32_e32 v49, 0xf0f0f0f, v49
	v_and_b32_e32 v51, 0xf0f0f0f, v51
	v_and_b32_e32 v53, 0xf0f0f0f, v53
	v_and_b32_e32 v55, 0xf0f0f0f, v55
	v_dot4c_i32_i8_e32 v153, s0, v50
	v_perm_b32 v50, v52, v48, s53
	v_perm_b32 v48, v52, v48, s54
	v_dot4c_i32_i8_e32 v147, s0, v50
	v_dot4c_i32_i8_e32 v148, s0, v48
	v_perm_b32 v48, v51, v49, s33
	v_perm_b32 v50, v55, v53, s33
	v_perm_b32 v49, v51, v49, s52
	v_perm_b32 v51, v55, v53, s52
	v_perm_b32 v52, v50, v48, s53
	v_perm_b32 v48, v50, v48, s54
	v_dot4c_i32_i8_e32 v145, s0, v48
	v_perm_b32 v48, v51, v49, s53
	v_dot4c_i32_i8_e32 v141, s0, v48
	v_perm_b32 v48, v51, v49, s54
	v_dot4c_i32_i8_e32 v151, s0, v54
	v_dot4c_i32_i8_e32 v143, s0, v52
	v_dot4c_i32_i8_e32 v142, s0, v48
	v_and_b32_e32 v48, 0xf0f0f0f, v111
	v_and_b32_e32 v50, 0xf0f0f0f, v107
	v_and_b32_e32 v52, 0xf0f0f0f, v103
	v_and_b32_e32 v54, 0xf0f0f0f, v99
	v_perm_b32 v56, v50, v48, s33
	v_perm_b32 v48, v50, v48, s52
	v_perm_b32 v50, v54, v52, s33
	v_lshrrev_b32_e32 v49, 4, v111
	v_lshrrev_b32_e32 v51, 4, v107
	v_lshrrev_b32_e32 v53, 4, v103
	v_lshrrev_b32_e32 v55, 4, v99
	v_perm_b32 v52, v54, v52, s52
	v_perm_b32 v54, v50, v56, s53
	v_perm_b32 v50, v50, v56, s54
	v_and_b32_e32 v49, 0xf0f0f0f, v49
	v_and_b32_e32 v51, 0xf0f0f0f, v51
	v_and_b32_e32 v53, 0xf0f0f0f, v53
	v_and_b32_e32 v55, 0xf0f0f0f, v55
	v_dot4c_i32_i8_e32 v140, s0, v50
	v_perm_b32 v50, v52, v48, s53
	v_perm_b32 v48, v52, v48, s54
	v_dot4c_i32_i8_e32 v137, s0, v50
	v_dot4c_i32_i8_e32 v139, s0, v48
	v_perm_b32 v48, v51, v49, s33
	v_perm_b32 v50, v55, v53, s33
	v_perm_b32 v49, v51, v49, s52
	v_perm_b32 v51, v55, v53, s52
	v_perm_b32 v52, v50, v48, s53
; __device__ void phase_gather(const Params& p) {
;     ...
; #pragma unroll
;           for (int k = 0; k < GROWS; ++k) {
;             const int e = __builtin_amdgcn_readlane(idv, j0 + 2 * GROWS + k);
;             rr[(gi + 2) % 3][k] = *(const u32x4*)(vb + (size_t)e * 1024 + lane * 16);
;           }
;         }
; #pragma unroll
;         for (int sub = 0; sub < GROWS / 4; ++sub) {
;           const int W4 = __builtin_amdgcn_readlane(pkv, j0 + 4 * sub);
; #pragma unroll
;           for (int m = 0; m < 4; ++m) {
;             unsigned lo[4], hi[4];
; #pragma unroll
;             for (int k = 0; k < 4; ++k) {
;               const unsigned w = rr[gi % 3][sub * 4 + k][m];
;               lo[k] = w & 0x0f0f0f0fu;
;               hi[k] = (w >> 4) & 0x0f0f0f0fu;
;             }
;             {
;               const unsigned p01l = __builtin_amdgcn_perm(lo[1], lo[0], 0x05010400u), p01h = __builtin_amdgcn_perm(lo[1], lo[0], 0x07030602u);
;               const unsigned p23l = __builtin_amdgcn_perm(lo[3], lo[2], 0x05010400u), p23h = __builtin_amdgcn_perm(lo[3], lo[2], 0x07030602u);
;               acc[m * 8 + 0] = __builtin_amdgcn_sdot4((int)__builtin_amdgcn_perm(p23l, p01l, 0x05040100u), W4, acc[m * 8 + 0], false);
;               acc[m * 8 + 1] = __builtin_amdgcn_sdot4((int)__builtin_amdgcn_perm(p23l, p01l, 0x07060302u), W4, acc[m * 8 + 1], false);
;               acc[m * 8 + 2] = __builtin_amdgcn_sdot4((int)__builtin_amdgcn_perm(p23h, p01h, 0x05040100u), W4, acc[m * 8 + 2], false);
;               acc[m * 8 + 3] = __builtin_amdgcn_sdot4((int)__builtin_amdgcn_perm(p23h, p01h, 0x07060302u), W4, acc[m * 8 + 3], false);
;             }
;             {
;               const unsigned p01l = __builtin_amdgcn_perm(hi[1], hi[0], 0x05010400u), p01h = __builtin_amdgcn_perm(hi[1], hi[0], 0x07030602u);
;               const unsigned p23l = __builtin_amdgcn_perm(hi[3], hi[2], 0x05010400u), p23h = __builtin_amdgcn_perm(hi[3], hi[2], 0x07030602u);
;               acc[m * 8 + 4] = __builtin_amdgcn_sdot4((int)__builtin_amdgcn_perm(p23l, p01l, 0x05040100u), W4, acc[m * 8 + 4], false);
;               acc[m * 8 + 5] = __builtin_amdgcn_sdot4((int)__builtin_amdgcn_perm(p23l, p01l, 0x07060302u), W4, acc[m * 8 + 5], false);
;               acc[m * 8 + 6] = __builtin_amdgcn_sdot4((int)__builtin_amdgcn_perm(p23h, p01h, 0x05040100u), W4, acc[m * 8 + 6], false);
	v_perm_b32 v48, v50, v48, s54
	v_dot4c_i32_i8_e32 v135, s0, v48
	v_perm_b32 v48, v51, v49, s53
	v_dot4c_i32_i8_e32 v123, s0, v48
	v_perm_b32 v48, v51, v49, s54
	v_dot4c_i32_i8_e32 v125, s0, v48
	v_and_b32_e32 v48, 0xf0f0f0f, v44
	v_and_b32_e32 v49, 0xf0f0f0f, v40
	v_and_b32_e32 v50, 0xf0f0f0f, v36
	v_and_b32_e32 v51, 0xf0f0f0f, v32
	v_dot4c_i32_i8_e32 v134, s0, v52
	v_perm_b32 v52, v49, v48, s33
	v_perm_b32 v48, v49, v48, s52
	v_perm_b32 v49, v51, v50, s33
	v_dot4c_i32_i8_e32 v136, s0, v54
	v_readlane_b32 s0, v170, 36
	v_lshrrev_b32_e32 v44, 4, v44
	v_lshrrev_b32_e32 v40, 4, v40
	v_lshrrev_b32_e32 v36, 4, v36
	v_lshrrev_b32_e32 v32, 4, v32
	v_perm_b32 v50, v51, v50, s52
	v_perm_b32 v51, v49, v52, s53
	v_perm_b32 v49, v49, v52, s54
	v_and_b32_e32 v44, 0xf0f0f0f, v44
	v_and_b32_e32 v40, 0xf0f0f0f, v40
	v_and_b32_e32 v36, 0xf0f0f0f, v36
	v_and_b32_e32 v32, 0xf0f0f0f, v32
	v_dot4c_i32_i8_e32 v164, s0, v49
	v_perm_b32 v49, v50, v48, s53
	v_perm_b32 v48, v50, v48, s54
	v_dot4c_i32_i8_e32 v162, s0, v48
	v_perm_b32 v48, v40, v44, s33
	v_perm_b32 v40, v40, v44, s52
	v_perm_b32 v44, v32, v36, s33
	v_perm_b32 v32, v32, v36, s52
	v_perm_b32 v36, v44, v48, s53
	v_dot4c_i32_i8_e32 v159, s0, v36
	v_perm_b32 v36, v44, v48, s54
	v_dot4c_i32_i8_e32 v160, s0, v36
	v_perm_b32 v36, v32, v40, s53
	v_perm_b32 v32, v32, v40, s54
	v_dot4c_i32_i8_e32 v157, s0, v36
	v_dot4c_i32_i8_e32 v158, s0, v32
	v_and_b32_e32 v32, 0xf0f0f0f, v45
	v_lshrrev_b32_e32 v36, 4, v45
	v_and_b32_e32 v40, 0xf0f0f0f, v41
	v_and_b32_e32 v44, 0xf0f0f0f, v37
	v_and_b32_e32 v45, 0xf0f0f0f, v33
	v_perm_b32 v48, v40, v32, s33
	v_perm_b32 v32, v40, v32, s52
	v_perm_b32 v40, v45, v44, s33
	v_lshrrev_b32_e32 v41, 4, v41
	v_lshrrev_b32_e32 v37, 4, v37
	v_lshrrev_b32_e32 v33, 4, v33
	v_perm_b32 v44, v45, v44, s52
	v_perm_b32 v45, v40, v48, s53
	v_perm_b32 v40, v40, v48, s54
	v_and_b32_e32 v36, 0xf0f0f0f, v36
	v_and_b32_e32 v41, 0xf0f0f0f, v41
	v_and_b32_e32 v37, 0xf0f0f0f, v37
	v_and_b32_e32 v33, 0xf0f0f0f, v33
	v_dot4c_i32_i8_e32 v154, s0, v40
	v_perm_b32 v40, v44, v32, s53
	v_perm_b32 v32, v44, v32, s54
	v_dot4c_i32_i8_e32 v149, s0, v40
	v_dot4c_i32_i8_e32 v150, s0, v32
	v_perm_b32 v32, v41, v36, s33
	v_perm_b32 v40, v33, v37, s33
	v_perm_b32 v36, v41, v36, s52
	v_perm_b32 v33, v33, v37, s52
	v_perm_b32 v37, v40, v32, s53
	v_perm_b32 v32, v40, v32, s54
	v_dot4c_i32_i8_e32 v146, s0, v32
	v_perm_b32 v32, v33, v36, s53
	v_dot4c_i32_i8_e32 v155, s0, v32
	v_perm_b32 v32, v33, v36, s54
	v_dot4c_i32_i8_e32 v156, s0, v32
	v_and_b32_e32 v32, 0xf0f0f0f, v46
	v_and_b32_e32 v36, 0xf0f0f0f, v42
	v_and_b32_e32 v40, 0xf0f0f0f, v38
	v_and_b32_e32 v41, 0xf0f0f0f, v34
	v_dot4c_i32_i8_e32 v144, s0, v37
	v_lshrrev_b32_e32 v37, 4, v42
	v_perm_b32 v42, v36, v32, s33
	v_perm_b32 v32, v36, v32, s52
	v_perm_b32 v36, v41, v40, s33
	v_lshrrev_b32_e32 v33, 4, v46
	v_lshrrev_b32_e32 v38, 4, v38
	v_lshrrev_b32_e32 v34, 4, v34
	v_perm_b32 v40, v41, v40, s52
	v_perm_b32 v41, v36, v42, s53
	v_perm_b32 v36, v36, v42, s54
	v_and_b32_e32 v33, 0xf0f0f0f, v33
	v_and_b32_e32 v37, 0xf0f0f0f, v37
	v_and_b32_e32 v38, 0xf0f0f0f, v38
	v_and_b32_e32 v34, 0xf0f0f0f, v34
	v_dot4c_i32_i8_e32 v153, s0, v36
	v_perm_b32 v36, v40, v32, s53
	v_perm_b32 v32, v40, v32, s54
	v_dot4c_i32_i8_e32 v147, s0, v36
	v_dot4c_i32_i8_e32 v148, s0, v32
	v_perm_b32 v32, v37, v33, s33
	v_perm_b32 v36, v34, v38, s33
	v_perm_b32 v33, v37, v33, s52
	v_perm_b32 v34, v34, v38, s52
	v_perm_b32 v37, v36, v32, s53
	v_perm_b32 v32, v36, v32, s54
	v_dot4c_i32_i8_e32 v145, s0, v32
	v_perm_b32 v32, v34, v33, s53
	v_dot4c_i32_i8_e32 v141, s0, v32
	v_perm_b32 v32, v34, v33, s54
	v_dot4c_i32_i8_e32 v143, s0, v37
	v_dot4c_i32_i8_e32 v142, s0, v32
	v_and_b32_e32 v32, 0xf0f0f0f, v47
	v_and_b32_e32 v34, 0xf0f0f0f, v43
	v_and_b32_e32 v37, 0xf0f0f0f, v39
	v_lshrrev_b32_e32 v38, 4, v39
	v_and_b32_e32 v39, 0xf0f0f0f, v35
	v_perm_b32 v40, v34, v32, s33
	v_perm_b32 v32, v34, v32, s52
	v_perm_b32 v34, v39, v37, s33
	v_lshrrev_b32_e32 v33, 4, v47
	v_lshrrev_b32_e32 v36, 4, v43
	v_lshrrev_b32_e32 v35, 4, v35
	v_perm_b32 v37, v39, v37, s52
	v_perm_b32 v39, v34, v40, s53
	v_perm_b32 v34, v34, v40, s54
	v_and_b32_e32 v33, 0xf0f0f0f, v33
	v_and_b32_e32 v36, 0xf0f0f0f, v36
	v_and_b32_e32 v38, 0xf0f0f0f, v38
	v_and_b32_e32 v35, 0xf0f0f0f, v35
	v_dot4c_i32_i8_e32 v140, s0, v34
	v_perm_b32 v34, v37, v32, s53
	v_perm_b32 v32, v37, v32, s54
	v_dot4c_i32_i8_e32 v137, s0, v34
	v_dot4c_i32_i8_e32 v139, s0, v32
	v_perm_b32 v32, v36, v33, s33
	v_perm_b32 v34, v35, v38, s33
	v_perm_b32 v33, v36, v33, s52
	v_perm_b32 v35, v35, v38, s52
	v_perm_b32 v36, v34, v32, s53
	v_perm_b32 v32, v34, v32, s54
	v_dot4c_i32_i8_e32 v135, s0, v32
	v_perm_b32 v32, v35, v33, s53
	v_dot4c_i32_i8_e32 v123, s0, v32
	v_perm_b32 v32, v35, v33, s54
	v_dot4c_i32_i8_e32 v163, s0, v51
	v_dot4c_i32_i8_e32 v161, s0, v49
	v_dot4c_i32_i8_e32 v152, s0, v45
	v_dot4c_i32_i8_e32 v151, s0, v41
	v_dot4c_i32_i8_e32 v136, s0, v39
	v_dot4c_i32_i8_e32 v134, s0, v36
	v_dot4c_i32_i8_e32 v125, s0, v32
	v_readlane_b32 s0, v250, 6
	v_readlane_b32 s1, v250, 7
	s_waitcnt vmcnt(5)
	v_lshrrev_b32_e32 v176, 4, v15
	v_lshrrev_b32_e32 v177, 4, v11
	v_lshl_add_u64 v[32:33], v[116:117], 0, s[0:1]
	v_readlane_b32 s0, v250, 4
	v_readlane_b32 s1, v250, 5
	global_load_dwordx4 v[60:63], v[32:33], off
	v_lshrrev_b32_e32 v179, 4, v7
	v_lshl_add_u64 v[32:33], v[116:117], 0, s[0:1]
	v_readlane_b32 s0, v250, 14
	v_readlane_b32 s1, v250, 15
	global_load_dwordx4 v[56:59], v[32:33], off
	v_lshrrev_b32_e32 v180, 4, v3
	v_lshl_add_u64 v[32:33], v[116:117], 0, s[0:1]
	v_readlane_b32 s0, v250, 10
	v_readlane_b32 s1, v250, 11
	global_load_dwordx4 v[52:55], v[32:33], off
	v_lshrrev_b32_e32 v110, 4, v31
	v_lshl_add_u64 v[32:33], v[116:117], 0, s[0:1]
	v_readlane_b32 s0, v250, 12
	v_readlane_b32 s1, v250, 13
	global_load_dwordx4 v[48:51], v[32:33], off
	v_lshrrev_b32_e32 v111, 4, v27
	v_lshl_add_u64 v[32:33], v[116:117], 0, s[0:1]
	v_readlane_b32 s0, v250, 2
	v_readlane_b32 s1, v250, 3
	global_load_dwordx4 v[44:47], v[32:33], off
	s_waitcnt vmcnt(7)
; __device__ void phase_gather(const Params& p) {
;     ...
;         for (int sub = 0; sub < GROWS / 4; ++sub) {
;           const int W4 = __builtin_amdgcn_readlane(pkv, j0 + 4 * sub);
; #pragma unroll
;           for (int m = 0; m < 4; ++m) {
;             unsigned lo[4], hi[4];
; #pragma unroll
;             for (int k = 0; k < 4; ++k) {
;               const unsigned w = rr[gi % 3][sub * 4 + k][m];
;               lo[k] = w & 0x0f0f0f0fu;
;               hi[k] = (w >> 4) & 0x0f0f0f0fu;
;             }
;             {
;               const unsigned p01l = __builtin_amdgcn_perm(lo[1], lo[0], 0x05010400u), p01h = __builtin_amdgcn_perm(lo[1], lo[0], 0x07030602u);
;               const unsigned p23l = __builtin_amdgcn_perm(lo[3], lo[2], 0x05010400u), p23h = __builtin_amdgcn_perm(lo[3], lo[2], 0x07030602u);
;               acc[m * 8 + 0] = __builtin_amdgcn_sdot4((int)__builtin_amdgcn_perm(p23l, p01l, 0x05040100u), W4, acc[m * 8 + 0], false);
;               acc[m * 8 + 1] = __builtin_amdgcn_sdot4((int)__builtin_amdgcn_perm(p23l, p01l, 0x07060302u), W4, acc[m * 8 + 1], false);
;               acc[m * 8 + 2] = __builtin_amdgcn_sdot4((int)__builtin_amdgcn_perm(p23h, p01h, 0x05040100u), W4, acc[m * 8 + 2], false);
;               acc[m * 8 + 3] = __builtin_amdgcn_sdot4((int)__builtin_amdgcn_perm(p23h, p01h, 0x07060302u), W4, acc[m * 8 + 3], false);
;             }
;             {
;               const unsigned p01l = __builtin_amdgcn_perm(hi[1], hi[0], 0x05010400u), p01h = __builtin_amdgcn_perm(hi[1], hi[0], 0x07030602u);
;               const unsigned p23l = __builtin_amdgcn_perm(hi[3], hi[2], 0x05010400u), p23h = __builtin_amdgcn_perm(hi[3], hi[2], 0x07030602u);
;               acc[m * 8 + 4] = __builtin_amdgcn_sdot4((int)__builtin_amdgcn_perm(p23l, p01l, 0x05040100u), W4, acc[m * 8 + 4], false);
;               acc[m * 8 + 5] = __builtin_amdgcn_sdot4((int)__builtin_amdgcn_perm(p23l, p01l, 0x07060302u), W4, acc[m * 8 + 5], false);
;               acc[m * 8 + 6] = __builtin_amdgcn_sdot4((int)__builtin_amdgcn_perm(p23h, p01h, 0x05040100u), W4, acc[m * 8 + 6], false);
;               acc[m * 8 + 7] = __builtin_amdgcn_sdot4((int)__builtin_amdgcn_perm(p23h, p01h, 0x07060302u), W4, acc[m * 8 + 7], false);
;             }
;           }
	v_lshrrev_b32_e32 v172, 4, v23
	v_lshl_add_u64 v[32:33], v[116:117], 0, s[0:1]
	v_readlane_b32 s0, v250, 0
	v_readlane_b32 s1, v250, 1
	global_load_dwordx4 v[40:43], v[32:33], off
	v_lshrrev_b32_e32 v173, 4, v19
	v_lshl_add_u64 v[32:33], v[116:117], 0, s[0:1]
	v_readlane_b32 s0, v250, 16
	v_and_b32_e32 v176, 0xf0f0f0f, v176
	v_and_b32_e32 v177, 0xf0f0f0f, v177
	v_and_b32_e32 v179, 0xf0f0f0f, v179
	v_and_b32_e32 v180, 0xf0f0f0f, v180
	v_readlane_b32 s1, v250, 17
	v_lshrrev_b32_e32 v103, 4, v79
	v_lshrrev_b32_e32 v104, 4, v75
	v_lshrrev_b32_e32 v106, 4, v71
	v_lshrrev_b32_e32 v107, 4, v67
	v_and_b32_e32 v110, 0xf0f0f0f, v110
	v_and_b32_e32 v111, 0xf0f0f0f, v111
	v_and_b32_e32 v172, 0xf0f0f0f, v172
	v_and_b32_e32 v173, 0xf0f0f0f, v173
	v_perm_b32 v178, v176, v177, s52
	v_perm_b32 v181, v179, v180, s52
	global_load_dwordx4 v[36:39], v[32:33], off
	v_lshl_add_u64 v[32:33], v[116:117], 0, s[0:1]
	v_readlane_b32 s0, v170, 40
	s_waitcnt vmcnt(7)
	v_lshrrev_b32_e32 v96, 4, v95
	v_lshrrev_b32_e32 v97, 4, v91
	v_lshrrev_b32_e32 v99, 4, v87
	v_lshrrev_b32_e32 v100, 4, v83
	v_and_b32_e32 v103, 0xf0f0f0f, v103
	v_and_b32_e32 v104, 0xf0f0f0f, v104
	v_and_b32_e32 v106, 0xf0f0f0f, v106
	v_and_b32_e32 v107, 0xf0f0f0f, v107
	v_perm_b32 v171, v110, v111, s52
	v_perm_b32 v174, v172, v173, s52
	v_perm_b32 v182, v178, v181, s54
	v_readlane_b32 s1, v170, 44
	v_and_b32_e32 v96, 0xf0f0f0f, v96
	v_and_b32_e32 v97, 0xf0f0f0f, v97
	v_and_b32_e32 v99, 0xf0f0f0f, v99
	v_and_b32_e32 v100, 0xf0f0f0f, v100
	v_perm_b32 v105, v103, v104, s52
	v_perm_b32 v108, v106, v107, s52
	v_perm_b32 v175, v171, v174, s54
	v_dot4c_i32_i8_e32 v125, s0, v182
	v_perm_b32 v98, v96, v97, s52
	v_perm_b32 v101, v99, v100, s52
	v_perm_b32 v109, v105, v108, s54
	v_dot4c_i32_i8_e32 v125, s1, v175
	v_perm_b32 v102, v98, v101, s54
	v_dot4c_i32_i8_e32 v125, s2, v109
	v_perm_b32 v98, v98, v101, s53
	v_perm_b32 v101, v105, v108, s53
	v_perm_b32 v105, v178, v181, s53
	v_dot4c_i32_i8_e32 v125, s3, v102
	v_perm_b32 v102, v171, v174, s53
	v_dot4c_i32_i8_e32 v123, s0, v105
	v_perm_b32 v96, v96, v97, s33
	v_perm_b32 v97, v99, v100, s33
	v_perm_b32 v100, v106, v107, s33
	v_perm_b32 v105, v176, v177, s33
	v_perm_b32 v106, v179, v180, s33
	v_dot4c_i32_i8_e32 v123, s1, v102
	v_perm_b32 v99, v103, v104, s33
	v_perm_b32 v102, v110, v111, s33
	v_perm_b32 v103, v172, v173, s33
	v_perm_b32 v107, v105, v106, s54
	v_perm_b32 v104, v102, v103, s54
	v_dot4c_i32_i8_e32 v135, s0, v107
	v_dot4c_i32_i8_e32 v123, s2, v101
	v_perm_b32 v101, v99, v100, s54
	v_dot4c_i32_i8_e32 v135, s1, v104
	v_dot4c_i32_i8_e32 v123, s3, v98
	v_perm_b32 v98, v96, v97, s54
	v_dot4c_i32_i8_e32 v135, s2, v101
	v_perm_b32 v96, v96, v97, s53
	v_perm_b32 v97, v99, v100, s53
	v_perm_b32 v99, v105, v106, s53
	v_and_b32_e32 v15, 0xf0f0f0f, v15
	v_and_b32_e32 v11, 0xf0f0f0f, v11
	v_and_b32_e32 v7, 0xf0f0f0f, v7
	v_and_b32_e32 v3, 0xf0f0f0f, v3
	v_dot4c_i32_i8_e32 v135, s3, v98
	v_perm_b32 v98, v102, v103, s53
	v_dot4c_i32_i8_e32 v134, s0, v99
	v_and_b32_e32 v31, 0xf0f0f0f, v31
	v_and_b32_e32 v27, 0xf0f0f0f, v27
	v_and_b32_e32 v23, 0xf0f0f0f, v23
	v_and_b32_e32 v19, 0xf0f0f0f, v19
	v_perm_b32 v105, v15, v11, s52
	v_perm_b32 v106, v7, v3, s52
	v_dot4c_i32_i8_e32 v134, s1, v98
	v_and_b32_e32 v79, 0xf0f0f0f, v79
	v_and_b32_e32 v75, 0xf0f0f0f, v75
	v_and_b32_e32 v71, 0xf0f0f0f, v71
	v_and_b32_e32 v67, 0xf0f0f0f, v67
	v_perm_b32 v102, v31, v27, s52
	v_perm_b32 v103, v23, v19, s52
	v_perm_b32 v107, v105, v106, s54
	v_dot4c_i32_i8_e32 v134, s2, v97
	v_and_b32_e32 v95, 0xf0f0f0f, v95
	v_and_b32_e32 v91, 0xf0f0f0f, v91
	v_and_b32_e32 v87, 0xf0f0f0f, v87
	v_and_b32_e32 v83, 0xf0f0f0f, v83
	v_perm_b32 v99, v79, v75, s52
	v_perm_b32 v100, v71, v67, s52
	v_perm_b32 v104, v102, v103, s54
	v_dot4c_i32_i8_e32 v139, s0, v107
	v_dot4c_i32_i8_e32 v134, s3, v96
	v_perm_b32 v96, v95, v91, s52
	v_perm_b32 v97, v87, v83, s52
	v_perm_b32 v101, v99, v100, s54
	v_dot4c_i32_i8_e32 v139, s1, v104
	v_perm_b32 v98, v96, v97, s54
	v_dot4c_i32_i8_e32 v139, s2, v101
	v_perm_b32 v96, v96, v97, s53
	v_perm_b32 v97, v99, v100, s53
	v_perm_b32 v99, v105, v106, s53
	v_perm_b32 v11, v15, v11, s33
	v_perm_b32 v3, v7, v3, s33
	v_dot4c_i32_i8_e32 v139, s3, v98
	v_perm_b32 v98, v102, v103, s53
	v_dot4c_i32_i8_e32 v137, s0, v99
	v_perm_b32 v27, v31, v27, s33
	v_perm_b32 v19, v23, v19, s33
	v_perm_b32 v7, v11, v3, s54
	v_perm_b32 v3, v11, v3, s53
	v_dot4c_i32_i8_e32 v137, s1, v98
	v_perm_b32 v91, v95, v91, s33
	v_perm_b32 v83, v87, v83, s33
	v_perm_b32 v75, v79, v75, s33
	v_perm_b32 v67, v71, v67, s33
	v_perm_b32 v23, v27, v19, s54
	v_perm_b32 v19, v27, v19, s53
	v_dot4c_i32_i8_e32 v136, s0, v3
	v_lshrrev_b32_e32 v101, 4, v14
	v_lshrrev_b32_e32 v102, 4, v10
	v_lshrrev_b32_e32 v104, 4, v6
	v_lshrrev_b32_e32 v105, 4, v2
	v_dot4c_i32_i8_e32 v137, s2, v97
	v_perm_b32 v87, v91, v83, s54
	v_dot4c_i32_i8_e32 v140, s0, v7
	v_perm_b32 v7, v91, v83, s53
	v_perm_b32 v15, v75, v67, s53
	v_dot4c_i32_i8_e32 v136, s1, v19
	v_lshrrev_b32_e32 v91, 4, v30
	v_lshrrev_b32_e32 v95, 4, v26
	v_lshrrev_b32_e32 v97, 4, v22
	v_lshrrev_b32_e32 v98, 4, v18
	v_and_b32_e32 v101, 0xf0f0f0f, v101
	v_and_b32_e32 v102, 0xf0f0f0f, v102
	v_and_b32_e32 v104, 0xf0f0f0f, v104
	v_and_b32_e32 v105, 0xf0f0f0f, v105
	v_perm_b32 v71, v75, v67, s54
	v_dot4c_i32_i8_e32 v136, s2, v15
	v_lshrrev_b32_e32 v31, 4, v78
	v_lshrrev_b32_e32 v67, 4, v74
	v_lshrrev_b32_e32 v75, 4, v70
	v_lshrrev_b32_e32 v79, 4, v66
	v_and_b32_e32 v91, 0xf0f0f0f, v91
	v_and_b32_e32 v95, 0xf0f0f0f, v95
	v_and_b32_e32 v97, 0xf0f0f0f, v97
	v_and_b32_e32 v98, 0xf0f0f0f, v98
	v_perm_b32 v103, v101, v102, s52
	v_perm_b32 v106, v104, v105, s52
	v_dot4c_i32_i8_e32 v137, s3, v96
; __device__ void phase_gather(const Params& p) {
;     ...
;         for (int sub = 0; sub < GROWS / 4; ++sub) {
;           const int W4 = __builtin_amdgcn_readlane(pkv, j0 + 4 * sub);
; #pragma unroll
;           for (int m = 0; m < 4; ++m) {
;             unsigned lo[4], hi[4];
; #pragma unroll
;             for (int k = 0; k < 4; ++k) {
;               const unsigned w = rr[gi % 3][sub * 4 + k][m];
;               lo[k] = w & 0x0f0f0f0fu;
;               hi[k] = (w >> 4) & 0x0f0f0f0fu;
;             }
;             {
;               const unsigned p01l = __builtin_amdgcn_perm(lo[1], lo[0], 0x05010400u), p01h = __builtin_amdgcn_perm(lo[1], lo[0], 0x07030602u);
;               const unsigned p23l = __builtin_amdgcn_perm(lo[3], lo[2], 0x05010400u), p23h = __builtin_amdgcn_perm(lo[3], lo[2], 0x07030602u);
;               acc[m * 8 + 0] = __builtin_amdgcn_sdot4((int)__builtin_amdgcn_perm(p23l, p01l, 0x05040100u), W4, acc[m * 8 + 0], false);
;               acc[m * 8 + 1] = __builtin_amdgcn_sdot4((int)__builtin_amdgcn_perm(p23l, p01l, 0x07060302u), W4, acc[m * 8 + 1], false);
;               acc[m * 8 + 2] = __builtin_amdgcn_sdot4((int)__builtin_amdgcn_perm(p23h, p01h, 0x05040100u), W4, acc[m * 8 + 2], false);
;               acc[m * 8 + 3] = __builtin_amdgcn_sdot4((int)__builtin_amdgcn_perm(p23h, p01h, 0x07060302u), W4, acc[m * 8 + 3], false);
;             }
;             {
;               const unsigned p01l = __builtin_amdgcn_perm(hi[1], hi[0], 0x05010400u), p01h = __builtin_amdgcn_perm(hi[1], hi[0], 0x07030602u);
;               const unsigned p23l = __builtin_amdgcn_perm(hi[3], hi[2], 0x05010400u), p23h = __builtin_amdgcn_perm(hi[3], hi[2], 0x07030602u);
;               acc[m * 8 + 4] = __builtin_amdgcn_sdot4((int)__builtin_amdgcn_perm(p23l, p01l, 0x05040100u), W4, acc[m * 8 + 4], false);
;               acc[m * 8 + 5] = __builtin_amdgcn_sdot4((int)__builtin_amdgcn_perm(p23l, p01l, 0x07060302u), W4, acc[m * 8 + 5], false);
;               acc[m * 8 + 6] = __builtin_amdgcn_sdot4((int)__builtin_amdgcn_perm(p23h, p01h, 0x05040100u), W4, acc[m * 8 + 6], false);
;               acc[m * 8 + 7] = __builtin_amdgcn_sdot4((int)__builtin_amdgcn_perm(p23h, p01h, 0x07060302u), W4, acc[m * 8 + 7], false);
;             }
;           }
	v_dot4c_i32_i8_e32 v140, s1, v23
	v_dot4c_i32_i8_e32 v136, s3, v7
	v_lshrrev_b32_e32 v3, 4, v94
	v_lshrrev_b32_e32 v7, 4, v90
	v_lshrrev_b32_e32 v15, 4, v86
	v_lshrrev_b32_e32 v19, 4, v82
	v_and_b32_e32 v31, 0xf0f0f0f, v31
	v_and_b32_e32 v67, 0xf0f0f0f, v67
	v_and_b32_e32 v75, 0xf0f0f0f, v75
	v_and_b32_e32 v79, 0xf0f0f0f, v79
	v_perm_b32 v96, v91, v95, s52
	v_perm_b32 v99, v97, v98, s52
	v_perm_b32 v107, v103, v106, s54
	v_dot4c_i32_i8_e32 v140, s2, v71
	v_and_b32_e32 v3, 0xf0f0f0f, v3
	v_and_b32_e32 v7, 0xf0f0f0f, v7
	v_and_b32_e32 v15, 0xf0f0f0f, v15
	v_and_b32_e32 v19, 0xf0f0f0f, v19
	v_perm_b32 v71, v31, v67, s52
	v_perm_b32 v83, v75, v79, s52
	v_perm_b32 v100, v96, v99, s54
	v_dot4c_i32_i8_e32 v142, s0, v107
	v_dot4c_i32_i8_e32 v140, s3, v87
	v_perm_b32 v11, v3, v7, s52
	v_perm_b32 v23, v15, v19, s52
	v_perm_b32 v87, v71, v83, s54
	v_dot4c_i32_i8_e32 v142, s1, v100
	v_perm_b32 v27, v11, v23, s54
	v_dot4c_i32_i8_e32 v142, s2, v87
	v_perm_b32 v11, v11, v23, s53
	v_perm_b32 v23, v71, v83, s53
	v_perm_b32 v71, v103, v106, s53
	v_dot4c_i32_i8_e32 v142, s3, v27
	v_perm_b32 v27, v96, v99, s53
	v_dot4c_i32_i8_e32 v141, s0, v71
	v_perm_b32 v3, v3, v7, s33
	v_perm_b32 v7, v15, v19, s33
	v_perm_b32 v19, v75, v79, s33
	v_perm_b32 v71, v101, v102, s33
	v_perm_b32 v75, v104, v105, s33
	v_dot4c_i32_i8_e32 v141, s1, v27
	v_perm_b32 v15, v31, v67, s33
	v_perm_b32 v27, v91, v95, s33
	v_perm_b32 v31, v97, v98, s33
	v_perm_b32 v79, v71, v75, s54
	v_perm_b32 v67, v27, v31, s54
	v_dot4c_i32_i8_e32 v145, s0, v79
	v_dot4c_i32_i8_e32 v141, s2, v23
	v_perm_b32 v23, v15, v19, s54
	v_dot4c_i32_i8_e32 v145, s1, v67
	v_dot4c_i32_i8_e32 v141, s3, v11
	v_perm_b32 v11, v3, v7, s54
	v_dot4c_i32_i8_e32 v145, s2, v23
	v_perm_b32 v3, v3, v7, s53
	v_perm_b32 v7, v15, v19, s53
	v_perm_b32 v15, v71, v75, s53
	v_dot4c_i32_i8_e32 v145, s3, v11
	v_perm_b32 v11, v27, v31, s53
	v_dot4c_i32_i8_e32 v143, s0, v15
	v_and_b32_e32 v14, 0xf0f0f0f, v14
	v_and_b32_e32 v10, 0xf0f0f0f, v10
	v_and_b32_e32 v6, 0xf0f0f0f, v6
	v_and_b32_e32 v2, 0xf0f0f0f, v2
	v_dot4c_i32_i8_e32 v143, s1, v11
	v_and_b32_e32 v15, 0xf0f0f0f, v86
	v_and_b32_e32 v30, 0xf0f0f0f, v30
	v_and_b32_e32 v26, 0xf0f0f0f, v26
	v_and_b32_e32 v22, 0xf0f0f0f, v22
	v_and_b32_e32 v18, 0xf0f0f0f, v18
	v_perm_b32 v83, v14, v10, s52
	v_perm_b32 v86, v6, v2, s52
	v_dot4c_i32_i8_e32 v143, s2, v7
	v_and_b32_e32 v31, 0xf0f0f0f, v78
	v_and_b32_e32 v67, 0xf0f0f0f, v74
	v_and_b32_e32 v70, 0xf0f0f0f, v70
	v_and_b32_e32 v66, 0xf0f0f0f, v66
	v_perm_b32 v78, v30, v26, s52
	v_perm_b32 v79, v22, v18, s52
	v_perm_b32 v87, v83, v86, s54
	v_dot4c_i32_i8_e32 v143, s3, v3
	v_and_b32_e32 v3, 0xf0f0f0f, v94
	v_and_b32_e32 v7, 0xf0f0f0f, v90
	v_and_b32_e32 v19, 0xf0f0f0f, v82
	v_perm_b32 v71, v31, v67, s52
	v_perm_b32 v74, v70, v66, s52
	v_perm_b32 v82, v78, v79, s54
	v_dot4c_i32_i8_e32 v148, s0, v87
	v_perm_b32 v11, v3, v7, s52
	v_perm_b32 v23, v15, v19, s52
	v_perm_b32 v75, v71, v74, s54
	v_dot4c_i32_i8_e32 v148, s1, v82
	v_perm_b32 v27, v11, v23, s54
	v_dot4c_i32_i8_e32 v148, s2, v75
	v_perm_b32 v11, v11, v23, s53
	v_perm_b32 v23, v71, v74, s53
	v_perm_b32 v71, v83, v86, s53
	global_load_dwordx4 v[32:35], v[32:33], off
	v_dot4c_i32_i8_e32 v148, s3, v27
	v_perm_b32 v27, v78, v79, s53
	v_dot4c_i32_i8_e32 v147, s0, v71
	v_dot4c_i32_i8_e32 v147, s1, v27
	v_perm_b32 v10, v14, v10, s33
	v_perm_b32 v2, v6, v2, s33
	v_dot4c_i32_i8_e32 v147, s2, v23
	v_perm_b32 v3, v3, v7, s33
	v_perm_b32 v7, v15, v19, s33
	v_perm_b32 v26, v30, v26, s33
	v_perm_b32 v18, v22, v18, s33
	v_perm_b32 v6, v10, v2, s54
	v_perm_b32 v2, v10, v2, s53
	v_dot4c_i32_i8_e32 v147, s3, v11
	v_perm_b32 v11, v3, v7, s54
	v_perm_b32 v15, v31, v67, s33
	v_perm_b32 v19, v70, v66, s33
	v_perm_b32 v22, v26, v18, s54
	v_dot4c_i32_i8_e32 v153, s0, v6
	v_perm_b32 v3, v3, v7, s53
	v_perm_b32 v7, v26, v18, s53
	v_dot4c_i32_i8_e32 v151, s0, v2
	v_lshrrev_b32_e32 v75, 4, v13
	v_lshrrev_b32_e32 v78, 4, v9
	v_lshrrev_b32_e32 v82, 4, v5
	v_lshrrev_b32_e32 v83, 4, v1
	v_perm_b32 v23, v15, v19, s54
	v_dot4c_i32_i8_e32 v153, s1, v22
	v_perm_b32 v6, v15, v19, s53
	v_dot4c_i32_i8_e32 v151, s1, v7
	v_lshrrev_b32_e32 v30, 4, v29
	v_lshrrev_b32_e32 v31, 4, v25
	v_lshrrev_b32_e32 v67, 4, v21
	v_lshrrev_b32_e32 v70, 4, v17
	v_and_b32_e32 v75, 0xf0f0f0f, v75
	v_and_b32_e32 v78, 0xf0f0f0f, v78
	v_and_b32_e32 v82, 0xf0f0f0f, v82
	v_and_b32_e32 v83, 0xf0f0f0f, v83
	v_dot4c_i32_i8_e32 v153, s2, v23
	v_dot4c_i32_i8_e32 v151, s2, v6
	v_lshrrev_b32_e32 v15, 4, v77
	v_lshrrev_b32_e32 v18, 4, v73
	v_lshrrev_b32_e32 v22, 4, v69
	v_lshrrev_b32_e32 v23, 4, v65
	v_and_b32_e32 v30, 0xf0f0f0f, v30
	v_and_b32_e32 v31, 0xf0f0f0f, v31
	v_and_b32_e32 v67, 0xf0f0f0f, v67
	v_and_b32_e32 v70, 0xf0f0f0f, v70
	v_perm_b32 v79, v75, v78, s52
	v_perm_b32 v86, v82, v83, s52
	v_dot4c_i32_i8_e32 v151, s3, v3
	v_lshrrev_b32_e32 v2, 4, v93
	v_lshrrev_b32_e32 v3, 4, v89
	v_lshrrev_b32_e32 v7, 4, v85
	v_lshrrev_b32_e32 v10, 4, v81
	v_and_b32_e32 v15, 0xf0f0f0f, v15
	v_and_b32_e32 v18, 0xf0f0f0f, v18
	v_and_b32_e32 v22, 0xf0f0f0f, v22
	v_and_b32_e32 v23, 0xf0f0f0f, v23
	v_perm_b32 v66, v30, v31, s52
	v_perm_b32 v71, v67, v70, s52
	v_perm_b32 v87, v79, v86, s54
	v_and_b32_e32 v2, 0xf0f0f0f, v2
	v_and_b32_e32 v3, 0xf0f0f0f, v3
	v_and_b32_e32 v7, 0xf0f0f0f, v7
	v_and_b32_e32 v10, 0xf0f0f0f, v10
	v_perm_b32 v19, v15, v18, s52
	v_perm_b32 v26, v22, v23, s52
	v_perm_b32 v74, v66, v71, s54
	v_dot4c_i32_i8_e32 v156, s0, v87
	v_dot4c_i32_i8_e32 v153, s3, v11
	v_perm_b32 v6, v2, v3, s52
	v_perm_b32 v11, v7, v10, s52
	v_perm_b32 v27, v19, v26, s54
	v_dot4c_i32_i8_e32 v156, s1, v74
	v_perm_b32 v14, v6, v11, s54
	v_dot4c_i32_i8_e32 v156, s2, v27
; __device__ void phase_gather(const Params& p) {
;     ...
; #pragma unroll
;         for (int sub = 0; sub < GROWS / 4; ++sub) {
;           const int W4 = __builtin_amdgcn_readlane(pkv, j0 + 4 * sub);
; #pragma unroll
;           for (int m = 0; m < 4; ++m) {
;             unsigned lo[4], hi[4];
; #pragma unroll
;             for (int k = 0; k < 4; ++k) {
;               const unsigned w = rr[gi % 3][sub * 4 + k][m];
;               lo[k] = w & 0x0f0f0f0fu;
;               hi[k] = (w >> 4) & 0x0f0f0f0fu;
;             }
;             {
;               const unsigned p01l = __builtin_amdgcn_perm(lo[1], lo[0], 0x05010400u), p01h = __builtin_amdgcn_perm(lo[1], lo[0], 0x07030602u);
;               const unsigned p23l = __builtin_amdgcn_perm(lo[3], lo[2], 0x05010400u), p23h = __builtin_amdgcn_perm(lo[3], lo[2], 0x07030602u);
;               acc[m * 8 + 0] = __builtin_amdgcn_sdot4((int)__builtin_amdgcn_perm(p23l, p01l, 0x05040100u), W4, acc[m * 8 + 0], false);
;               acc[m * 8 + 1] = __builtin_amdgcn_sdot4((int)__builtin_amdgcn_perm(p23l, p01l, 0x07060302u), W4, acc[m * 8 + 1], false);
;               acc[m * 8 + 2] = __builtin_amdgcn_sdot4((int)__builtin_amdgcn_perm(p23h, p01h, 0x05040100u), W4, acc[m * 8 + 2], false);
;               acc[m * 8 + 3] = __builtin_amdgcn_sdot4((int)__builtin_amdgcn_perm(p23h, p01h, 0x07060302u), W4, acc[m * 8 + 3], false);
;             }
;             {
;               const unsigned p01l = __builtin_amdgcn_perm(hi[1], hi[0], 0x05010400u), p01h = __builtin_amdgcn_perm(hi[1], hi[0], 0x07030602u);
;               const unsigned p23l = __builtin_amdgcn_perm(hi[3], hi[2], 0x05010400u), p23h = __builtin_amdgcn_perm(hi[3], hi[2], 0x07030602u);
;               acc[m * 8 + 4] = __builtin_amdgcn_sdot4((int)__builtin_amdgcn_perm(p23l, p01l, 0x05040100u), W4, acc[m * 8 + 4], false);
;               acc[m * 8 + 5] = __builtin_amdgcn_sdot4((int)__builtin_amdgcn_perm(p23l, p01l, 0x07060302u), W4, acc[m * 8 + 5], false);
;               acc[m * 8 + 6] = __builtin_amdgcn_sdot4((int)__builtin_amdgcn_perm(p23h, p01h, 0x05040100u), W4, acc[m * 8 + 6], false);
;               acc[m * 8 + 7] = __builtin_amdgcn_sdot4((int)__builtin_amdgcn_perm(p23h, p01h, 0x07060302u), W4, acc[m * 8 + 7], false);
;             }
;           }
;         }
	v_perm_b32 v6, v6, v11, s53
	v_perm_b32 v11, v19, v26, s53
	v_perm_b32 v19, v79, v86, s53
	v_dot4c_i32_i8_e32 v156, s3, v14
	v_perm_b32 v14, v66, v71, s53
	v_dot4c_i32_i8_e32 v155, s0, v19
	v_perm_b32 v2, v2, v3, s33
	v_perm_b32 v3, v7, v10, s33
	v_perm_b32 v10, v22, v23, s33
	v_perm_b32 v19, v75, v78, s33
	v_perm_b32 v22, v82, v83, s33
	v_dot4c_i32_i8_e32 v155, s1, v14
	v_perm_b32 v7, v15, v18, s33
	v_perm_b32 v14, v30, v31, s33
	v_perm_b32 v15, v67, v70, s33
	v_perm_b32 v23, v19, v22, s54
	v_perm_b32 v18, v14, v15, s54
	v_dot4c_i32_i8_e32 v146, s0, v23
	v_dot4c_i32_i8_e32 v155, s2, v11
	v_perm_b32 v11, v7, v10, s54
	v_dot4c_i32_i8_e32 v146, s1, v18
	v_dot4c_i32_i8_e32 v155, s3, v6
	v_perm_b32 v6, v2, v3, s54
	v_dot4c_i32_i8_e32 v146, s2, v11
	v_perm_b32 v2, v2, v3, s53
	v_perm_b32 v3, v7, v10, s53
	v_perm_b32 v7, v19, v22, s53
	v_dot4c_i32_i8_e32 v146, s3, v6
	v_perm_b32 v6, v14, v15, s53
	v_dot4c_i32_i8_e32 v144, s0, v7
	v_and_b32_e32 v13, 0xf0f0f0f, v13
	v_and_b32_e32 v9, 0xf0f0f0f, v9
	v_and_b32_e32 v5, 0xf0f0f0f, v5
	v_and_b32_e32 v1, 0xf0f0f0f, v1
	v_dot4c_i32_i8_e32 v144, s1, v6
	v_and_b32_e32 v29, 0xf0f0f0f, v29
	v_and_b32_e32 v25, 0xf0f0f0f, v25
	v_and_b32_e32 v21, 0xf0f0f0f, v21
	v_and_b32_e32 v17, 0xf0f0f0f, v17
	v_perm_b32 v66, v13, v9, s52
	v_perm_b32 v67, v5, v1, s52
	v_dot4c_i32_i8_e32 v144, s2, v3
	v_and_b32_e32 v15, 0xf0f0f0f, v77
	v_and_b32_e32 v18, 0xf0f0f0f, v73
	v_and_b32_e32 v22, 0xf0f0f0f, v69
	v_and_b32_e32 v23, 0xf0f0f0f, v65
	v_perm_b32 v30, v29, v25, s52
	v_perm_b32 v31, v21, v17, s52
	v_perm_b32 v69, v66, v67, s54
	v_dot4c_i32_i8_e32 v144, s3, v2
	v_and_b32_e32 v2, 0xf0f0f0f, v93
	v_and_b32_e32 v3, 0xf0f0f0f, v89
	v_and_b32_e32 v7, 0xf0f0f0f, v85
	v_and_b32_e32 v10, 0xf0f0f0f, v81
	v_perm_b32 v19, v15, v18, s52
	v_perm_b32 v26, v22, v23, s52
	v_perm_b32 v65, v30, v31, s54
	v_dot4c_i32_i8_e32 v150, s0, v69
	v_perm_b32 v6, v2, v3, s52
	v_perm_b32 v11, v7, v10, s52
	v_perm_b32 v27, v19, v26, s54
	v_dot4c_i32_i8_e32 v150, s1, v65
	v_perm_b32 v14, v6, v11, s54
	v_dot4c_i32_i8_e32 v150, s2, v27
	v_perm_b32 v6, v6, v11, s53
	v_perm_b32 v11, v19, v26, s53
	v_perm_b32 v19, v66, v67, s53
	v_dot4c_i32_i8_e32 v150, s3, v14
	v_perm_b32 v14, v30, v31, s53
	v_dot4c_i32_i8_e32 v149, s0, v19
	v_perm_b32 v9, v13, v9, s33
	v_perm_b32 v1, v5, v1, s33
	v_dot4c_i32_i8_e32 v149, s1, v14
	v_perm_b32 v2, v2, v3, s33
	v_perm_b32 v3, v7, v10, s33
	v_perm_b32 v7, v15, v18, s33
	v_perm_b32 v14, v29, v25, s33
	v_perm_b32 v15, v21, v17, s33
	v_perm_b32 v5, v9, v1, s54
	v_perm_b32 v1, v9, v1, s53
	v_dot4c_i32_i8_e32 v149, s2, v11
	v_perm_b32 v10, v22, v23, s33
	v_perm_b32 v17, v14, v15, s54
	v_dot4c_i32_i8_e32 v154, s0, v5
	v_perm_b32 v5, v14, v15, s53
	v_dot4c_i32_i8_e32 v152, s0, v1
	v_lshrrev_b32_e32 v29, 4, v12
	v_lshrrev_b32_e32 v30, 4, v8
	v_lshrrev_b32_e32 v65, 4, v4
	v_lshrrev_b32_e32 v66, 4, v0
	v_dot4c_i32_i8_e32 v149, s3, v6
	v_perm_b32 v6, v2, v3, s54
	v_perm_b32 v11, v7, v10, s54
	v_dot4c_i32_i8_e32 v154, s1, v17
	v_perm_b32 v2, v2, v3, s53
	v_perm_b32 v3, v7, v10, s53
	v_dot4c_i32_i8_e32 v152, s1, v5
	v_lshrrev_b32_e32 v19, 4, v28
	v_lshrrev_b32_e32 v21, 4, v24
	v_lshrrev_b32_e32 v23, 4, v20
	v_lshrrev_b32_e32 v25, 4, v16
	v_and_b32_e32 v29, 0xf0f0f0f, v29
	v_and_b32_e32 v30, 0xf0f0f0f, v30
	v_and_b32_e32 v65, 0xf0f0f0f, v65
	v_and_b32_e32 v66, 0xf0f0f0f, v66
	v_dot4c_i32_i8_e32 v154, s2, v11
	v_dot4c_i32_i8_e32 v152, s2, v3
	v_lshrrev_b32_e32 v10, 4, v76
	v_lshrrev_b32_e32 v11, 4, v72
	v_lshrrev_b32_e32 v14, 4, v68
	v_lshrrev_b32_e32 v15, 4, v64
	v_and_b32_e32 v19, 0xf0f0f0f, v19
	v_and_b32_e32 v21, 0xf0f0f0f, v21
	v_and_b32_e32 v23, 0xf0f0f0f, v23
	v_and_b32_e32 v25, 0xf0f0f0f, v25
	v_perm_b32 v31, v29, v30, s52
	v_perm_b32 v67, v65, v66, s52
	v_dot4c_i32_i8_e32 v154, s3, v6
	v_dot4c_i32_i8_e32 v152, s3, v2
	v_lshrrev_b32_e32 v1, 4, v92
	v_lshrrev_b32_e32 v2, 4, v88
	v_lshrrev_b32_e32 v5, 4, v84
	v_lshrrev_b32_e32 v6, 4, v80
	v_and_b32_e32 v10, 0xf0f0f0f, v10
	v_and_b32_e32 v11, 0xf0f0f0f, v11
	v_and_b32_e32 v14, 0xf0f0f0f, v14
	v_and_b32_e32 v15, 0xf0f0f0f, v15
	v_perm_b32 v22, v19, v21, s52
	v_perm_b32 v26, v23, v25, s52
	v_perm_b32 v69, v31, v67, s54
	v_and_b32_e32 v1, 0xf0f0f0f, v1
	v_and_b32_e32 v2, 0xf0f0f0f, v2
	v_and_b32_e32 v5, 0xf0f0f0f, v5
	v_and_b32_e32 v6, 0xf0f0f0f, v6
	v_perm_b32 v13, v10, v11, s52
	v_perm_b32 v17, v14, v15, s52
	v_perm_b32 v27, v22, v26, s54
	v_dot4c_i32_i8_e32 v158, s0, v69
	v_perm_b32 v3, v1, v2, s52
	v_perm_b32 v7, v5, v6, s52
	v_perm_b32 v18, v13, v17, s54
	v_dot4c_i32_i8_e32 v158, s1, v27
	v_perm_b32 v9, v3, v7, s54
	v_dot4c_i32_i8_e32 v158, s2, v18
	v_perm_b32 v3, v3, v7, s53
	v_perm_b32 v7, v13, v17, s53
	v_perm_b32 v13, v31, v67, s53
	v_dot4c_i32_i8_e32 v158, s3, v9
	v_perm_b32 v9, v22, v26, s53
	v_dot4c_i32_i8_e32 v157, s0, v13
	v_perm_b32 v1, v1, v2, s33
	v_perm_b32 v2, v5, v6, s33
	v_perm_b32 v6, v14, v15, s33
	v_perm_b32 v13, v29, v30, s33
	v_perm_b32 v14, v65, v66, s33
	v_dot4c_i32_i8_e32 v157, s1, v9
	v_perm_b32 v5, v10, v11, s33
	v_perm_b32 v9, v19, v21, s33
	v_perm_b32 v10, v23, v25, s33
	v_perm_b32 v15, v13, v14, s54
	v_perm_b32 v11, v9, v10, s54
	v_dot4c_i32_i8_e32 v160, s0, v15
	v_dot4c_i32_i8_e32 v157, s2, v7
	v_perm_b32 v7, v5, v6, s54
	v_dot4c_i32_i8_e32 v160, s1, v11
	v_dot4c_i32_i8_e32 v157, s3, v3
	v_perm_b32 v3, v1, v2, s54
	v_dot4c_i32_i8_e32 v160, s2, v7
	v_perm_b32 v1, v1, v2, s53
	v_perm_b32 v2, v5, v6, s53
	v_perm_b32 v5, v13, v14, s53
	v_dot4c_i32_i8_e32 v160, s3, v3
	v_perm_b32 v3, v9, v10, s53
	v_dot4c_i32_i8_e32 v159, s0, v5
	v_and_b32_e32 v12, 0xf0f0f0f, v12
	v_and_b32_e32 v8, 0xf0f0f0f, v8
	v_and_b32_e32 v4, 0xf0f0f0f, v4
	v_and_b32_e32 v0, 0xf0f0f0f, v0
; __device__ void phase_gather(const Params& p) {
;     ...
; #pragma unroll
;         for (int sub = 0; sub < GROWS / 4; ++sub) {
;           const int W4 = __builtin_amdgcn_readlane(pkv, j0 + 4 * sub);
; #pragma unroll
;           for (int m = 0; m < 4; ++m) {
;             unsigned lo[4], hi[4];
; #pragma unroll
;             for (int k = 0; k < 4; ++k) {
;               const unsigned w = rr[gi % 3][sub * 4 + k][m];
;               lo[k] = w & 0x0f0f0f0fu;
;               hi[k] = (w >> 4) & 0x0f0f0f0fu;
;             }
;             {
;               const unsigned p01l = __builtin_amdgcn_perm(lo[1], lo[0], 0x05010400u), p01h = __builtin_amdgcn_perm(lo[1], lo[0], 0x07030602u);
;               const unsigned p23l = __builtin_amdgcn_perm(lo[3], lo[2], 0x05010400u), p23h = __builtin_amdgcn_perm(lo[3], lo[2], 0x07030602u);
;               acc[m * 8 + 0] = __builtin_amdgcn_sdot4((int)__builtin_amdgcn_perm(p23l, p01l, 0x05040100u), W4, acc[m * 8 + 0], false);
;               acc[m * 8 + 1] = __builtin_amdgcn_sdot4((int)__builtin_amdgcn_perm(p23l, p01l, 0x07060302u), W4, acc[m * 8 + 1], false);
;               acc[m * 8 + 2] = __builtin_amdgcn_sdot4((int)__builtin_amdgcn_perm(p23h, p01h, 0x05040100u), W4, acc[m * 8 + 2], false);
;               acc[m * 8 + 3] = __builtin_amdgcn_sdot4((int)__builtin_amdgcn_perm(p23h, p01h, 0x07060302u), W4, acc[m * 8 + 3], false);
;             }
;             {
;               const unsigned p01l = __builtin_amdgcn_perm(hi[1], hi[0], 0x05010400u), p01h = __builtin_amdgcn_perm(hi[1], hi[0], 0x07030602u);
;               const unsigned p23l = __builtin_amdgcn_perm(hi[3], hi[2], 0x05010400u), p23h = __builtin_amdgcn_perm(hi[3], hi[2], 0x07030602u);
;               acc[m * 8 + 4] = __builtin_amdgcn_sdot4((int)__builtin_amdgcn_perm(p23l, p01l, 0x05040100u), W4, acc[m * 8 + 4], false);
;               acc[m * 8 + 5] = __builtin_amdgcn_sdot4((int)__builtin_amdgcn_perm(p23l, p01l, 0x07060302u), W4, acc[m * 8 + 5], false);
;               acc[m * 8 + 6] = __builtin_amdgcn_sdot4((int)__builtin_amdgcn_perm(p23h, p01h, 0x05040100u), W4, acc[m * 8 + 6], false);
;               acc[m * 8 + 7] = __builtin_amdgcn_sdot4((int)__builtin_amdgcn_perm(p23h, p01h, 0x07060302u), W4, acc[m * 8 + 7], false);
;             }
;           }
;         }
	v_dot4c_i32_i8_e32 v159, s1, v3
	v_and_b32_e32 v19, 0xf0f0f0f, v28
	v_and_b32_e32 v21, 0xf0f0f0f, v24
	v_and_b32_e32 v20, 0xf0f0f0f, v20
	v_and_b32_e32 v16, 0xf0f0f0f, v16
	v_perm_b32 v25, v12, v8, s52
	v_perm_b32 v26, v4, v0, s52
	v_dot4c_i32_i8_e32 v159, s2, v2
	v_and_b32_e32 v10, 0xf0f0f0f, v76
	v_and_b32_e32 v11, 0xf0f0f0f, v72
	v_and_b32_e32 v14, 0xf0f0f0f, v68
	v_and_b32_e32 v15, 0xf0f0f0f, v64
	v_perm_b32 v22, v19, v21, s52
	v_perm_b32 v23, v20, v16, s52
	v_perm_b32 v27, v25, v26, s54
	v_dot4c_i32_i8_e32 v159, s3, v1
	v_and_b32_e32 v1, 0xf0f0f0f, v92
	v_and_b32_e32 v2, 0xf0f0f0f, v88
	v_and_b32_e32 v5, 0xf0f0f0f, v84
	v_and_b32_e32 v6, 0xf0f0f0f, v80
	v_perm_b32 v13, v10, v11, s52
	v_perm_b32 v17, v14, v15, s52
	v_perm_b32 v24, v22, v23, s54
	v_dot4c_i32_i8_e32 v162, s0, v27
	v_perm_b32 v3, v1, v2, s52
	v_perm_b32 v7, v5, v6, s52
	v_perm_b32 v18, v13, v17, s54
	v_dot4c_i32_i8_e32 v162, s1, v24
	v_perm_b32 v9, v3, v7, s54
	v_dot4c_i32_i8_e32 v162, s2, v18
	v_perm_b32 v3, v3, v7, s53
	v_perm_b32 v7, v13, v17, s53
	v_perm_b32 v13, v25, v26, s53
	v_dot4c_i32_i8_e32 v162, s3, v9
	v_perm_b32 v9, v22, v23, s53
	v_dot4c_i32_i8_e32 v161, s0, v13
	v_perm_b32 v8, v12, v8, s33
	v_perm_b32 v0, v4, v0, s33
	v_dot4c_i32_i8_e32 v161, s1, v9
	v_perm_b32 v1, v1, v2, s33
	v_perm_b32 v2, v5, v6, s33
	v_perm_b32 v5, v10, v11, s33
	v_perm_b32 v9, v19, v21, s33
	v_perm_b32 v10, v20, v16, s33
	v_perm_b32 v4, v8, v0, s54
	v_perm_b32 v6, v14, v15, s33
	v_perm_b32 v11, v9, v10, s54
	v_dot4c_i32_i8_e32 v164, s0, v4
	v_dot4c_i32_i8_e32 v161, s2, v7
	v_perm_b32 v7, v5, v6, s54
	v_dot4c_i32_i8_e32 v164, s1, v11
	v_dot4c_i32_i8_e32 v161, s3, v3
	v_perm_b32 v3, v1, v2, s54
	v_dot4c_i32_i8_e32 v164, s2, v7
	v_perm_b32 v0, v8, v0, s53
	v_dot4c_i32_i8_e32 v164, s3, v3
	v_perm_b32 v3, v9, v10, s53
	v_dot4c_i32_i8_e32 v163, s0, v0
	v_perm_b32 v1, v1, v2, s53
	v_perm_b32 v2, v5, v6, s53
	v_dot4c_i32_i8_e32 v163, s1, v3
	v_dot4c_i32_i8_e32 v163, s2, v2
	s_waitcnt vmcnt(7)
	v_and_b32_e32 v0, 0xf0f0f0f, v60
	s_waitcnt vmcnt(6)
	v_and_b32_e32 v2, 0xf0f0f0f, v56
	s_waitcnt vmcnt(5)
	v_and_b32_e32 v4, 0xf0f0f0f, v52
	s_waitcnt vmcnt(4)
	v_and_b32_e32 v6, 0xf0f0f0f, v48
	v_perm_b32 v8, v2, v0, s33
	v_perm_b32 v0, v2, v0, s52
	v_perm_b32 v2, v6, v4, s33
	v_dot4c_i32_i8_e32 v163, s3, v1
	v_readlane_b32 s0, v170, 56
	v_lshrrev_b32_e32 v1, 4, v60
	v_lshrrev_b32_e32 v3, 4, v56
	v_lshrrev_b32_e32 v5, 4, v52
	v_lshrrev_b32_e32 v7, 4, v48
	v_perm_b32 v4, v6, v4, s52
	v_perm_b32 v6, v2, v8, s53
	v_perm_b32 v2, v2, v8, s54
	v_and_b32_e32 v1, 0xf0f0f0f, v1
	v_and_b32_e32 v3, 0xf0f0f0f, v3
	v_and_b32_e32 v5, 0xf0f0f0f, v5
	v_and_b32_e32 v7, 0xf0f0f0f, v7
	v_dot4c_i32_i8_e32 v164, s0, v2
	v_perm_b32 v2, v4, v0, s53
	v_perm_b32 v0, v4, v0, s54
	v_dot4c_i32_i8_e32 v161, s0, v2
	v_dot4c_i32_i8_e32 v162, s0, v0
	v_perm_b32 v0, v3, v1, s33
	v_perm_b32 v2, v7, v5, s33
	v_perm_b32 v1, v3, v1, s52
	v_perm_b32 v3, v7, v5, s52
	v_perm_b32 v4, v2, v0, s53
	v_perm_b32 v0, v2, v0, s54
	v_dot4c_i32_i8_e32 v160, s0, v0
	v_perm_b32 v0, v3, v1, s53
	v_dot4c_i32_i8_e32 v157, s0, v0
	v_perm_b32 v0, v3, v1, s54
	v_dot4c_i32_i8_e32 v163, s0, v6
	v_dot4c_i32_i8_e32 v159, s0, v4
	v_dot4c_i32_i8_e32 v158, s0, v0
	v_and_b32_e32 v0, 0xf0f0f0f, v61
	v_and_b32_e32 v2, 0xf0f0f0f, v57
	v_and_b32_e32 v4, 0xf0f0f0f, v53
	v_and_b32_e32 v6, 0xf0f0f0f, v49
	v_perm_b32 v8, v2, v0, s33
	v_perm_b32 v0, v2, v0, s52
	v_perm_b32 v2, v6, v4, s33
	v_lshrrev_b32_e32 v1, 4, v61
	v_lshrrev_b32_e32 v3, 4, v57
	v_lshrrev_b32_e32 v5, 4, v53
	v_lshrrev_b32_e32 v7, 4, v49
	v_perm_b32 v4, v6, v4, s52
	v_perm_b32 v6, v2, v8, s53
	v_perm_b32 v2, v2, v8, s54
	v_and_b32_e32 v1, 0xf0f0f0f, v1
	v_and_b32_e32 v3, 0xf0f0f0f, v3
	v_and_b32_e32 v5, 0xf0f0f0f, v5
	v_and_b32_e32 v7, 0xf0f0f0f, v7
	v_dot4c_i32_i8_e32 v154, s0, v2
	v_perm_b32 v2, v4, v0, s53
	v_perm_b32 v0, v4, v0, s54
	v_dot4c_i32_i8_e32 v149, s0, v2
	v_dot4c_i32_i8_e32 v150, s0, v0
	v_perm_b32 v0, v3, v1, s33
	v_perm_b32 v2, v7, v5, s33
	v_perm_b32 v1, v3, v1, s52
	v_perm_b32 v3, v7, v5, s52
	v_perm_b32 v4, v2, v0, s53
	v_perm_b32 v0, v2, v0, s54
	v_dot4c_i32_i8_e32 v146, s0, v0
	v_perm_b32 v0, v3, v1, s53
	v_dot4c_i32_i8_e32 v155, s0, v0
	v_perm_b32 v0, v3, v1, s54
	v_dot4c_i32_i8_e32 v152, s0, v6
	v_dot4c_i32_i8_e32 v144, s0, v4
	v_dot4c_i32_i8_e32 v156, s0, v0
	v_and_b32_e32 v0, 0xf0f0f0f, v62
	v_and_b32_e32 v2, 0xf0f0f0f, v58
	v_and_b32_e32 v4, 0xf0f0f0f, v54
	v_and_b32_e32 v6, 0xf0f0f0f, v50
	v_perm_b32 v8, v2, v0, s33
	v_perm_b32 v0, v2, v0, s52
	v_perm_b32 v2, v6, v4, s33
	v_lshrrev_b32_e32 v1, 4, v62
	v_lshrrev_b32_e32 v3, 4, v58
	v_lshrrev_b32_e32 v5, 4, v54
	v_lshrrev_b32_e32 v7, 4, v50
	v_perm_b32 v4, v6, v4, s52
	v_perm_b32 v6, v2, v8, s53
	v_perm_b32 v2, v2, v8, s54
	v_and_b32_e32 v1, 0xf0f0f0f, v1
	v_and_b32_e32 v3, 0xf0f0f0f, v3
	v_and_b32_e32 v5, 0xf0f0f0f, v5
	v_and_b32_e32 v7, 0xf0f0f0f, v7
	v_dot4c_i32_i8_e32 v153, s0, v2
	v_perm_b32 v2, v4, v0, s53
	v_perm_b32 v0, v4, v0, s54
	v_dot4c_i32_i8_e32 v147, s0, v2
	v_dot4c_i32_i8_e32 v148, s0, v0
	v_perm_b32 v0, v3, v1, s33
	v_perm_b32 v2, v7, v5, s33
	v_perm_b32 v1, v3, v1, s52
	v_perm_b32 v3, v7, v5, s52
	v_perm_b32 v4, v2, v0, s53
	v_perm_b32 v0, v2, v0, s54
	v_dot4c_i32_i8_e32 v145, s0, v0
	v_perm_b32 v0, v3, v1, s53
	v_dot4c_i32_i8_e32 v141, s0, v0
	v_perm_b32 v0, v3, v1, s54
	v_dot4c_i32_i8_e32 v151, s0, v6
	v_dot4c_i32_i8_e32 v143, s0, v4
	v_dot4c_i32_i8_e32 v142, s0, v0
	v_and_b32_e32 v0, 0xf0f0f0f, v63
	v_and_b32_e32 v2, 0xf0f0f0f, v59
	v_and_b32_e32 v4, 0xf0f0f0f, v55
	v_and_b32_e32 v6, 0xf0f0f0f, v51
	v_perm_b32 v8, v2, v0, s33
	v_perm_b32 v0, v2, v0, s52
	v_perm_b32 v2, v6, v4, s33
	v_lshrrev_b32_e32 v1, 4, v63
	v_lshrrev_b32_e32 v3, 4, v59
	v_lshrrev_b32_e32 v5, 4, v55
	v_lshrrev_b32_e32 v7, 4, v51
	v_perm_b32 v4, v6, v4, s52
	v_perm_b32 v6, v2, v8, s53
	v_perm_b32 v2, v2, v8, s54
	v_and_b32_e32 v1, 0xf0f0f0f, v1
	v_and_b32_e32 v3, 0xf0f0f0f, v3
	v_and_b32_e32 v5, 0xf0f0f0f, v5
	v_and_b32_e32 v7, 0xf0f0f0f, v7
	v_dot4c_i32_i8_e32 v140, s0, v2
	v_perm_b32 v2, v4, v0, s53
	v_perm_b32 v0, v4, v0, s54
	v_dot4c_i32_i8_e32 v137, s0, v2
	v_dot4c_i32_i8_e32 v139, s0, v0
	v_perm_b32 v0, v3, v1, s33
	v_perm_b32 v2, v7, v5, s33
	v_perm_b32 v1, v3, v1, s52
	v_perm_b32 v3, v7, v5, s52
	v_perm_b32 v4, v2, v0, s53
	v_perm_b32 v0, v2, v0, s54
	v_dot4c_i32_i8_e32 v135, s0, v0
	v_perm_b32 v0, v3, v1, s53
	v_dot4c_i32_i8_e32 v123, s0, v0
	v_perm_b32 v0, v3, v1, s54
	v_dot4c_i32_i8_e32 v136, s0, v6
	v_dot4c_i32_i8_e32 v134, s0, v4
	v_dot4c_i32_i8_e32 v125, s0, v0
	s_waitcnt vmcnt(3)
; __device__ void phase_gather(const Params& p) {
;     ...
; #pragma unroll 1
;     for (int half = 0; half < 2; ++half) {
;     ...
; #pragma unroll
;         for (int sub = 0; sub < GROWS / 4; ++sub) {
;           const int W4 = __builtin_amdgcn_readlane(pkv, j0 + 4 * sub);
; #pragma unroll
;           for (int m = 0; m < 4; ++m) {
;             unsigned lo[4], hi[4];
; #pragma unroll
;             for (int k = 0; k < 4; ++k) {
;               const unsigned w = rr[gi % 3][sub * 4 + k][m];
;               lo[k] = w & 0x0f0f0f0fu;
;               hi[k] = (w >> 4) & 0x0f0f0f0fu;
;             }
;             {
;               const unsigned p01l = __builtin_amdgcn_perm(lo[1], lo[0], 0x05010400u), p01h = __builtin_amdgcn_perm(lo[1], lo[0], 0x07030602u);
;               const unsigned p23l = __builtin_amdgcn_perm(lo[3], lo[2], 0x05010400u), p23h = __builtin_amdgcn_perm(lo[3], lo[2], 0x07030602u);
;               acc[m * 8 + 0] = __builtin_amdgcn_sdot4((int)__builtin_amdgcn_perm(p23l, p01l, 0x05040100u), W4, acc[m * 8 + 0], false);
;               acc[m * 8 + 1] = __builtin_amdgcn_sdot4((int)__builtin_amdgcn_perm(p23l, p01l, 0x07060302u), W4, acc[m * 8 + 1], false);
;               acc[m * 8 + 2] = __builtin_amdgcn_sdot4((int)__builtin_amdgcn_perm(p23h, p01h, 0x05040100u), W4, acc[m * 8 + 2], false);
;               acc[m * 8 + 3] = __builtin_amdgcn_sdot4((int)__builtin_amdgcn_perm(p23h, p01h, 0x07060302u), W4, acc[m * 8 + 3], false);
;             }
;             {
;               const unsigned p01l = __builtin_amdgcn_perm(hi[1], hi[0], 0x05010400u), p01h = __builtin_amdgcn_perm(hi[1], hi[0], 0x07030602u);
;               const unsigned p23l = __builtin_amdgcn_perm(hi[3], hi[2], 0x05010400u), p23h = __builtin_amdgcn_perm(hi[3], hi[2], 0x07030602u);
;               acc[m * 8 + 4] = __builtin_amdgcn_sdot4((int)__builtin_amdgcn_perm(p23l, p01l, 0x05040100u), W4, acc[m * 8 + 4], false);
;               acc[m * 8 + 5] = __builtin_amdgcn_sdot4((int)__builtin_amdgcn_perm(p23l, p01l, 0x07060302u), W4, acc[m * 8 + 5], false);
;               acc[m * 8 + 6] = __builtin_amdgcn_sdot4((int)__builtin_amdgcn_perm(p23h, p01h, 0x05040100u), W4, acc[m * 8 + 6], false);
;               acc[m * 8 + 7] = __builtin_amdgcn_sdot4((int)__builtin_amdgcn_perm(p23h, p01h, 0x07060302u), W4, acc[m * 8 + 7], false);
;             }
;           }
;         }
	v_and_b32_e32 v0, 0xf0f0f0f, v44
	s_waitcnt vmcnt(2)
	v_and_b32_e32 v2, 0xf0f0f0f, v40
	s_waitcnt vmcnt(1)
	v_and_b32_e32 v4, 0xf0f0f0f, v36
	s_waitcnt vmcnt(0)
	v_and_b32_e32 v6, 0xf0f0f0f, v32
	v_perm_b32 v8, v2, v0, s33
	v_perm_b32 v0, v2, v0, s52
	v_perm_b32 v2, v6, v4, s33
	v_readlane_b32 s0, v170, 60
	v_lshrrev_b32_e32 v1, 4, v44
	v_lshrrev_b32_e32 v3, 4, v40
	v_lshrrev_b32_e32 v5, 4, v36
	v_lshrrev_b32_e32 v7, 4, v32
	v_perm_b32 v4, v6, v4, s52
	v_perm_b32 v6, v2, v8, s53
	v_perm_b32 v2, v2, v8, s54
	v_and_b32_e32 v1, 0xf0f0f0f, v1
	v_and_b32_e32 v3, 0xf0f0f0f, v3
	v_and_b32_e32 v5, 0xf0f0f0f, v5
	v_and_b32_e32 v7, 0xf0f0f0f, v7
	v_dot4c_i32_i8_e32 v164, s0, v2
	v_perm_b32 v2, v4, v0, s53
	v_perm_b32 v0, v4, v0, s54
	v_dot4c_i32_i8_e32 v161, s0, v2
	v_dot4c_i32_i8_e32 v162, s0, v0
	v_perm_b32 v0, v3, v1, s33
	v_perm_b32 v2, v7, v5, s33
	v_perm_b32 v1, v3, v1, s52
	v_perm_b32 v3, v7, v5, s52
	v_perm_b32 v4, v2, v0, s53
	v_perm_b32 v0, v2, v0, s54
	v_dot4c_i32_i8_e32 v160, s0, v0
	v_perm_b32 v0, v3, v1, s53
	v_dot4c_i32_i8_e32 v157, s0, v0
	v_perm_b32 v0, v3, v1, s54
	v_dot4c_i32_i8_e32 v163, s0, v6
	v_dot4c_i32_i8_e32 v159, s0, v4
	v_dot4c_i32_i8_e32 v158, s0, v0
	v_and_b32_e32 v0, 0xf0f0f0f, v45
	v_and_b32_e32 v2, 0xf0f0f0f, v41
	v_and_b32_e32 v4, 0xf0f0f0f, v37
	v_and_b32_e32 v6, 0xf0f0f0f, v33
	v_perm_b32 v8, v2, v0, s33
	v_perm_b32 v0, v2, v0, s52
	v_perm_b32 v2, v6, v4, s33
	v_lshrrev_b32_e32 v1, 4, v45
	v_lshrrev_b32_e32 v3, 4, v41
	v_lshrrev_b32_e32 v5, 4, v37
	v_lshrrev_b32_e32 v7, 4, v33
	v_perm_b32 v4, v6, v4, s52
	v_perm_b32 v6, v2, v8, s53
	v_perm_b32 v2, v2, v8, s54
	v_and_b32_e32 v1, 0xf0f0f0f, v1
	v_and_b32_e32 v3, 0xf0f0f0f, v3
	v_and_b32_e32 v5, 0xf0f0f0f, v5
	v_and_b32_e32 v7, 0xf0f0f0f, v7
	v_dot4c_i32_i8_e32 v154, s0, v2
	v_perm_b32 v2, v4, v0, s53
	v_perm_b32 v0, v4, v0, s54
	v_dot4c_i32_i8_e32 v149, s0, v2
	v_dot4c_i32_i8_e32 v150, s0, v0
	v_perm_b32 v0, v3, v1, s33
	v_perm_b32 v2, v7, v5, s33
	v_perm_b32 v1, v3, v1, s52
	v_perm_b32 v3, v7, v5, s52
	v_perm_b32 v4, v2, v0, s53
	v_perm_b32 v0, v2, v0, s54
	v_dot4c_i32_i8_e32 v146, s0, v0
	v_perm_b32 v0, v3, v1, s53
	v_dot4c_i32_i8_e32 v155, s0, v0
	v_perm_b32 v0, v3, v1, s54
	v_dot4c_i32_i8_e32 v152, s0, v6
	v_dot4c_i32_i8_e32 v144, s0, v4
	v_dot4c_i32_i8_e32 v156, s0, v0
	v_and_b32_e32 v0, 0xf0f0f0f, v46
	v_and_b32_e32 v2, 0xf0f0f0f, v42
	v_and_b32_e32 v4, 0xf0f0f0f, v38
	v_and_b32_e32 v6, 0xf0f0f0f, v34
	v_perm_b32 v8, v2, v0, s33
	v_perm_b32 v0, v2, v0, s52
	v_perm_b32 v2, v6, v4, s33
	v_lshrrev_b32_e32 v1, 4, v46
	v_lshrrev_b32_e32 v3, 4, v42
	v_lshrrev_b32_e32 v5, 4, v38
	v_lshrrev_b32_e32 v7, 4, v34
	v_perm_b32 v4, v6, v4, s52
	v_perm_b32 v6, v2, v8, s53
	v_perm_b32 v2, v2, v8, s54
	v_and_b32_e32 v1, 0xf0f0f0f, v1
	v_and_b32_e32 v3, 0xf0f0f0f, v3
	v_and_b32_e32 v5, 0xf0f0f0f, v5
	v_and_b32_e32 v7, 0xf0f0f0f, v7
	v_dot4c_i32_i8_e32 v153, s0, v2
	v_perm_b32 v2, v4, v0, s53
	v_perm_b32 v0, v4, v0, s54
	v_dot4c_i32_i8_e32 v147, s0, v2
	v_dot4c_i32_i8_e32 v148, s0, v0
	v_perm_b32 v0, v3, v1, s33
	v_perm_b32 v2, v7, v5, s33
	v_perm_b32 v1, v3, v1, s52
	v_perm_b32 v3, v7, v5, s52
	v_perm_b32 v4, v2, v0, s53
	v_perm_b32 v0, v2, v0, s54
	v_dot4c_i32_i8_e32 v145, s0, v0
	v_perm_b32 v0, v3, v1, s53
	v_dot4c_i32_i8_e32 v141, s0, v0
	v_perm_b32 v0, v3, v1, s54
	v_dot4c_i32_i8_e32 v151, s0, v6
	v_dot4c_i32_i8_e32 v142, s0, v0
	v_and_b32_e32 v0, 0xf0f0f0f, v47
	v_lshrrev_b32_e32 v1, 4, v47
	v_and_b32_e32 v5, 0xf0f0f0f, v43
	v_and_b32_e32 v6, 0xf0f0f0f, v39
	v_and_b32_e32 v7, 0xf0f0f0f, v35
	v_and_b32_e32 v2, 0xf0f0f0f, v1
	v_lshrrev_b32_e32 v1, 4, v43
	v_perm_b32 v8, v5, v0, s33
	v_perm_b32 v0, v5, v0, s52
	v_perm_b32 v5, v7, v6, s33
	v_dot4c_i32_i8_e32 v143, s0, v4
	v_and_b32_e32 v4, 0xf0f0f0f, v1
	v_lshrrev_b32_e32 v1, 4, v39
	v_lshrrev_b32_e32 v3, 4, v35
	v_perm_b32 v6, v7, v6, s52
	v_perm_b32 v7, v5, v8, s53
	v_perm_b32 v5, v5, v8, s54
	v_and_b32_e32 v1, 0xf0f0f0f, v1
	v_and_b32_e32 v3, 0xf0f0f0f, v3
	v_dot4c_i32_i8_e32 v140, s0, v5
	v_perm_b32 v5, v6, v0, s53
	v_perm_b32 v0, v6, v0, s54
	v_dot4c_i32_i8_e32 v139, s0, v0
	v_perm_b32 v0, v4, v2, s33
	v_perm_b32 v2, v4, v2, s52
	v_perm_b32 v4, v3, v1, s33
	v_perm_b32 v1, v3, v1, s52
	v_perm_b32 v3, v4, v0, s53
	v_perm_b32 v0, v4, v0, s54
	v_dot4c_i32_i8_e32 v135, s0, v0
	v_perm_b32 v0, v1, v2, s53
	v_dot4c_i32_i8_e32 v123, s0, v0
	v_perm_b32 v0, v1, v2, s54
	v_dot4c_i32_i8_e32 v136, s0, v7
	v_dot4c_i32_i8_e32 v137, s0, v5
	v_dot4c_i32_i8_e32 v134, s0, v3
	v_dot4c_i32_i8_e32 v125, s0, v0
	s_mov_b64 s[0:1], 0
	s_cbranch_vccz .LBB0_1321
; __device__ void phase_gather(const Params& p) {
;     ...
;     float val[32];
;     float ss = 0.f;
;     const int off8 = 8 * wsumq;
; #pragma unroll
;     for (int q = 0; q < 8; ++q) {
;       f32x4 v = *(const f32x4*)(orow + q * 4);
; #pragma unroll
;       for (int k = 0; k < 4; ++k) {
;         val[q * 4 + k] = sw * (float)(acc[q * 4 + k] - off8) + v[k];
;         ss += val[q * 4 + k] * val[q * 4 + k];
;       }
;     }
	v_lshlrev_b64 v[0:1], 13, v[112:113]
	v_lshl_add_u64 v[4:5], v[118:119], 0, v[0:1]
	global_load_dwordx4 v[0:3], v[120:121], off
	global_load_dwordx4 v[30:33], v[4:5], off offset:112
	global_load_dwordx4 v[34:37], v[4:5], off offset:96
	s_waitcnt lgkmcnt(0)
	v_add_lshl_u32 v39, v166, v167, 3
	v_sub_u32_e32 v40, v163, v39
	v_sub_u32_e32 v41, v164, v39
	v_sub_u32_e32 v42, v161, v39
	v_sub_u32_e32 v43, v162, v39
	v_cvt_f32_i32_e32 v41, v41
	v_cvt_f32_i32_e32 v40, v40
	v_cvt_f32_i32_e32 v43, v43
	v_cvt_f32_i32_e32 v42, v42
	v_sub_u32_e32 v44, v159, v39
	v_sub_u32_e32 v45, v160, v39
	v_mul_f32_e32 v38, 0x3c010204, v165
	v_cvt_f32_i32_e32 v45, v45
	v_cvt_f32_i32_e32 v44, v44
	v_sub_u32_e32 v46, v157, v39
	v_sub_u32_e32 v47, v158, v39
	v_cvt_f32_i32_e32 v47, v47
	v_cvt_f32_i32_e32 v46, v46
	v_sub_u32_e32 v48, v152, v39
	v_sub_u32_e32 v49, v154, v39
	v_cvt_f32_i32_e32 v49, v49
	v_cvt_f32_i32_e32 v48, v48
	v_sub_u32_e32 v50, v149, v39
	v_sub_u32_e32 v51, v150, v39
	v_cvt_f32_i32_e32 v51, v51
	v_cvt_f32_i32_e32 v50, v50
	v_sub_u32_e32 v52, v144, v39
	v_sub_u32_e32 v53, v146, v39
	v_cvt_f32_i32_e32 v53, v53
	v_cvt_f32_i32_e32 v52, v52
	v_sub_u32_e32 v54, v155, v39
	v_sub_u32_e32 v55, v156, v39
	v_cvt_f32_i32_e32 v55, v55
	v_cvt_f32_i32_e32 v54, v54
	v_sub_u32_e32 v56, v151, v39
	v_sub_u32_e32 v57, v153, v39
	v_cvt_f32_i32_e32 v57, v57
	v_cvt_f32_i32_e32 v56, v56
	v_sub_u32_e32 v58, v147, v39
	v_sub_u32_e32 v59, v148, v39
	v_sub_u32_e32 v62, v141, v39
	v_sub_u32_e32 v63, v142, v39
	v_cvt_f32_i32_e32 v59, v59
	v_cvt_f32_i32_e32 v58, v58
	v_sub_u32_e32 v60, v143, v39
	v_sub_u32_e32 v61, v145, v39
	v_cvt_f32_i32_e32 v63, v63
	v_cvt_f32_i32_e32 v62, v62
	v_cvt_f32_i32_e32 v61, v61
	v_cvt_f32_i32_e32 v60, v60
	v_sub_u32_e32 v64, v137, v39
	v_sub_u32_e32 v65, v139, v39
	v_cvt_f32_i32_e32 v65, v65
	v_cvt_f32_i32_e32 v64, v64
	v_sub_u32_e32 v68, v123, v39
	v_cvt_f32_i32_e32 v68, v68
	v_readlane_b32 s68, v250, 28
	s_movk_i32 s0, 0x3fff
	v_readlane_b32 s70, v250, 30
	v_add_u32_e32 v112, s68, v112
	v_readlane_b32 s71, v250, 31
	v_readlane_b32 s69, v250, 29
	s_waitcnt vmcnt(8)
	v_pk_fma_f32 v[228:229], v[38:39], v[40:41], v[228:229] op_sel_hi:[0,1,1]
	v_pk_fma_f32 v[230:231], v[38:39], v[42:43], v[230:231] op_sel_hi:[0,1,1]
	v_pk_mul_f32 v[40:41], v[228:229], v[228:229]
	v_pk_mul_f32 v[42:43], v[230:231], v[230:231]
	v_add_f32_e32 v40, v40, v41
	s_waitcnt vmcnt(7)
	v_pk_fma_f32 v[232:233], v[38:39], v[44:45], v[232:233] op_sel_hi:[0,1,1]
	v_add_f32_e32 v40, v42, v40
	v_pk_mul_f32 v[44:45], v[232:233], v[232:233]
	v_add_f32_e32 v40, v43, v40
	v_pk_fma_f32 v[234:235], v[38:39], v[46:47], v[234:235] op_sel_hi:[0,1,1]
	v_add_f32_e32 v40, v44, v40
	v_pk_mul_f32 v[46:47], v[234:235], v[234:235]
	v_add_f32_e32 v40, v45, v40
	s_waitcnt vmcnt(6)
	v_pk_fma_f32 v[236:237], v[38:39], v[48:49], v[236:237] op_sel_hi:[0,1,1]
	v_add_f32_e32 v40, v46, v40
	v_pk_mul_f32 v[48:49], v[236:237], v[236:237]
	v_add_f32_e32 v40, v47, v40
	v_pk_fma_f32 v[238:239], v[38:39], v[50:51], v[238:239] op_sel_hi:[0,1,1]
	v_add_f32_e32 v40, v48, v40
	v_pk_mul_f32 v[50:51], v[238:239], v[238:239]
	v_add_f32_e32 v40, v49, v40
	s_waitcnt vmcnt(5)
	v_pk_fma_f32 v[240:241], v[38:39], v[52:53], v[240:241] op_sel_hi:[0,1,1]
	v_add_f32_e32 v40, v50, v40
	v_pk_mul_f32 v[52:53], v[240:241], v[240:241]
	v_add_f32_e32 v40, v51, v40
	v_pk_fma_f32 v[242:243], v[38:39], v[54:55], v[242:243] op_sel_hi:[0,1,1]
	v_add_f32_e32 v40, v52, v40
	v_pk_mul_f32 v[54:55], v[242:243], v[242:243]
	v_add_f32_e32 v40, v53, v40
	s_waitcnt vmcnt(4)
	v_pk_fma_f32 v[244:245], v[38:39], v[56:57], v[244:245] op_sel_hi:[0,1,1]
	v_add_f32_e32 v40, v54, v40
	v_pk_mul_f32 v[56:57], v[244:245], v[244:245]
	v_add_f32_e32 v40, v55, v40
	v_pk_fma_f32 v[246:247], v[38:39], v[58:59], v[246:247] op_sel_hi:[0,1,1]
	v_add_f32_e32 v40, v56, v40
	s_waitcnt vmcnt(3)
	v_pk_fma_f32 v[186:187], v[38:39], v[62:63], v[186:187] op_sel_hi:[0,1,1]
	v_pk_mul_f32 v[58:59], v[246:247], v[246:247]
	v_sub_u32_e32 v62, v136, v39
	v_sub_u32_e32 v63, v140, v39
	v_add_f32_e32 v40, v57, v40
	v_pk_fma_f32 v[184:185], v[38:39], v[60:61], v[184:185] op_sel_hi:[0,1,1]
	v_cvt_f32_i32_e32 v63, v63
	v_cvt_f32_i32_e32 v62, v62
	v_add_f32_e32 v40, v58, v40
	v_pk_mul_f32 v[60:61], v[184:185], v[184:185]
	v_add_f32_e32 v40, v59, v40
	v_add_f32_e32 v40, v60, v40
	v_pk_mul_f32 v[66:67], v[186:187], v[186:187]
	s_waitcnt vmcnt(0)
; __device__ void phase_gather(const Params& p) {
;     ...
;     ss = wave_sum(ss);
;     const float rs3 = rsqrtf(ss * (1.f / 2048.f) + EPSV);
; #pragma unroll
;     for (int q = 0; q < 8; ++q) {
;       f32x4 wf = *(const f32x4*)(p.norm_final_w + lane * 32 + q * 4);
;       f32x4 o = {val[q * 4 + 0] * rs3 * wf[0], val[q * 4 + 1] * rs3 * wf[1], val[q * 4 + 2] * rs3 * wf[2],
;                  val[q * 4 + 3] * rs3 * wf[3]};
;       *(f32x4*)(orow + q * 4) = o;
;     }
	v_pk_fma_f32 v[36:37], v[38:39], v[64:65], v[36:37] op_sel_hi:[0,1,1]
	v_sub_u32_e32 v64, v134, v39
	v_sub_u32_e32 v65, v135, v39
	v_add_f32_e32 v40, v61, v40
	v_pk_fma_f32 v[34:35], v[38:39], v[62:63], v[34:35] op_sel_hi:[0,1,1]
	v_cvt_f32_i32_e32 v65, v65
	v_cvt_f32_i32_e32 v64, v64
	v_add_f32_e32 v40, v66, v40
	v_pk_mul_f32 v[62:63], v[34:35], v[34:35]
	v_sub_u32_e32 v39, v125, v39
	v_add_f32_e32 v40, v67, v40
	v_cvt_f32_i32_e32 v69, v39
	v_add_f32_e32 v40, v62, v40
	v_pk_mul_f32 v[70:71], v[36:37], v[36:37]
	v_add_f32_e32 v40, v63, v40
	v_pk_fma_f32 v[30:31], v[38:39], v[64:65], v[30:31] op_sel_hi:[0,1,1]
	v_add_f32_e32 v40, v70, v40
	v_pk_mul_f32 v[64:65], v[30:31], v[30:31]
	v_add_f32_e32 v40, v71, v40
	v_pk_fma_f32 v[32:33], v[38:39], v[68:69], v[32:33] op_sel_hi:[0,1,1]
	v_add_f32_e32 v40, v64, v40
	v_pk_mul_f32 v[38:39], v[32:33], v[32:33]
	v_add_f32_e32 v40, v65, v40
	v_add_f32_e32 v38, v38, v40
	v_add_f32_e32 v38, v39, v38
	ds_bpermute_b32 v39, v126, v38
	s_waitcnt lgkmcnt(0)
	v_add_f32_e32 v38, v38, v39
	ds_bpermute_b32 v39, v127, v38
	s_waitcnt lgkmcnt(0)
	v_add_f32_e32 v38, v38, v39
	ds_bpermute_b32 v39, v128, v38
	s_waitcnt lgkmcnt(0)
	v_add_f32_e32 v38, v38, v39
	ds_bpermute_b32 v39, v129, v38
	s_waitcnt lgkmcnt(0)
	v_add_f32_e32 v38, v38, v39
	ds_bpermute_b32 v39, v130, v38
	s_waitcnt lgkmcnt(0)
	v_add_f32_e32 v38, v38, v39
	ds_bpermute_b32 v39, v131, v38
	s_waitcnt lgkmcnt(0)
	v_add_f32_e32 v38, v38, v39
	v_fmamk_f32 v38, v38, 0x3a000000, v133
	v_mul_f32_e32 v39, 0x4b800000, v38
	v_cmp_gt_f32_e32 vcc, s55, v38
	s_nop 1
	v_cndmask_b32_e32 v38, v38, v39, vcc
	v_rsq_f32_e32 v38, v38
	s_nop 0
	v_mul_f32_e32 v39, 0x45800000, v38
	v_cndmask_b32_e32 v38, v38, v39, vcc
	v_pk_mul_f32 v[228:229], v[228:229], v[38:39] op_sel_hi:[1,0]
	v_pk_mul_f32 v[230:231], v[230:231], v[38:39] op_sel_hi:[1,0]
	v_pk_mul_f32 v[0:1], v[0:1], v[228:229]
	v_pk_mul_f32 v[2:3], v[2:3], v[230:231]
	global_store_dwordx4 v[4:5], v[0:3], off
	v_pk_mul_f32 v[228:229], v[234:235], v[38:39] op_sel_hi:[1,0]
	v_pk_mul_f32 v[230:231], v[232:233], v[38:39] op_sel_hi:[1,0]
	v_cmp_lt_i32_e32 vcc, s0, v112
	v_readlane_b32 s0, v250, 32
	v_readlane_b32 s1, v250, 33
	s_or_b64 s[0:1], vcc, s[0:1]
	v_pk_mul_f32 v[0:1], v[188:189], v[230:231]
	v_pk_mul_f32 v[2:3], v[190:191], v[228:229]
	global_store_dwordx4 v[4:5], v[0:3], off offset:16
	v_pk_mul_f32 v[228:229], v[238:239], v[38:39] op_sel_hi:[1,0]
	v_pk_mul_f32 v[230:231], v[236:237], v[38:39] op_sel_hi:[1,0]
	v_pk_mul_f32 v[2:3], v[194:195], v[228:229]
	v_pk_mul_f32 v[0:1], v[192:193], v[230:231]
	global_store_dwordx4 v[4:5], v[0:3], off offset:32
	v_pk_mul_f32 v[228:229], v[242:243], v[38:39] op_sel_hi:[1,0]
	v_pk_mul_f32 v[230:231], v[240:241], v[38:39] op_sel_hi:[1,0]
	v_pk_mul_f32 v[2:3], v[198:199], v[228:229]
	v_pk_mul_f32 v[0:1], v[196:197], v[230:231]
	global_store_dwordx4 v[4:5], v[0:3], off offset:48
	v_pk_mul_f32 v[228:229], v[246:247], v[38:39] op_sel_hi:[1,0]
	v_pk_mul_f32 v[230:231], v[244:245], v[38:39] op_sel_hi:[1,0]
	v_pk_mul_f32 v[2:3], v[202:203], v[228:229]
	v_pk_mul_f32 v[0:1], v[200:201], v[230:231]
	global_store_dwordx4 v[4:5], v[0:3], off offset:64
	v_pk_mul_f32 v[228:229], v[186:187], v[38:39] op_sel_hi:[1,0]
	v_pk_mul_f32 v[230:231], v[184:185], v[38:39] op_sel_hi:[1,0]
	v_pk_mul_f32 v[2:3], v[206:207], v[228:229]
	v_pk_mul_f32 v[0:1], v[204:205], v[230:231]
	global_store_dwordx4 v[4:5], v[0:3], off offset:80
	v_pk_mul_f32 v[228:229], v[36:37], v[38:39] op_sel_hi:[1,0]
	v_pk_mul_f32 v[230:231], v[34:35], v[38:39] op_sel_hi:[1,0]
	v_pk_mul_f32 v[2:3], v[210:211], v[228:229]
	v_pk_mul_f32 v[0:1], v[208:209], v[230:231]
	global_store_dwordx4 v[4:5], v[0:3], off offset:96
	v_pk_mul_f32 v[228:229], v[32:33], v[38:39] op_sel_hi:[1,0]
	v_pk_mul_f32 v[230:231], v[30:31], v[38:39] op_sel_hi:[1,0]
	v_pk_mul_f32 v[2:3], v[214:215], v[228:229]
	v_pk_mul_f32 v[0:1], v[212:213], v[230:231]
	global_store_dwordx4 v[4:5], v[0:3], off offset:112
	s_andn2_b64 exec, exec, s[0:1]
	s_cbranch_execnz .LBB0_1318
